# backedge: loop-edge edit - K-loop counter/pointer SALU updates and exit compare hoisted above the loop-back s_barrier (12 sites), only the branch stays behind it
# baseline (speedup 1.0000x reference)
.Lpeel_214:
	ds_read_b128 v[66:69], v161
	ds_read_b128 v[70:73], v161 offset:1024
	ds_read_b128 v[74:77], v161 offset:2048
	ds_read_b128 v[78:81], v161 offset:3072
	ds_read_b128 v[168:171], v163
	ds_read_b128 v[172:175], v163 offset:1024
	ds_read_b128 v[176:179], v163 offset:2048
	ds_read_b128 v[180:183], v163 offset:3072
	s_add_u32 s87, s84, 0xfffe0080
	s_addc_u32 s91, s85, -1
	s_cmp_eq_u32 s86, 4
	s_cselect_b32 s95, s34, s91
	s_cselect_b32 s94, s35, s87
	s_cselect_b32 s97, s75, s90
	s_cselect_b32 s96, s77, s89
	v_lshl_add_u64 v[158:159], s[84:85], 0, v[152:153]
	s_add_i32 m0, s56, 0xc000
	ds_read_b128 v[184:187], v165
	ds_read_b128 v[188:191], v165 offset:1024
	ds_read_b128 v[192:195], v165 offset:2048
	ds_read_b128 v[196:199], v165 offset:3072
	ds_read_b128 v[200:203], v165 offset:4096
	ds_read_b128 v[204:207], v165 offset:5120
	ds_read_b128 v[208:211], v165 offset:6144
	ds_read_b128 v[212:215], v165 offset:7168
	global_load_lds_dwordx4 v[158:159], off
	v_lshl_add_u64 v[158:159], v[158:159], 0, s[4:5]
	s_add_i32 m0, s56, 0xe000
	s_nop 0
	global_load_lds_dwordx4 v[158:159], off
	s_waitcnt vmcnt(8)
	s_waitcnt lgkmcnt(0)
	s_barrier
	s_setprio 1
	s_waitcnt lgkmcnt(0)
	v_mfma_i32_16x16x64_i8 v[142:145], v[66:69], v[184:187], 0
	v_mfma_i32_16x16x64_i8 v[138:141], v[74:77], v[184:187], 0
	v_mfma_i32_16x16x64_i8 v[126:129], v[66:69], v[192:195], 0
	v_mfma_i32_16x16x64_i8 v[122:125], v[74:77], v[192:195], 0
	v_mfma_i32_16x16x64_i8 v[110:113], v[66:69], v[200:203], 0
	v_mfma_i32_16x16x64_i8 v[106:109], v[74:77], v[200:203], 0
	v_mfma_i32_16x16x64_i8 v[94:97], v[66:69], v[208:211], 0
	v_mfma_i32_16x16x64_i8 v[90:93], v[74:77], v[208:211], 0
	v_mfma_i32_16x16x64_i8 v[142:145], v[70:73], v[188:191], v[142:145]
	v_mfma_i32_16x16x64_i8 v[138:141], v[78:81], v[188:191], v[138:141]
	v_mfma_i32_16x16x64_i8 v[126:129], v[70:73], v[196:199], v[126:129]
	v_mfma_i32_16x16x64_i8 v[122:125], v[78:81], v[196:199], v[122:125]
	v_mfma_i32_16x16x64_i8 v[110:113], v[70:73], v[204:207], v[110:113]
	v_mfma_i32_16x16x64_i8 v[106:109], v[78:81], v[204:207], v[106:109]
	v_mfma_i32_16x16x64_i8 v[94:97], v[70:73], v[212:215], v[94:97]
	v_mfma_i32_16x16x64_i8 v[90:93], v[78:81], v[212:215], v[90:93]
	s_setprio 0
	s_setprio 1
	v_mfma_i32_16x16x64_i8 v[134:137], v[168:171], v[184:187], 0
	v_mfma_i32_16x16x64_i8 v[130:133], v[176:179], v[184:187], 0
	v_mfma_i32_16x16x64_i8 v[118:121], v[168:171], v[192:195], 0
	v_mfma_i32_16x16x64_i8 v[114:117], v[176:179], v[192:195], 0
	v_mfma_i32_16x16x64_i8 v[102:105], v[168:171], v[200:203], 0
	v_mfma_i32_16x16x64_i8 v[98:101], v[176:179], v[200:203], 0
	v_mfma_i32_16x16x64_i8 v[86:89], v[168:171], v[208:211], 0
	v_mfma_i32_16x16x64_i8 v[82:85], v[176:179], v[208:211], 0
	v_mfma_i32_16x16x64_i8 v[134:137], v[172:175], v[188:191], v[134:137]
	v_mfma_i32_16x16x64_i8 v[130:133], v[180:183], v[188:191], v[130:133]
	v_mfma_i32_16x16x64_i8 v[118:121], v[172:175], v[196:199], v[118:121]
	v_mfma_i32_16x16x64_i8 v[114:117], v[180:183], v[196:199], v[114:117]
	v_mfma_i32_16x16x64_i8 v[102:105], v[172:175], v[204:207], v[102:105]
	v_mfma_i32_16x16x64_i8 v[98:101], v[180:183], v[204:207], v[98:101]
	v_mfma_i32_16x16x64_i8 v[86:89], v[172:175], v[212:215], v[86:89]
	v_mfma_i32_16x16x64_i8 v[82:85], v[180:183], v[212:215], v[82:85]
	s_setprio 0
	s_barrier
	s_add_i32 s87, s64, s16
	v_lshl_add_u64 v[158:159], s[96:97], 0, v[148:149]
	s_mov_b32 m0, s87
	ds_read_b128 v[184:187], v165 offset:16384
	ds_read_b128 v[188:191], v165 offset:17408
	ds_read_b128 v[192:195], v165 offset:18432
	ds_read_b128 v[196:199], v165 offset:19456
	ds_read_b128 v[200:203], v165 offset:20480
	ds_read_b128 v[204:207], v165 offset:21504
	ds_read_b128 v[208:211], v165 offset:22528
	ds_read_b128 v[212:215], v165 offset:23552
	global_load_lds_dwordx4 v[158:159], off
	v_lshl_add_u64 v[216:217], v[158:159], 0, s[4:5]
	s_add_i32 m0, s87, 0x2000
	s_add_i32 s87, s65, s16
	global_load_lds_dwordx4 v[216:217], off
	v_lshl_add_u64 v[216:217], v[158:159], 0, s[10:11]
	s_mov_b32 m0, s87
	s_nop 0
	global_load_lds_dwordx4 v[216:217], off
	v_lshl_add_u64 v[216:217], v[158:159], 0, s[12:13]
	s_add_i32 m0, s87, 0x2000
	s_nop 0
	global_load_lds_dwordx4 v[216:217], off
	v_lshl_add_u64 v[216:217], s[94:95], 0, v[146:147]
	s_mov_b32 m0, s56
	v_lshl_add_u64 v[218:219], v[216:217], 0, s[4:5]
	global_load_lds_dwordx4 v[216:217], off
	s_mov_b32 m0, s57
	s_nop 0
	global_load_lds_dwordx4 v[218:219], off
	s_waitcnt vmcnt(8)
	s_waitcnt lgkmcnt(0)
	s_barrier
	s_setprio 1
	s_waitcnt lgkmcnt(0)
	v_mfma_i32_16x16x64_i8 v[62:65], v[66:69], v[184:187], 0
	v_mfma_i32_16x16x64_i8 v[58:61], v[74:77], v[184:187], 0
	v_mfma_i32_16x16x64_i8 v[46:49], v[66:69], v[192:195], 0
	v_mfma_i32_16x16x64_i8 v[42:45], v[74:77], v[192:195], 0
	v_mfma_i32_16x16x64_i8 v[30:33], v[66:69], v[200:203], 0
	v_mfma_i32_16x16x64_i8 v[26:29], v[74:77], v[200:203], 0
	v_mfma_i32_16x16x64_i8 v[14:17], v[66:69], v[208:211], 0
	v_mfma_i32_16x16x64_i8 v[10:13], v[74:77], v[208:211], 0
	v_mfma_i32_16x16x64_i8 v[62:65], v[70:73], v[188:191], v[62:65]
	v_mfma_i32_16x16x64_i8 v[58:61], v[78:81], v[188:191], v[58:61]
	v_mfma_i32_16x16x64_i8 v[46:49], v[70:73], v[196:199], v[46:49]
	v_mfma_i32_16x16x64_i8 v[42:45], v[78:81], v[196:199], v[42:45]
	v_mfma_i32_16x16x64_i8 v[30:33], v[70:73], v[204:207], v[30:33]
	v_mfma_i32_16x16x64_i8 v[26:29], v[78:81], v[204:207], v[26:29]
	v_mfma_i32_16x16x64_i8 v[14:17], v[70:73], v[212:215], v[14:17]
	v_mfma_i32_16x16x64_i8 v[10:13], v[78:81], v[212:215], v[10:13]
	s_setprio 0
	s_setprio 1
	v_mfma_i32_16x16x64_i8 v[54:57], v[168:171], v[184:187], 0
	v_mfma_i32_16x16x64_i8 v[50:53], v[176:179], v[184:187], 0
	v_mfma_i32_16x16x64_i8 v[38:41], v[168:171], v[192:195], 0
	v_mfma_i32_16x16x64_i8 v[34:37], v[176:179], v[192:195], 0
	v_mfma_i32_16x16x64_i8 v[22:25], v[168:171], v[200:203], 0
	v_mfma_i32_16x16x64_i8 v[18:21], v[176:179], v[200:203], 0
	v_mfma_i32_16x16x64_i8 v[6:9], v[168:171], v[208:211], 0
	v_mfma_i32_16x16x64_i8 v[2:5], v[176:179], v[208:211], 0
	v_mfma_i32_16x16x64_i8 v[54:57], v[172:175], v[188:191], v[54:57]
	v_mfma_i32_16x16x64_i8 v[50:53], v[180:183], v[188:191], v[50:53]
	v_mfma_i32_16x16x64_i8 v[38:41], v[172:175], v[196:199], v[38:41]
	v_mfma_i32_16x16x64_i8 v[34:37], v[180:183], v[196:199], v[34:37]
	v_mfma_i32_16x16x64_i8 v[22:25], v[172:175], v[204:207], v[22:25]
	v_mfma_i32_16x16x64_i8 v[18:21], v[180:183], v[204:207], v[18:21]
	v_mfma_i32_16x16x64_i8 v[6:9], v[172:175], v[212:215], v[6:9]
	v_mfma_i32_16x16x64_i8 v[2:5], v[180:183], v[212:215], v[2:5]
	s_setprio 0
	s_barrier
	s_add_i32 s87, 0, 0x18000
	s_add_i32 s91, 0, 0x1c000
	v_add_u32_e32 v78, s87, v1
	v_add_u32_e32 v150, s91, v1
	ds_read_b128 v[66:69], v78
	ds_read_b128 v[70:73], v78 offset:1024
	ds_read_b128 v[74:77], v78 offset:2048
	ds_read_b128 v[78:81], v78 offset:3072
	ds_read_b128 v[168:171], v150
	ds_read_b128 v[172:175], v150 offset:1024
	ds_read_b128 v[176:179], v150 offset:2048
	ds_read_b128 v[180:183], v150 offset:3072
	s_mov_b32 m0, s58
	v_lshl_add_u64 v[218:219], v[216:217], 0, s[10:11]
	ds_read_b128 v[184:187], v165 offset:32768
	ds_read_b128 v[188:191], v165 offset:33792
	ds_read_b128 v[192:195], v165 offset:34816
	ds_read_b128 v[196:199], v165 offset:35840
	ds_read_b128 v[200:203], v165 offset:36864
	ds_read_b128 v[204:207], v165 offset:37888
	ds_read_b128 v[208:211], v165 offset:38912
	ds_read_b128 v[212:215], v165 offset:39936
	global_load_lds_dwordx4 v[218:219], off
	v_lshl_add_u64 v[218:219], v[216:217], 0, s[12:13]
	s_mov_b32 m0, s59
	s_nop 0
	global_load_lds_dwordx4 v[218:219], off
	s_waitcnt vmcnt(8)
	s_waitcnt lgkmcnt(0)
	s_barrier
	s_setprio 1
	s_waitcnt lgkmcnt(0)
	v_mfma_i32_16x16x64_i8 v[142:145], v[66:69], v[184:187], v[142:145]
	v_mfma_i32_16x16x64_i8 v[138:141], v[74:77], v[184:187], v[138:141]
	v_mfma_i32_16x16x64_i8 v[126:129], v[66:69], v[192:195], v[126:129]
	v_mfma_i32_16x16x64_i8 v[122:125], v[74:77], v[192:195], v[122:125]
	v_mfma_i32_16x16x64_i8 v[110:113], v[66:69], v[200:203], v[110:113]
	v_mfma_i32_16x16x64_i8 v[106:109], v[74:77], v[200:203], v[106:109]
	v_mfma_i32_16x16x64_i8 v[94:97], v[66:69], v[208:211], v[94:97]
	v_mfma_i32_16x16x64_i8 v[90:93], v[74:77], v[208:211], v[90:93]
	v_mfma_i32_16x16x64_i8 v[142:145], v[70:73], v[188:191], v[142:145]
	v_mfma_i32_16x16x64_i8 v[138:141], v[78:81], v[188:191], v[138:141]
	v_mfma_i32_16x16x64_i8 v[126:129], v[70:73], v[196:199], v[126:129]
	v_mfma_i32_16x16x64_i8 v[122:125], v[78:81], v[196:199], v[122:125]
	v_mfma_i32_16x16x64_i8 v[110:113], v[70:73], v[204:207], v[110:113]
	v_mfma_i32_16x16x64_i8 v[106:109], v[78:81], v[204:207], v[106:109]
	v_mfma_i32_16x16x64_i8 v[94:97], v[70:73], v[212:215], v[94:97]
	v_mfma_i32_16x16x64_i8 v[90:93], v[78:81], v[212:215], v[90:93]
	s_setprio 0
	s_setprio 1
	v_mfma_i32_16x16x64_i8 v[134:137], v[168:171], v[184:187], v[134:137]
	v_mfma_i32_16x16x64_i8 v[130:133], v[176:179], v[184:187], v[130:133]
	v_mfma_i32_16x16x64_i8 v[118:121], v[168:171], v[192:195], v[118:121]
	v_mfma_i32_16x16x64_i8 v[114:117], v[176:179], v[192:195], v[114:117]
	v_mfma_i32_16x16x64_i8 v[102:105], v[168:171], v[200:203], v[102:105]
	v_mfma_i32_16x16x64_i8 v[98:101], v[176:179], v[200:203], v[98:101]
	v_mfma_i32_16x16x64_i8 v[86:89], v[168:171], v[208:211], v[86:89]
	v_mfma_i32_16x16x64_i8 v[82:85], v[176:179], v[208:211], v[82:85]
	v_mfma_i32_16x16x64_i8 v[134:137], v[172:175], v[188:191], v[134:137]
	v_mfma_i32_16x16x64_i8 v[130:133], v[180:183], v[188:191], v[130:133]
	v_mfma_i32_16x16x64_i8 v[118:121], v[172:175], v[196:199], v[118:121]
	v_mfma_i32_16x16x64_i8 v[114:117], v[180:183], v[196:199], v[114:117]
	v_mfma_i32_16x16x64_i8 v[102:105], v[172:175], v[204:207], v[102:105]
	v_mfma_i32_16x16x64_i8 v[98:101], v[180:183], v[204:207], v[98:101]
	v_mfma_i32_16x16x64_i8 v[86:89], v[172:175], v[212:215], v[86:89]
	v_mfma_i32_16x16x64_i8 v[82:85], v[180:183], v[212:215], v[82:85]
	s_setprio 0
	s_barrier
	s_add_i32 s87, s87, s16
	v_lshl_add_u64 v[218:219], v[158:159], 0, s[48:49]
	s_mov_b32 m0, s87
	ds_read_b128 v[184:187], v165 offset:49152
	ds_read_b128 v[188:191], v165 offset:50176
	ds_read_b128 v[192:195], v165 offset:51200
	ds_read_b128 v[196:199], v165 offset:52224
	ds_read_b128 v[200:203], v165 offset:53248
	ds_read_b128 v[204:207], v165 offset:54272
	ds_read_b128 v[208:211], v165 offset:55296
	ds_read_b128 v[212:215], v165 offset:56320
	global_load_lds_dwordx4 v[218:219], off
	v_lshl_add_u64 v[218:219], v[158:159], 0, s[50:51]
	s_add_i32 m0, s87, 0x2000
	s_add_i32 s87, s91, s16
	global_load_lds_dwordx4 v[218:219], off
	v_lshl_add_u64 v[218:219], v[158:159], 0, s[52:53]
	s_mov_b32 m0, s87
	v_lshl_add_u64 v[158:159], v[158:159], 0, s[66:67]
	global_load_lds_dwordx4 v[218:219], off
	s_add_i32 m0, s87, 0x2000
	s_nop 0
	global_load_lds_dwordx4 v[158:159], off
	v_lshl_add_u64 v[158:159], v[216:217], 0, s[48:49]
	s_mov_b32 m0, s62
	s_nop 0
	global_load_lds_dwordx4 v[158:159], off
	v_lshl_add_u64 v[158:159], v[216:217], 0, s[50:51]
	s_mov_b32 m0, s63
	s_nop 0
	global_load_lds_dwordx4 v[158:159], off
	s_waitcnt vmcnt(8)
	s_waitcnt lgkmcnt(0)
	s_barrier
	s_setprio 1
	s_waitcnt lgkmcnt(0)
	v_mfma_i32_16x16x64_i8 v[62:65], v[66:69], v[184:187], v[62:65]
	v_mfma_i32_16x16x64_i8 v[58:61], v[74:77], v[184:187], v[58:61]
	v_mfma_i32_16x16x64_i8 v[46:49], v[66:69], v[192:195], v[46:49]
	v_mfma_i32_16x16x64_i8 v[42:45], v[74:77], v[192:195], v[42:45]
	v_mfma_i32_16x16x64_i8 v[30:33], v[66:69], v[200:203], v[30:33]
	v_mfma_i32_16x16x64_i8 v[26:29], v[74:77], v[200:203], v[26:29]
	v_mfma_i32_16x16x64_i8 v[14:17], v[66:69], v[208:211], v[14:17]
	v_mfma_i32_16x16x64_i8 v[10:13], v[74:77], v[208:211], v[10:13]
	v_mfma_i32_16x16x64_i8 v[62:65], v[70:73], v[188:191], v[62:65]
	v_mfma_i32_16x16x64_i8 v[58:61], v[78:81], v[188:191], v[58:61]
	v_mfma_i32_16x16x64_i8 v[46:49], v[70:73], v[196:199], v[46:49]
	v_mfma_i32_16x16x64_i8 v[42:45], v[78:81], v[196:199], v[42:45]
	v_mfma_i32_16x16x64_i8 v[30:33], v[70:73], v[204:207], v[30:33]
	v_mfma_i32_16x16x64_i8 v[26:29], v[78:81], v[204:207], v[26:29]
	v_mfma_i32_16x16x64_i8 v[14:17], v[70:73], v[212:215], v[14:17]
	v_mfma_i32_16x16x64_i8 v[10:13], v[78:81], v[212:215], v[10:13]
	s_setprio 0
	s_setprio 1
	v_mfma_i32_16x16x64_i8 v[54:57], v[168:171], v[184:187], v[54:57]
	v_mfma_i32_16x16x64_i8 v[50:53], v[176:179], v[184:187], v[50:53]
	v_mfma_i32_16x16x64_i8 v[38:41], v[168:171], v[192:195], v[38:41]
	v_mfma_i32_16x16x64_i8 v[34:37], v[176:179], v[192:195], v[34:37]
	v_mfma_i32_16x16x64_i8 v[22:25], v[168:171], v[200:203], v[22:25]
	v_mfma_i32_16x16x64_i8 v[18:21], v[176:179], v[200:203], v[18:21]
	v_mfma_i32_16x16x64_i8 v[6:9], v[168:171], v[208:211], v[6:9]
	v_mfma_i32_16x16x64_i8 v[2:5], v[176:179], v[208:211], v[2:5]
	v_mfma_i32_16x16x64_i8 v[54:57], v[172:175], v[188:191], v[54:57]
	v_mfma_i32_16x16x64_i8 v[50:53], v[180:183], v[188:191], v[50:53]
	v_mfma_i32_16x16x64_i8 v[38:41], v[172:175], v[196:199], v[38:41]
	v_mfma_i32_16x16x64_i8 v[34:37], v[180:183], v[196:199], v[34:37]
	v_mfma_i32_16x16x64_i8 v[22:25], v[172:175], v[204:207], v[22:25]
	v_mfma_i32_16x16x64_i8 v[18:21], v[180:183], v[204:207], v[18:21]
	v_mfma_i32_16x16x64_i8 v[6:9], v[172:175], v[212:215], v[6:9]
	v_mfma_i32_16x16x64_i8 v[2:5], v[180:183], v[212:215], v[2:5]
	s_setprio 0
	s_add_i32 s86, s86, 2
	s_add_u32 s89, s89, 0x100
	s_addc_u32 s90, s90, 0
	s_add_u32 s84, s84, 0x100
	s_addc_u32 s85, s85, 0
	s_cmp_gt_u32 s86, 5
	s_barrier
	s_cbranch_scc1 .Lpeel_exit_214
.LBB0_214:
	ds_read_b128 v[66:69], v161
	ds_read_b128 v[70:73], v161 offset:1024
	ds_read_b128 v[74:77], v161 offset:2048
	ds_read_b128 v[78:81], v161 offset:3072
	ds_read_b128 v[168:171], v163
	ds_read_b128 v[172:175], v163 offset:1024
	ds_read_b128 v[176:179], v163 offset:2048
	ds_read_b128 v[180:183], v163 offset:3072
	s_add_u32 s87, s84, 0xfffe0080
	s_addc_u32 s91, s85, -1
	s_cmp_eq_u32 s86, 4
	s_cselect_b32 s95, s34, s91
	s_cselect_b32 s94, s35, s87
	s_cselect_b32 s97, s75, s90
	s_cselect_b32 s96, s77, s89
	v_lshl_add_u64 v[158:159], s[84:85], 0, v[152:153]
	s_add_i32 m0, s56, 0xc000
	ds_read_b128 v[184:187], v165
	ds_read_b128 v[188:191], v165 offset:1024
	ds_read_b128 v[192:195], v165 offset:2048
	ds_read_b128 v[196:199], v165 offset:3072
	ds_read_b128 v[200:203], v165 offset:4096
	ds_read_b128 v[204:207], v165 offset:5120
	ds_read_b128 v[208:211], v165 offset:6144
	ds_read_b128 v[212:215], v165 offset:7168
	global_load_lds_dwordx4 v[158:159], off
	v_lshl_add_u64 v[158:159], v[158:159], 0, s[4:5]
	s_add_i32 m0, s56, 0xe000
	s_nop 0
	global_load_lds_dwordx4 v[158:159], off
	s_waitcnt vmcnt(8)
	s_waitcnt lgkmcnt(0)
	s_barrier
	s_setprio 1
	s_waitcnt lgkmcnt(0)
	v_mfma_i32_16x16x64_i8 v[142:145], v[66:69], v[184:187], v[142:145]
	v_mfma_i32_16x16x64_i8 v[138:141], v[74:77], v[184:187], v[138:141]
	v_mfma_i32_16x16x64_i8 v[126:129], v[66:69], v[192:195], v[126:129]
	v_mfma_i32_16x16x64_i8 v[122:125], v[74:77], v[192:195], v[122:125]
	v_mfma_i32_16x16x64_i8 v[110:113], v[66:69], v[200:203], v[110:113]
	v_mfma_i32_16x16x64_i8 v[106:109], v[74:77], v[200:203], v[106:109]
	v_mfma_i32_16x16x64_i8 v[94:97], v[66:69], v[208:211], v[94:97]
	v_mfma_i32_16x16x64_i8 v[90:93], v[74:77], v[208:211], v[90:93]
	v_mfma_i32_16x16x64_i8 v[142:145], v[70:73], v[188:191], v[142:145]
	v_mfma_i32_16x16x64_i8 v[138:141], v[78:81], v[188:191], v[138:141]
	v_mfma_i32_16x16x64_i8 v[126:129], v[70:73], v[196:199], v[126:129]
	v_mfma_i32_16x16x64_i8 v[122:125], v[78:81], v[196:199], v[122:125]
	v_mfma_i32_16x16x64_i8 v[110:113], v[70:73], v[204:207], v[110:113]
	v_mfma_i32_16x16x64_i8 v[106:109], v[78:81], v[204:207], v[106:109]
	v_mfma_i32_16x16x64_i8 v[94:97], v[70:73], v[212:215], v[94:97]
	v_mfma_i32_16x16x64_i8 v[90:93], v[78:81], v[212:215], v[90:93]
	s_setprio 0
	s_setprio 1
	v_mfma_i32_16x16x64_i8 v[134:137], v[168:171], v[184:187], v[134:137]
	v_mfma_i32_16x16x64_i8 v[130:133], v[176:179], v[184:187], v[130:133]
	v_mfma_i32_16x16x64_i8 v[118:121], v[168:171], v[192:195], v[118:121]
	v_mfma_i32_16x16x64_i8 v[114:117], v[176:179], v[192:195], v[114:117]
	v_mfma_i32_16x16x64_i8 v[102:105], v[168:171], v[200:203], v[102:105]
	v_mfma_i32_16x16x64_i8 v[98:101], v[176:179], v[200:203], v[98:101]
	v_mfma_i32_16x16x64_i8 v[86:89], v[168:171], v[208:211], v[86:89]
	v_mfma_i32_16x16x64_i8 v[82:85], v[176:179], v[208:211], v[82:85]
	v_mfma_i32_16x16x64_i8 v[134:137], v[172:175], v[188:191], v[134:137]
	v_mfma_i32_16x16x64_i8 v[130:133], v[180:183], v[188:191], v[130:133]
	v_mfma_i32_16x16x64_i8 v[118:121], v[172:175], v[196:199], v[118:121]
	v_mfma_i32_16x16x64_i8 v[114:117], v[180:183], v[196:199], v[114:117]
	v_mfma_i32_16x16x64_i8 v[102:105], v[172:175], v[204:207], v[102:105]
	v_mfma_i32_16x16x64_i8 v[98:101], v[180:183], v[204:207], v[98:101]
	v_mfma_i32_16x16x64_i8 v[86:89], v[172:175], v[212:215], v[86:89]
	v_mfma_i32_16x16x64_i8 v[82:85], v[180:183], v[212:215], v[82:85]
	s_setprio 0
	s_barrier
	s_add_i32 s87, s64, s16
	v_lshl_add_u64 v[158:159], s[96:97], 0, v[148:149]
	s_mov_b32 m0, s87
	ds_read_b128 v[184:187], v165 offset:16384
	ds_read_b128 v[188:191], v165 offset:17408
	ds_read_b128 v[192:195], v165 offset:18432
	ds_read_b128 v[196:199], v165 offset:19456
	ds_read_b128 v[200:203], v165 offset:20480
	ds_read_b128 v[204:207], v165 offset:21504
	ds_read_b128 v[208:211], v165 offset:22528
	ds_read_b128 v[212:215], v165 offset:23552
	global_load_lds_dwordx4 v[158:159], off
	v_lshl_add_u64 v[216:217], v[158:159], 0, s[4:5]
	s_add_i32 m0, s87, 0x2000
	s_add_i32 s87, s65, s16
	global_load_lds_dwordx4 v[216:217], off
	v_lshl_add_u64 v[216:217], v[158:159], 0, s[10:11]
	s_mov_b32 m0, s87
	s_nop 0
	global_load_lds_dwordx4 v[216:217], off
	v_lshl_add_u64 v[216:217], v[158:159], 0, s[12:13]
	s_add_i32 m0, s87, 0x2000
	s_nop 0
	global_load_lds_dwordx4 v[216:217], off
	v_lshl_add_u64 v[216:217], s[94:95], 0, v[146:147]
	s_mov_b32 m0, s56
	v_lshl_add_u64 v[218:219], v[216:217], 0, s[4:5]
	global_load_lds_dwordx4 v[216:217], off
	s_mov_b32 m0, s57
	s_nop 0
	global_load_lds_dwordx4 v[218:219], off
	s_waitcnt vmcnt(8)
	s_waitcnt lgkmcnt(0)
	s_barrier
	s_setprio 1
	s_waitcnt lgkmcnt(0)
	v_mfma_i32_16x16x64_i8 v[62:65], v[66:69], v[184:187], v[62:65]
	v_mfma_i32_16x16x64_i8 v[58:61], v[74:77], v[184:187], v[58:61]
	v_mfma_i32_16x16x64_i8 v[46:49], v[66:69], v[192:195], v[46:49]
	v_mfma_i32_16x16x64_i8 v[42:45], v[74:77], v[192:195], v[42:45]
	v_mfma_i32_16x16x64_i8 v[30:33], v[66:69], v[200:203], v[30:33]
	v_mfma_i32_16x16x64_i8 v[26:29], v[74:77], v[200:203], v[26:29]
	v_mfma_i32_16x16x64_i8 v[14:17], v[66:69], v[208:211], v[14:17]
	v_mfma_i32_16x16x64_i8 v[10:13], v[74:77], v[208:211], v[10:13]
	v_mfma_i32_16x16x64_i8 v[62:65], v[70:73], v[188:191], v[62:65]
	v_mfma_i32_16x16x64_i8 v[58:61], v[78:81], v[188:191], v[58:61]
	v_mfma_i32_16x16x64_i8 v[46:49], v[70:73], v[196:199], v[46:49]
	v_mfma_i32_16x16x64_i8 v[42:45], v[78:81], v[196:199], v[42:45]
	v_mfma_i32_16x16x64_i8 v[30:33], v[70:73], v[204:207], v[30:33]
	v_mfma_i32_16x16x64_i8 v[26:29], v[78:81], v[204:207], v[26:29]
	v_mfma_i32_16x16x64_i8 v[14:17], v[70:73], v[212:215], v[14:17]
	v_mfma_i32_16x16x64_i8 v[10:13], v[78:81], v[212:215], v[10:13]
	s_setprio 0
	s_setprio 1
	v_mfma_i32_16x16x64_i8 v[54:57], v[168:171], v[184:187], v[54:57]
	v_mfma_i32_16x16x64_i8 v[50:53], v[176:179], v[184:187], v[50:53]
	v_mfma_i32_16x16x64_i8 v[38:41], v[168:171], v[192:195], v[38:41]
	v_mfma_i32_16x16x64_i8 v[34:37], v[176:179], v[192:195], v[34:37]
	v_mfma_i32_16x16x64_i8 v[22:25], v[168:171], v[200:203], v[22:25]
	v_mfma_i32_16x16x64_i8 v[18:21], v[176:179], v[200:203], v[18:21]
	v_mfma_i32_16x16x64_i8 v[6:9], v[168:171], v[208:211], v[6:9]
	v_mfma_i32_16x16x64_i8 v[2:5], v[176:179], v[208:211], v[2:5]
	v_mfma_i32_16x16x64_i8 v[54:57], v[172:175], v[188:191], v[54:57]
	v_mfma_i32_16x16x64_i8 v[50:53], v[180:183], v[188:191], v[50:53]
	v_mfma_i32_16x16x64_i8 v[38:41], v[172:175], v[196:199], v[38:41]
	v_mfma_i32_16x16x64_i8 v[34:37], v[180:183], v[196:199], v[34:37]
	v_mfma_i32_16x16x64_i8 v[22:25], v[172:175], v[204:207], v[22:25]
	v_mfma_i32_16x16x64_i8 v[18:21], v[180:183], v[204:207], v[18:21]
	v_mfma_i32_16x16x64_i8 v[6:9], v[172:175], v[212:215], v[6:9]
	v_mfma_i32_16x16x64_i8 v[2:5], v[180:183], v[212:215], v[2:5]
	s_setprio 0
	s_barrier
	s_add_i32 s87, 0, 0x18000
	s_add_i32 s91, 0, 0x1c000
	v_add_u32_e32 v78, s87, v1
	v_add_u32_e32 v150, s91, v1
	ds_read_b128 v[66:69], v78
	ds_read_b128 v[70:73], v78 offset:1024
	ds_read_b128 v[74:77], v78 offset:2048
	ds_read_b128 v[78:81], v78 offset:3072
	ds_read_b128 v[168:171], v150
	ds_read_b128 v[172:175], v150 offset:1024
	ds_read_b128 v[176:179], v150 offset:2048
	ds_read_b128 v[180:183], v150 offset:3072
	s_mov_b32 m0, s58
	v_lshl_add_u64 v[218:219], v[216:217], 0, s[10:11]
	ds_read_b128 v[184:187], v165 offset:32768
	ds_read_b128 v[188:191], v165 offset:33792
	ds_read_b128 v[192:195], v165 offset:34816
	ds_read_b128 v[196:199], v165 offset:35840
	ds_read_b128 v[200:203], v165 offset:36864
	ds_read_b128 v[204:207], v165 offset:37888
	ds_read_b128 v[208:211], v165 offset:38912
	ds_read_b128 v[212:215], v165 offset:39936
	global_load_lds_dwordx4 v[218:219], off
	v_lshl_add_u64 v[218:219], v[216:217], 0, s[12:13]
	s_mov_b32 m0, s59
	s_nop 0
	global_load_lds_dwordx4 v[218:219], off
	s_waitcnt vmcnt(8)
	s_waitcnt lgkmcnt(0)
	s_barrier
	s_setprio 1
	s_waitcnt lgkmcnt(0)
	v_mfma_i32_16x16x64_i8 v[142:145], v[66:69], v[184:187], v[142:145]
	v_mfma_i32_16x16x64_i8 v[138:141], v[74:77], v[184:187], v[138:141]
	v_mfma_i32_16x16x64_i8 v[126:129], v[66:69], v[192:195], v[126:129]
	v_mfma_i32_16x16x64_i8 v[122:125], v[74:77], v[192:195], v[122:125]
	v_mfma_i32_16x16x64_i8 v[110:113], v[66:69], v[200:203], v[110:113]
	v_mfma_i32_16x16x64_i8 v[106:109], v[74:77], v[200:203], v[106:109]
	v_mfma_i32_16x16x64_i8 v[94:97], v[66:69], v[208:211], v[94:97]
	v_mfma_i32_16x16x64_i8 v[90:93], v[74:77], v[208:211], v[90:93]
	v_mfma_i32_16x16x64_i8 v[142:145], v[70:73], v[188:191], v[142:145]
	v_mfma_i32_16x16x64_i8 v[138:141], v[78:81], v[188:191], v[138:141]
	v_mfma_i32_16x16x64_i8 v[126:129], v[70:73], v[196:199], v[126:129]
	v_mfma_i32_16x16x64_i8 v[122:125], v[78:81], v[196:199], v[122:125]
	v_mfma_i32_16x16x64_i8 v[110:113], v[70:73], v[204:207], v[110:113]
	v_mfma_i32_16x16x64_i8 v[106:109], v[78:81], v[204:207], v[106:109]
	v_mfma_i32_16x16x64_i8 v[94:97], v[70:73], v[212:215], v[94:97]
	v_mfma_i32_16x16x64_i8 v[90:93], v[78:81], v[212:215], v[90:93]
	s_setprio 0
	s_setprio 1
	v_mfma_i32_16x16x64_i8 v[134:137], v[168:171], v[184:187], v[134:137]
	v_mfma_i32_16x16x64_i8 v[130:133], v[176:179], v[184:187], v[130:133]
	v_mfma_i32_16x16x64_i8 v[118:121], v[168:171], v[192:195], v[118:121]
	v_mfma_i32_16x16x64_i8 v[114:117], v[176:179], v[192:195], v[114:117]
	v_mfma_i32_16x16x64_i8 v[102:105], v[168:171], v[200:203], v[102:105]
	v_mfma_i32_16x16x64_i8 v[98:101], v[176:179], v[200:203], v[98:101]
	v_mfma_i32_16x16x64_i8 v[86:89], v[168:171], v[208:211], v[86:89]
	v_mfma_i32_16x16x64_i8 v[82:85], v[176:179], v[208:211], v[82:85]
	v_mfma_i32_16x16x64_i8 v[134:137], v[172:175], v[188:191], v[134:137]
	v_mfma_i32_16x16x64_i8 v[130:133], v[180:183], v[188:191], v[130:133]
	v_mfma_i32_16x16x64_i8 v[118:121], v[172:175], v[196:199], v[118:121]
	v_mfma_i32_16x16x64_i8 v[114:117], v[180:183], v[196:199], v[114:117]
	v_mfma_i32_16x16x64_i8 v[102:105], v[172:175], v[204:207], v[102:105]
	v_mfma_i32_16x16x64_i8 v[98:101], v[180:183], v[204:207], v[98:101]
	v_mfma_i32_16x16x64_i8 v[86:89], v[172:175], v[212:215], v[86:89]
	v_mfma_i32_16x16x64_i8 v[82:85], v[180:183], v[212:215], v[82:85]
	s_setprio 0
	s_barrier
	s_add_i32 s87, s87, s16
	v_lshl_add_u64 v[218:219], v[158:159], 0, s[48:49]
	s_mov_b32 m0, s87
	ds_read_b128 v[184:187], v165 offset:49152
	ds_read_b128 v[188:191], v165 offset:50176
	ds_read_b128 v[192:195], v165 offset:51200
	ds_read_b128 v[196:199], v165 offset:52224
	ds_read_b128 v[200:203], v165 offset:53248
	ds_read_b128 v[204:207], v165 offset:54272
	ds_read_b128 v[208:211], v165 offset:55296
	ds_read_b128 v[212:215], v165 offset:56320
	global_load_lds_dwordx4 v[218:219], off
	v_lshl_add_u64 v[218:219], v[158:159], 0, s[50:51]
	s_add_i32 m0, s87, 0x2000
	s_add_i32 s87, s91, s16
	global_load_lds_dwordx4 v[218:219], off
	v_lshl_add_u64 v[218:219], v[158:159], 0, s[52:53]
	s_mov_b32 m0, s87
	v_lshl_add_u64 v[158:159], v[158:159], 0, s[66:67]
	global_load_lds_dwordx4 v[218:219], off
	s_add_i32 m0, s87, 0x2000
	s_nop 0
	global_load_lds_dwordx4 v[158:159], off
	v_lshl_add_u64 v[158:159], v[216:217], 0, s[48:49]
	s_mov_b32 m0, s62
	s_nop 0
	global_load_lds_dwordx4 v[158:159], off
	v_lshl_add_u64 v[158:159], v[216:217], 0, s[50:51]
	s_mov_b32 m0, s63
	s_nop 0
	global_load_lds_dwordx4 v[158:159], off
	s_waitcnt vmcnt(8)
	s_waitcnt lgkmcnt(0)
	s_barrier
	s_setprio 1
	s_waitcnt lgkmcnt(0)
	v_mfma_i32_16x16x64_i8 v[62:65], v[66:69], v[184:187], v[62:65]
	v_mfma_i32_16x16x64_i8 v[58:61], v[74:77], v[184:187], v[58:61]
	v_mfma_i32_16x16x64_i8 v[46:49], v[66:69], v[192:195], v[46:49]
	v_mfma_i32_16x16x64_i8 v[42:45], v[74:77], v[192:195], v[42:45]
	v_mfma_i32_16x16x64_i8 v[30:33], v[66:69], v[200:203], v[30:33]
	v_mfma_i32_16x16x64_i8 v[26:29], v[74:77], v[200:203], v[26:29]
	v_mfma_i32_16x16x64_i8 v[14:17], v[66:69], v[208:211], v[14:17]
	v_mfma_i32_16x16x64_i8 v[10:13], v[74:77], v[208:211], v[10:13]
	v_mfma_i32_16x16x64_i8 v[62:65], v[70:73], v[188:191], v[62:65]
	v_mfma_i32_16x16x64_i8 v[58:61], v[78:81], v[188:191], v[58:61]
	v_mfma_i32_16x16x64_i8 v[46:49], v[70:73], v[196:199], v[46:49]
	v_mfma_i32_16x16x64_i8 v[42:45], v[78:81], v[196:199], v[42:45]
	v_mfma_i32_16x16x64_i8 v[30:33], v[70:73], v[204:207], v[30:33]
	v_mfma_i32_16x16x64_i8 v[26:29], v[78:81], v[204:207], v[26:29]
	v_mfma_i32_16x16x64_i8 v[14:17], v[70:73], v[212:215], v[14:17]
	v_mfma_i32_16x16x64_i8 v[10:13], v[78:81], v[212:215], v[10:13]
	s_setprio 0
	s_setprio 1
	v_mfma_i32_16x16x64_i8 v[54:57], v[168:171], v[184:187], v[54:57]
	v_mfma_i32_16x16x64_i8 v[50:53], v[176:179], v[184:187], v[50:53]
	v_mfma_i32_16x16x64_i8 v[38:41], v[168:171], v[192:195], v[38:41]
	v_mfma_i32_16x16x64_i8 v[34:37], v[176:179], v[192:195], v[34:37]
	v_mfma_i32_16x16x64_i8 v[22:25], v[168:171], v[200:203], v[22:25]
	v_mfma_i32_16x16x64_i8 v[18:21], v[176:179], v[200:203], v[18:21]
	v_mfma_i32_16x16x64_i8 v[6:9], v[168:171], v[208:211], v[6:9]
	v_mfma_i32_16x16x64_i8 v[2:5], v[176:179], v[208:211], v[2:5]
	v_mfma_i32_16x16x64_i8 v[54:57], v[172:175], v[188:191], v[54:57]
	v_mfma_i32_16x16x64_i8 v[50:53], v[180:183], v[188:191], v[50:53]
	v_mfma_i32_16x16x64_i8 v[38:41], v[172:175], v[196:199], v[38:41]
	v_mfma_i32_16x16x64_i8 v[34:37], v[180:183], v[196:199], v[34:37]
	v_mfma_i32_16x16x64_i8 v[22:25], v[172:175], v[204:207], v[22:25]
	v_mfma_i32_16x16x64_i8 v[18:21], v[180:183], v[204:207], v[18:21]
	v_mfma_i32_16x16x64_i8 v[6:9], v[172:175], v[212:215], v[6:9]
	v_mfma_i32_16x16x64_i8 v[2:5], v[180:183], v[212:215], v[2:5]
	s_setprio 0
	s_add_i32 s86, s86, 2
	s_add_u32 s89, s89, 0x100
	s_addc_u32 s90, s90, 0
	s_add_u32 s84, s84, 0x100
	s_addc_u32 s85, s85, 0
	s_cmp_gt_u32 s86, 5
	s_barrier
	s_cbranch_scc0 .LBB0_214

.Lpeel_275:
	ds_read_b128 v[140:143], v186
	ds_read_b128 v[144:147], v186 offset:1024
	ds_read_b128 v[148:151], v186 offset:2048
	ds_read_b128 v[152:155], v186 offset:3072
	ds_read_b128 v[156:159], v187
	ds_read_b128 v[160:163], v187 offset:1024
	ds_read_b128 v[164:167], v187 offset:2048
	ds_read_b128 v[168:171], v187 offset:3072
	s_add_u32 s78, s0, 0xfffa8080
	s_addc_u32 s79, s1, -1
	s_cmp_eq_u32 s88, 18
	s_cselect_b32 s79, s75, s79
	s_cselect_b32 s78, s74, s78
	s_cselect_b32 s81, s77, s87
	s_cselect_b32 s80, s76, s86
	v_lshl_add_u64 v[180:181], s[0:1], 0, v[134:135]
	s_add_i32 m0, s17, 0xc000
	ds_read_b128 v[172:175], v188
	ds_read_b128 v[176:179], v188 offset:1024
	ds_read_b128 v[192:195], v188 offset:2048
	ds_read_b128 v[196:199], v188 offset:3072
	ds_read_b128 v[200:203], v188 offset:4096
	ds_read_b128 v[204:207], v188 offset:5120
	ds_read_b128 v[208:211], v188 offset:6144
	ds_read_b128 v[212:215], v188 offset:7168
	global_load_lds_dwordx4 v[180:181], off
	v_lshl_add_u64 v[180:181], v[180:181], 0, s[10:11]
	s_add_i32 m0, s17, 0xe000
	s_nop 0
	global_load_lds_dwordx4 v[180:181], off
	s_waitcnt vmcnt(8)
	s_waitcnt lgkmcnt(0)
	s_barrier
	s_setprio 1
	s_waitcnt lgkmcnt(0)
	v_mfma_scale_f32_16x16x128_f8f6f4 v[126:129], v[140:147], v[172:179], 0, v189, v189 op_sel_hi:[0, 0, 0]
	v_mfma_scale_f32_16x16x128_f8f6f4 v[122:125], v[148:155], v[172:179], 0, v189, v189 op_sel_hi:[0, 0, 0]
	v_mfma_scale_f32_16x16x128_f8f6f4 v[118:121], v[140:147], v[192:199], 0, v189, v189 op_sel_hi:[0, 0, 0]
	v_mfma_scale_f32_16x16x128_f8f6f4 v[114:117], v[148:155], v[192:199], 0, v189, v189 op_sel_hi:[0, 0, 0]
	v_mfma_scale_f32_16x16x128_f8f6f4 v[110:113], v[140:147], v[200:207], 0, v189, v189 op_sel_hi:[0, 0, 0]
	v_mfma_scale_f32_16x16x128_f8f6f4 v[106:109], v[148:155], v[200:207], 0, v189, v189 op_sel_hi:[0, 0, 0]
	v_mfma_scale_f32_16x16x128_f8f6f4 v[102:105], v[140:147], v[208:215], 0, v189, v189 op_sel_hi:[0, 0, 0]
	v_mfma_scale_f32_16x16x128_f8f6f4 v[98:101], v[148:155], v[208:215], 0, v189, v189 op_sel_hi:[0, 0, 0]
	s_setprio 0
	s_setprio 1
	v_mfma_scale_f32_16x16x128_f8f6f4 v[180:183], v[156:163], v[172:179], 0, v189, v189 op_sel_hi:[0, 0, 0]
	v_mfma_scale_f32_16x16x128_f8f6f4 v[172:175], v[164:171], v[172:179], 0, v189, v189 op_sel_hi:[0, 0, 0]
	v_mfma_scale_f32_16x16x128_f8f6f4 v[176:179], v[156:163], v[192:199], 0, v189, v189 op_sel_hi:[0, 0, 0]
	v_mfma_scale_f32_16x16x128_f8f6f4 v[192:195], v[164:171], v[192:199], 0, v189, v189 op_sel_hi:[0, 0, 0]
	v_mfma_scale_f32_16x16x128_f8f6f4 v[196:199], v[156:163], v[200:207], 0, v189, v189 op_sel_hi:[0, 0, 0]
	v_mfma_scale_f32_16x16x128_f8f6f4 v[200:203], v[164:171], v[200:207], 0, v189, v189 op_sel_hi:[0, 0, 0]
	v_mfma_scale_f32_16x16x128_f8f6f4 v[204:207], v[156:163], v[208:215], 0, v189, v189 op_sel_hi:[0, 0, 0]
	v_mfma_scale_f32_16x16x128_f8f6f4 v[208:211], v[164:171], v[208:215], 0, v189, v189 op_sel_hi:[0, 0, 0]
	s_setprio 0
	s_barrier
	v_lshl_add_u64 v[184:185], s[80:81], 0, v[132:133]
	s_add_i32 s80, s82, s16
	s_mov_b32 m0, s80
	s_nop 1
	ds_read_b128 v[34:37], v188 offset:16384
	ds_read_b128 v[38:41], v188 offset:17408
	ds_read_b128 v[42:45], v188 offset:18432
	ds_read_b128 v[46:49], v188 offset:19456
	ds_read_b128 v[50:53], v188 offset:20480
	ds_read_b128 v[54:57], v188 offset:21504
	ds_read_b128 v[58:61], v188 offset:22528
	ds_read_b128 v[62:65], v188 offset:23552
	global_load_lds_dwordx4 v[184:185], off
	v_lshl_add_u64 v[212:213], v[184:185], 0, s[10:11]
	s_add_i32 m0, s80, 0x2000
	s_add_i32 s80, s83, s16
	global_load_lds_dwordx4 v[212:213], off
	v_lshl_add_u64 v[212:213], v[184:185], 0, s[12:13]
	s_mov_b32 m0, s80
	v_lshl_add_u64 v[252:253], s[78:79], 0, v[130:131]
	global_load_lds_dwordx4 v[212:213], off
	v_lshl_add_u64 v[212:213], v[184:185], 0, s[14:15]
	s_add_i32 m0, s80, 0x2000
	s_nop 0
	global_load_lds_dwordx4 v[212:213], off
	s_mov_b32 m0, s17
	v_lshl_add_u64 v[212:213], v[252:253], 0, s[10:11]
	global_load_lds_dwordx4 v[252:253], off
	s_mov_b32 m0, s33
	s_nop 0
	global_load_lds_dwordx4 v[212:213], off
	s_waitcnt vmcnt(8)
	s_waitcnt lgkmcnt(0)
	s_barrier
	s_setprio 1
	s_waitcnt lgkmcnt(0)
	v_mfma_scale_f32_16x16x128_f8f6f4 v[94:97], v[140:147], v[34:41], 0, v189, v189 op_sel_hi:[0, 0, 0]
	v_mfma_scale_f32_16x16x128_f8f6f4 v[90:93], v[148:155], v[34:41], 0, v189, v189 op_sel_hi:[0, 0, 0]
	v_mfma_scale_f32_16x16x128_f8f6f4 v[86:89], v[140:147], v[42:49], 0, v189, v189 op_sel_hi:[0, 0, 0]
	v_mfma_scale_f32_16x16x128_f8f6f4 v[82:85], v[148:155], v[42:49], 0, v189, v189 op_sel_hi:[0, 0, 0]
	v_mfma_scale_f32_16x16x128_f8f6f4 v[78:81], v[140:147], v[50:57], 0, v189, v189 op_sel_hi:[0, 0, 0]
	v_mfma_scale_f32_16x16x128_f8f6f4 v[74:77], v[148:155], v[50:57], 0, v189, v189 op_sel_hi:[0, 0, 0]
	v_mfma_scale_f32_16x16x128_f8f6f4 v[212:215], v[140:147], v[58:65], 0, v189, v189 op_sel_hi:[0, 0, 0]
	v_mfma_scale_f32_16x16x128_f8f6f4 v[216:219], v[148:155], v[58:65], 0, v189, v189 op_sel_hi:[0, 0, 0]
	s_setprio 0
	s_setprio 1
	v_mfma_scale_f32_16x16x128_f8f6f4 v[220:223], v[156:163], v[34:41], 0, v189, v189 op_sel_hi:[0, 0, 0]
	v_mfma_scale_f32_16x16x128_f8f6f4 v[224:227], v[164:171], v[34:41], 0, v189, v189 op_sel_hi:[0, 0, 0]
	v_mfma_scale_f32_16x16x128_f8f6f4 v[228:231], v[156:163], v[42:49], 0, v189, v189 op_sel_hi:[0, 0, 0]
	v_mfma_scale_f32_16x16x128_f8f6f4 v[232:235], v[164:171], v[42:49], 0, v189, v189 op_sel_hi:[0, 0, 0]
	v_mfma_scale_f32_16x16x128_f8f6f4 v[236:239], v[156:163], v[50:57], 0, v189, v189 op_sel_hi:[0, 0, 0]
	v_mfma_scale_f32_16x16x128_f8f6f4 v[240:243], v[164:171], v[50:57], 0, v189, v189 op_sel_hi:[0, 0, 0]
	v_mfma_scale_f32_16x16x128_f8f6f4 v[244:247], v[156:163], v[58:65], 0, v189, v189 op_sel_hi:[0, 0, 0]
	v_mfma_scale_f32_16x16x128_f8f6f4 v[248:251], v[164:171], v[58:65], 0, v189, v189 op_sel_hi:[0, 0, 0]
	s_setprio 0
	s_barrier
	s_add_i32 s78, 0, 0x18000
	s_add_i32 s79, 0, 0x1c000
	v_add_u32_e32 v14, s78, v1
	v_add_u32_e32 v18, s79, v1
	s_nop 0
	ds_read_b128 v[2:5], v14
	ds_read_b128 v[6:9], v14 offset:1024
	ds_read_b128 v[10:13], v14 offset:2048
	ds_read_b128 v[14:17], v14 offset:3072
	ds_read_b128 v[140:143], v18
	ds_read_b128 v[144:147], v18 offset:1024
	ds_read_b128 v[148:151], v18 offset:2048
	ds_read_b128 v[152:155], v18 offset:3072
	s_mov_b32 m0, s54
	v_lshl_add_u64 v[42:43], v[252:253], 0, s[12:13]
	ds_read_b128 v[18:21], v188 offset:32768
	ds_read_b128 v[22:25], v188 offset:33792
	ds_read_b128 v[26:29], v188 offset:34816
	ds_read_b128 v[30:33], v188 offset:35840
	ds_read_b128 v[34:37], v188 offset:36864
	ds_read_b128 v[38:41], v188 offset:37888
	ds_read_b128 v[66:69], v188 offset:38912
	ds_read_b128 v[70:73], v188 offset:39936
	global_load_lds_dwordx4 v[42:43], off
	v_lshl_add_u64 v[42:43], v[252:253], 0, s[14:15]
	s_mov_b32 m0, s55
	s_nop 0
	global_load_lds_dwordx4 v[42:43], off
	s_waitcnt vmcnt(8)
	s_waitcnt lgkmcnt(0)
	s_barrier
	s_setprio 1
	s_waitcnt lgkmcnt(0)
	v_mfma_scale_f32_16x16x128_f8f6f4 v[126:129], v[2:9], v[18:25], v[126:129], v189, v189 op_sel_hi:[0,0,0]
	v_mfma_scale_f32_16x16x128_f8f6f4 v[122:125], v[10:17], v[18:25], v[122:125], v189, v189 op_sel_hi:[0,0,0]
	v_mfma_scale_f32_16x16x128_f8f6f4 v[118:121], v[2:9], v[26:33], v[118:121], v189, v189 op_sel_hi:[0,0,0]
	v_mfma_scale_f32_16x16x128_f8f6f4 v[114:117], v[10:17], v[26:33], v[114:117], v189, v189 op_sel_hi:[0,0,0]
	v_mfma_scale_f32_16x16x128_f8f6f4 v[110:113], v[2:9], v[34:41], v[110:113], v189, v189 op_sel_hi:[0,0,0]
	v_mfma_scale_f32_16x16x128_f8f6f4 v[106:109], v[10:17], v[34:41], v[106:109], v189, v189 op_sel_hi:[0,0,0]
	v_mfma_scale_f32_16x16x128_f8f6f4 v[102:105], v[2:9], v[66:73], v[102:105], v189, v189 op_sel_hi:[0,0,0]
	v_mfma_scale_f32_16x16x128_f8f6f4 v[98:101], v[10:17], v[66:73], v[98:101], v189, v189 op_sel_hi:[0,0,0]
	s_setprio 0
	s_setprio 1
	v_mfma_scale_f32_16x16x128_f8f6f4 v[62:65], v[140:147], v[18:25], v[180:183], v189, v189 op_sel_hi:[0,0,0]
	v_mfma_scale_f32_16x16x128_f8f6f4 v[58:61], v[148:155], v[18:25], v[172:175], v189, v189 op_sel_hi:[0,0,0]
	v_mfma_scale_f32_16x16x128_f8f6f4 v[54:57], v[140:147], v[26:33], v[176:179], v189, v189 op_sel_hi:[0,0,0]
	v_mfma_scale_f32_16x16x128_f8f6f4 v[50:53], v[148:155], v[26:33], v[192:195], v189, v189 op_sel_hi:[0,0,0]
	v_mfma_scale_f32_16x16x128_f8f6f4 v[46:49], v[140:147], v[34:41], v[196:199], v189, v189 op_sel_hi:[0,0,0]
	v_mfma_scale_f32_16x16x128_f8f6f4 v[42:45], v[148:155], v[34:41], v[200:203], v189, v189 op_sel_hi:[0,0,0]
	v_mfma_scale_f32_16x16x128_f8f6f4 v[38:41], v[140:147], v[66:73], v[204:207], v189, v189 op_sel_hi:[0,0,0]
	v_mfma_scale_f32_16x16x128_f8f6f4 v[34:37], v[148:155], v[66:73], v[208:211], v189, v189 op_sel_hi:[0,0,0]
	s_setprio 0
	s_barrier
	s_add_i32 s78, s78, s16
	v_lshl_add_u64 v[26:27], v[184:185], 0, s[48:49]
	s_mov_b32 m0, s78
	ds_read_b128 v[18:21], v188 offset:49152
	ds_read_b128 v[22:25], v188 offset:50176
	ds_read_b128 v[156:159], v188 offset:51200
	ds_read_b128 v[160:163], v188 offset:52224
	ds_read_b128 v[164:167], v188 offset:53248
	ds_read_b128 v[168:171], v188 offset:54272
	ds_read_b128 v[172:175], v188 offset:55296
	ds_read_b128 v[176:179], v188 offset:56320
	global_load_lds_dwordx4 v[26:27], off
	v_lshl_add_u64 v[26:27], v[184:185], 0, s[50:51]
	s_add_i32 m0, s78, 0x2000
	s_add_i32 s78, s79, s16
	global_load_lds_dwordx4 v[26:27], off
	v_lshl_add_u64 v[26:27], v[184:185], 0, s[52:53]
	s_mov_b32 m0, s78
	s_nop 0
	global_load_lds_dwordx4 v[26:27], off
	v_lshl_add_u64 v[26:27], v[184:185], 0, s[66:67]
	s_add_i32 m0, s78, 0x2000
	s_nop 0
	global_load_lds_dwordx4 v[26:27], off
	v_lshl_add_u64 v[26:27], v[252:253], 0, s[48:49]
	s_mov_b32 m0, s59
	s_nop 0
	global_load_lds_dwordx4 v[26:27], off
	v_lshl_add_u64 v[26:27], v[252:253], 0, s[50:51]
	s_mov_b32 m0, s60
	s_nop 0
	global_load_lds_dwordx4 v[26:27], off
	s_waitcnt vmcnt(8)
	s_waitcnt lgkmcnt(0)
	s_barrier
	s_setprio 1
	s_waitcnt lgkmcnt(0)
	v_mfma_scale_f32_16x16x128_f8f6f4 v[94:97], v[2:9], v[18:25], v[94:97], v189, v189 op_sel_hi:[0,0,0]
	v_mfma_scale_f32_16x16x128_f8f6f4 v[90:93], v[10:17], v[18:25], v[90:93], v189, v189 op_sel_hi:[0,0,0]
	v_mfma_scale_f32_16x16x128_f8f6f4 v[86:89], v[2:9], v[156:163], v[86:89], v189, v189 op_sel_hi:[0,0,0]
	v_mfma_scale_f32_16x16x128_f8f6f4 v[82:85], v[10:17], v[156:163], v[82:85], v189, v189 op_sel_hi:[0,0,0]
	v_mfma_scale_f32_16x16x128_f8f6f4 v[78:81], v[2:9], v[164:171], v[78:81], v189, v189 op_sel_hi:[0,0,0]
	v_mfma_scale_f32_16x16x128_f8f6f4 v[74:77], v[10:17], v[164:171], v[74:77], v189, v189 op_sel_hi:[0,0,0]
	v_mfma_scale_f32_16x16x128_f8f6f4 v[70:73], v[2:9], v[172:179], v[212:215], v189, v189 op_sel_hi:[0,0,0]
	v_mfma_scale_f32_16x16x128_f8f6f4 v[66:69], v[10:17], v[172:179], v[216:219], v189, v189 op_sel_hi:[0,0,0]
	s_setprio 0
	s_setprio 1
	v_mfma_scale_f32_16x16x128_f8f6f4 v[30:33], v[140:147], v[18:25], v[220:223], v189, v189 op_sel_hi:[0,0,0]
	v_mfma_scale_f32_16x16x128_f8f6f4 v[26:29], v[148:155], v[18:25], v[224:227], v189, v189 op_sel_hi:[0,0,0]
	v_mfma_scale_f32_16x16x128_f8f6f4 v[22:25], v[140:147], v[156:163], v[228:231], v189, v189 op_sel_hi:[0,0,0]
	v_mfma_scale_f32_16x16x128_f8f6f4 v[18:21], v[148:155], v[156:163], v[232:235], v189, v189 op_sel_hi:[0,0,0]
	v_mfma_scale_f32_16x16x128_f8f6f4 v[14:17], v[140:147], v[164:171], v[236:239], v189, v189 op_sel_hi:[0,0,0]
	v_mfma_scale_f32_16x16x128_f8f6f4 v[10:13], v[148:155], v[164:171], v[240:243], v189, v189 op_sel_hi:[0,0,0]
	v_mfma_scale_f32_16x16x128_f8f6f4 v[6:9], v[140:147], v[172:179], v[244:247], v189, v189 op_sel_hi:[0,0,0]
	v_mfma_scale_f32_16x16x128_f8f6f4 v[2:5], v[148:155], v[172:179], v[248:251], v189, v189 op_sel_hi:[0,0,0]
	s_setprio 0
	s_add_i32 s88, s88, 2
	s_add_u32 s86, s86, 0x100
	s_addc_u32 s87, s87, 0
	s_add_u32 s0, s0, 0x100
	s_addc_u32 s1, s1, 0
	s_cmp_gt_u32 s88, 19
	s_barrier
	s_cbranch_scc1 .Lpeel_exit_275
.LBB0_275:
	ds_read_b128 v[140:143], v186
	ds_read_b128 v[144:147], v186 offset:1024
	ds_read_b128 v[148:151], v186 offset:2048
	ds_read_b128 v[152:155], v186 offset:3072
	ds_read_b128 v[156:159], v187
	ds_read_b128 v[160:163], v187 offset:1024
	ds_read_b128 v[164:167], v187 offset:2048
	ds_read_b128 v[168:171], v187 offset:3072
	s_add_u32 s78, s0, 0xfffa8080
	s_addc_u32 s79, s1, -1
	s_cmp_eq_u32 s88, 18
	s_cselect_b32 s79, s75, s79
	s_cselect_b32 s78, s74, s78
	s_cselect_b32 s81, s77, s87
	s_cselect_b32 s80, s76, s86
	v_lshl_add_u64 v[180:181], s[0:1], 0, v[134:135]
	s_add_i32 m0, s17, 0xc000
	ds_read_b128 v[172:175], v188
	ds_read_b128 v[176:179], v188 offset:1024
	ds_read_b128 v[192:195], v188 offset:2048
	ds_read_b128 v[196:199], v188 offset:3072
	ds_read_b128 v[200:203], v188 offset:4096
	ds_read_b128 v[204:207], v188 offset:5120
	ds_read_b128 v[208:211], v188 offset:6144
	ds_read_b128 v[212:215], v188 offset:7168
	global_load_lds_dwordx4 v[180:181], off
	v_lshl_add_u64 v[180:181], v[180:181], 0, s[10:11]
	s_add_i32 m0, s17, 0xe000
	s_nop 0
	global_load_lds_dwordx4 v[180:181], off
	s_waitcnt vmcnt(8)
	s_waitcnt lgkmcnt(0)
	s_barrier
	s_setprio 1
	s_waitcnt lgkmcnt(0)
	v_mfma_scale_f32_16x16x128_f8f6f4 v[126:129], v[140:147], v[172:179], v[126:129], v189, v189 op_sel_hi:[0,0,0]
	v_mfma_scale_f32_16x16x128_f8f6f4 v[122:125], v[148:155], v[172:179], v[122:125], v189, v189 op_sel_hi:[0,0,0]
	v_mfma_scale_f32_16x16x128_f8f6f4 v[118:121], v[140:147], v[192:199], v[118:121], v189, v189 op_sel_hi:[0,0,0]
	v_mfma_scale_f32_16x16x128_f8f6f4 v[114:117], v[148:155], v[192:199], v[114:117], v189, v189 op_sel_hi:[0,0,0]
	v_mfma_scale_f32_16x16x128_f8f6f4 v[110:113], v[140:147], v[200:207], v[110:113], v189, v189 op_sel_hi:[0,0,0]
	v_mfma_scale_f32_16x16x128_f8f6f4 v[106:109], v[148:155], v[200:207], v[106:109], v189, v189 op_sel_hi:[0,0,0]
	v_mfma_scale_f32_16x16x128_f8f6f4 v[102:105], v[140:147], v[208:215], v[102:105], v189, v189 op_sel_hi:[0,0,0]
	v_mfma_scale_f32_16x16x128_f8f6f4 v[98:101], v[148:155], v[208:215], v[98:101], v189, v189 op_sel_hi:[0,0,0]
	s_setprio 0
	s_setprio 1
	v_mfma_scale_f32_16x16x128_f8f6f4 v[180:183], v[156:163], v[172:179], v[62:65], v189, v189 op_sel_hi:[0,0,0]
	v_mfma_scale_f32_16x16x128_f8f6f4 v[172:175], v[164:171], v[172:179], v[58:61], v189, v189 op_sel_hi:[0,0,0]
	v_mfma_scale_f32_16x16x128_f8f6f4 v[176:179], v[156:163], v[192:199], v[54:57], v189, v189 op_sel_hi:[0,0,0]
	v_mfma_scale_f32_16x16x128_f8f6f4 v[192:195], v[164:171], v[192:199], v[50:53], v189, v189 op_sel_hi:[0,0,0]
	v_mfma_scale_f32_16x16x128_f8f6f4 v[196:199], v[156:163], v[200:207], v[46:49], v189, v189 op_sel_hi:[0,0,0]
	v_mfma_scale_f32_16x16x128_f8f6f4 v[200:203], v[164:171], v[200:207], v[42:45], v189, v189 op_sel_hi:[0,0,0]
	v_mfma_scale_f32_16x16x128_f8f6f4 v[204:207], v[156:163], v[208:215], v[38:41], v189, v189 op_sel_hi:[0,0,0]
	v_mfma_scale_f32_16x16x128_f8f6f4 v[208:211], v[164:171], v[208:215], v[34:37], v189, v189 op_sel_hi:[0,0,0]
	s_setprio 0
	s_barrier
	v_lshl_add_u64 v[184:185], s[80:81], 0, v[132:133]
	s_add_i32 s80, s82, s16
	s_mov_b32 m0, s80
	s_nop 1
	ds_read_b128 v[34:37], v188 offset:16384
	ds_read_b128 v[38:41], v188 offset:17408
	ds_read_b128 v[42:45], v188 offset:18432
	ds_read_b128 v[46:49], v188 offset:19456
	ds_read_b128 v[50:53], v188 offset:20480
	ds_read_b128 v[54:57], v188 offset:21504
	ds_read_b128 v[58:61], v188 offset:22528
	ds_read_b128 v[62:65], v188 offset:23552
	global_load_lds_dwordx4 v[184:185], off
	v_lshl_add_u64 v[212:213], v[184:185], 0, s[10:11]
	s_add_i32 m0, s80, 0x2000
	s_add_i32 s80, s83, s16
	global_load_lds_dwordx4 v[212:213], off
	v_lshl_add_u64 v[212:213], v[184:185], 0, s[12:13]
	s_mov_b32 m0, s80
	v_lshl_add_u64 v[252:253], s[78:79], 0, v[130:131]
	global_load_lds_dwordx4 v[212:213], off
	v_lshl_add_u64 v[212:213], v[184:185], 0, s[14:15]
	s_add_i32 m0, s80, 0x2000
	s_nop 0
	global_load_lds_dwordx4 v[212:213], off
	s_mov_b32 m0, s17
	v_lshl_add_u64 v[212:213], v[252:253], 0, s[10:11]
	global_load_lds_dwordx4 v[252:253], off
	s_mov_b32 m0, s33
	s_nop 0
	global_load_lds_dwordx4 v[212:213], off
	s_waitcnt vmcnt(8)
	s_waitcnt lgkmcnt(0)
	s_barrier
	s_setprio 1
	s_waitcnt lgkmcnt(0)
	v_mfma_scale_f32_16x16x128_f8f6f4 v[94:97], v[140:147], v[34:41], v[94:97], v189, v189 op_sel_hi:[0,0,0]
	v_mfma_scale_f32_16x16x128_f8f6f4 v[90:93], v[148:155], v[34:41], v[90:93], v189, v189 op_sel_hi:[0,0,0]
	v_mfma_scale_f32_16x16x128_f8f6f4 v[86:89], v[140:147], v[42:49], v[86:89], v189, v189 op_sel_hi:[0,0,0]
	v_mfma_scale_f32_16x16x128_f8f6f4 v[82:85], v[148:155], v[42:49], v[82:85], v189, v189 op_sel_hi:[0,0,0]
	v_mfma_scale_f32_16x16x128_f8f6f4 v[78:81], v[140:147], v[50:57], v[78:81], v189, v189 op_sel_hi:[0,0,0]
	v_mfma_scale_f32_16x16x128_f8f6f4 v[74:77], v[148:155], v[50:57], v[74:77], v189, v189 op_sel_hi:[0,0,0]
	v_mfma_scale_f32_16x16x128_f8f6f4 v[212:215], v[140:147], v[58:65], v[70:73], v189, v189 op_sel_hi:[0,0,0]
	v_mfma_scale_f32_16x16x128_f8f6f4 v[216:219], v[148:155], v[58:65], v[66:69], v189, v189 op_sel_hi:[0,0,0]
	s_setprio 0
	s_setprio 1
	v_mfma_scale_f32_16x16x128_f8f6f4 v[220:223], v[156:163], v[34:41], v[30:33], v189, v189 op_sel_hi:[0,0,0]
	v_mfma_scale_f32_16x16x128_f8f6f4 v[224:227], v[164:171], v[34:41], v[26:29], v189, v189 op_sel_hi:[0,0,0]
	v_mfma_scale_f32_16x16x128_f8f6f4 v[228:231], v[156:163], v[42:49], v[22:25], v189, v189 op_sel_hi:[0,0,0]
	v_mfma_scale_f32_16x16x128_f8f6f4 v[232:235], v[164:171], v[42:49], v[18:21], v189, v189 op_sel_hi:[0,0,0]
	v_mfma_scale_f32_16x16x128_f8f6f4 v[236:239], v[156:163], v[50:57], v[14:17], v189, v189 op_sel_hi:[0,0,0]
	v_mfma_scale_f32_16x16x128_f8f6f4 v[240:243], v[164:171], v[50:57], v[10:13], v189, v189 op_sel_hi:[0,0,0]
	v_mfma_scale_f32_16x16x128_f8f6f4 v[244:247], v[156:163], v[58:65], v[6:9], v189, v189 op_sel_hi:[0,0,0]
	v_mfma_scale_f32_16x16x128_f8f6f4 v[248:251], v[164:171], v[58:65], v[2:5], v189, v189 op_sel_hi:[0,0,0]
	s_setprio 0
	s_barrier
	s_add_i32 s78, 0, 0x18000
	s_add_i32 s79, 0, 0x1c000
	v_add_u32_e32 v14, s78, v1
	v_add_u32_e32 v18, s79, v1
	s_nop 0
	ds_read_b128 v[2:5], v14
	ds_read_b128 v[6:9], v14 offset:1024
	ds_read_b128 v[10:13], v14 offset:2048
	ds_read_b128 v[14:17], v14 offset:3072
	ds_read_b128 v[140:143], v18
	ds_read_b128 v[144:147], v18 offset:1024
	ds_read_b128 v[148:151], v18 offset:2048
	ds_read_b128 v[152:155], v18 offset:3072
	s_mov_b32 m0, s54
	v_lshl_add_u64 v[42:43], v[252:253], 0, s[12:13]
	ds_read_b128 v[18:21], v188 offset:32768
	ds_read_b128 v[22:25], v188 offset:33792
	ds_read_b128 v[26:29], v188 offset:34816
	ds_read_b128 v[30:33], v188 offset:35840
	ds_read_b128 v[34:37], v188 offset:36864
	ds_read_b128 v[38:41], v188 offset:37888
	ds_read_b128 v[66:69], v188 offset:38912
	ds_read_b128 v[70:73], v188 offset:39936
	global_load_lds_dwordx4 v[42:43], off
	v_lshl_add_u64 v[42:43], v[252:253], 0, s[14:15]
	s_mov_b32 m0, s55
	s_nop 0
	global_load_lds_dwordx4 v[42:43], off
	s_waitcnt vmcnt(8)
	s_waitcnt lgkmcnt(0)
	s_barrier
	s_setprio 1
	s_waitcnt lgkmcnt(0)
	v_mfma_scale_f32_16x16x128_f8f6f4 v[126:129], v[2:9], v[18:25], v[126:129], v189, v189 op_sel_hi:[0,0,0]
	v_mfma_scale_f32_16x16x128_f8f6f4 v[122:125], v[10:17], v[18:25], v[122:125], v189, v189 op_sel_hi:[0,0,0]
	v_mfma_scale_f32_16x16x128_f8f6f4 v[118:121], v[2:9], v[26:33], v[118:121], v189, v189 op_sel_hi:[0,0,0]
	v_mfma_scale_f32_16x16x128_f8f6f4 v[114:117], v[10:17], v[26:33], v[114:117], v189, v189 op_sel_hi:[0,0,0]
	v_mfma_scale_f32_16x16x128_f8f6f4 v[110:113], v[2:9], v[34:41], v[110:113], v189, v189 op_sel_hi:[0,0,0]
	v_mfma_scale_f32_16x16x128_f8f6f4 v[106:109], v[10:17], v[34:41], v[106:109], v189, v189 op_sel_hi:[0,0,0]
	v_mfma_scale_f32_16x16x128_f8f6f4 v[102:105], v[2:9], v[66:73], v[102:105], v189, v189 op_sel_hi:[0,0,0]
	v_mfma_scale_f32_16x16x128_f8f6f4 v[98:101], v[10:17], v[66:73], v[98:101], v189, v189 op_sel_hi:[0,0,0]
	s_setprio 0
	s_setprio 1
	v_mfma_scale_f32_16x16x128_f8f6f4 v[62:65], v[140:147], v[18:25], v[180:183], v189, v189 op_sel_hi:[0,0,0]
	v_mfma_scale_f32_16x16x128_f8f6f4 v[58:61], v[148:155], v[18:25], v[172:175], v189, v189 op_sel_hi:[0,0,0]
	v_mfma_scale_f32_16x16x128_f8f6f4 v[54:57], v[140:147], v[26:33], v[176:179], v189, v189 op_sel_hi:[0,0,0]
	v_mfma_scale_f32_16x16x128_f8f6f4 v[50:53], v[148:155], v[26:33], v[192:195], v189, v189 op_sel_hi:[0,0,0]
	v_mfma_scale_f32_16x16x128_f8f6f4 v[46:49], v[140:147], v[34:41], v[196:199], v189, v189 op_sel_hi:[0,0,0]
	v_mfma_scale_f32_16x16x128_f8f6f4 v[42:45], v[148:155], v[34:41], v[200:203], v189, v189 op_sel_hi:[0,0,0]
	v_mfma_scale_f32_16x16x128_f8f6f4 v[38:41], v[140:147], v[66:73], v[204:207], v189, v189 op_sel_hi:[0,0,0]
	v_mfma_scale_f32_16x16x128_f8f6f4 v[34:37], v[148:155], v[66:73], v[208:211], v189, v189 op_sel_hi:[0,0,0]
	s_setprio 0
	s_barrier
	s_add_i32 s78, s78, s16
	v_lshl_add_u64 v[26:27], v[184:185], 0, s[48:49]
	s_mov_b32 m0, s78
	ds_read_b128 v[18:21], v188 offset:49152
	ds_read_b128 v[22:25], v188 offset:50176
	ds_read_b128 v[156:159], v188 offset:51200
	ds_read_b128 v[160:163], v188 offset:52224
	ds_read_b128 v[164:167], v188 offset:53248
	ds_read_b128 v[168:171], v188 offset:54272
	ds_read_b128 v[172:175], v188 offset:55296
	ds_read_b128 v[176:179], v188 offset:56320
	global_load_lds_dwordx4 v[26:27], off
	v_lshl_add_u64 v[26:27], v[184:185], 0, s[50:51]
	s_add_i32 m0, s78, 0x2000
	s_add_i32 s78, s79, s16
	global_load_lds_dwordx4 v[26:27], off
	v_lshl_add_u64 v[26:27], v[184:185], 0, s[52:53]
	s_mov_b32 m0, s78
	s_nop 0
	global_load_lds_dwordx4 v[26:27], off
	v_lshl_add_u64 v[26:27], v[184:185], 0, s[66:67]
	s_add_i32 m0, s78, 0x2000
	s_nop 0
	global_load_lds_dwordx4 v[26:27], off
	v_lshl_add_u64 v[26:27], v[252:253], 0, s[48:49]
	s_mov_b32 m0, s59
	s_nop 0
	global_load_lds_dwordx4 v[26:27], off
	v_lshl_add_u64 v[26:27], v[252:253], 0, s[50:51]
	s_mov_b32 m0, s60
	s_nop 0
	global_load_lds_dwordx4 v[26:27], off
	s_waitcnt vmcnt(8)
	s_waitcnt lgkmcnt(0)
	s_barrier
	s_setprio 1
	s_waitcnt lgkmcnt(0)
	v_mfma_scale_f32_16x16x128_f8f6f4 v[94:97], v[2:9], v[18:25], v[94:97], v189, v189 op_sel_hi:[0,0,0]
	v_mfma_scale_f32_16x16x128_f8f6f4 v[90:93], v[10:17], v[18:25], v[90:93], v189, v189 op_sel_hi:[0,0,0]
	v_mfma_scale_f32_16x16x128_f8f6f4 v[86:89], v[2:9], v[156:163], v[86:89], v189, v189 op_sel_hi:[0,0,0]
	v_mfma_scale_f32_16x16x128_f8f6f4 v[82:85], v[10:17], v[156:163], v[82:85], v189, v189 op_sel_hi:[0,0,0]
	v_mfma_scale_f32_16x16x128_f8f6f4 v[78:81], v[2:9], v[164:171], v[78:81], v189, v189 op_sel_hi:[0,0,0]
	v_mfma_scale_f32_16x16x128_f8f6f4 v[74:77], v[10:17], v[164:171], v[74:77], v189, v189 op_sel_hi:[0,0,0]
	v_mfma_scale_f32_16x16x128_f8f6f4 v[70:73], v[2:9], v[172:179], v[212:215], v189, v189 op_sel_hi:[0,0,0]
	v_mfma_scale_f32_16x16x128_f8f6f4 v[66:69], v[10:17], v[172:179], v[216:219], v189, v189 op_sel_hi:[0,0,0]
	s_setprio 0
	s_setprio 1
	v_mfma_scale_f32_16x16x128_f8f6f4 v[30:33], v[140:147], v[18:25], v[220:223], v189, v189 op_sel_hi:[0,0,0]
	v_mfma_scale_f32_16x16x128_f8f6f4 v[26:29], v[148:155], v[18:25], v[224:227], v189, v189 op_sel_hi:[0,0,0]
	v_mfma_scale_f32_16x16x128_f8f6f4 v[22:25], v[140:147], v[156:163], v[228:231], v189, v189 op_sel_hi:[0,0,0]
	v_mfma_scale_f32_16x16x128_f8f6f4 v[18:21], v[148:155], v[156:163], v[232:235], v189, v189 op_sel_hi:[0,0,0]
	v_mfma_scale_f32_16x16x128_f8f6f4 v[14:17], v[140:147], v[164:171], v[236:239], v189, v189 op_sel_hi:[0,0,0]
	v_mfma_scale_f32_16x16x128_f8f6f4 v[10:13], v[148:155], v[164:171], v[240:243], v189, v189 op_sel_hi:[0,0,0]
	v_mfma_scale_f32_16x16x128_f8f6f4 v[6:9], v[140:147], v[172:179], v[244:247], v189, v189 op_sel_hi:[0,0,0]
	v_mfma_scale_f32_16x16x128_f8f6f4 v[2:5], v[148:155], v[172:179], v[248:251], v189, v189 op_sel_hi:[0,0,0]
	s_setprio 0
	s_add_i32 s88, s88, 2
	s_add_u32 s86, s86, 0x100
	s_addc_u32 s87, s87, 0
	s_add_u32 s0, s0, 0x100
	s_addc_u32 s1, s1, 0
	s_cmp_gt_u32 s88, 19
	s_barrier
	s_cbranch_scc0 .LBB0_275

.Lpeel_348:
	s_waitcnt vmcnt(0)
	ds_read_b128 v[130:133], v202
	ds_read_b128 v[134:137], v202 offset:1024
	ds_read_b128 v[138:141], v202 offset:2048
	ds_read_b128 v[142:145], v202 offset:3072
	ds_read_b128 v[146:149], v203
	ds_read_b128 v[150:153], v203 offset:1024
	ds_read_b128 v[164:167], v203 offset:2048
	ds_read_b128 v[168:171], v203 offset:3072
	s_add_u32 s92, s6, 0xfffc0080
	s_addc_u32 s93, s7, -1
	s_cmp_eq_u32 s87, 12
	s_cselect_b32 vcc_hi, s1, s93
	s_cselect_b32 vcc_lo, s34, s92
	s_cselect_b32 s93, s35, s85
	s_cselect_b32 s92, s83, s84
	v_lshl_add_u64 v[200:201], s[6:7], 0, v[158:159]
	s_add_i32 m0, s58, 0xc000
	ds_read_b128 v[172:175], v204
	ds_read_b128 v[176:179], v204 offset:1024
	ds_read_b128 v[180:183], v204 offset:2048
	ds_read_b128 v[184:187], v204 offset:3072
	ds_read_b128 v[188:191], v204 offset:4096
	ds_read_b128 v[192:195], v204 offset:5120
	ds_read_b128 v[196:199], v204 offset:6144
	ds_read_b128 v[206:209], v204 offset:7168
	global_load_lds_dwordx4 v[200:201], off
	v_lshl_add_u64 v[200:201], v[200:201], 0, s[12:13]
	s_add_i32 m0, s58, 0xe000
	s_nop 0
	global_load_lds_dwordx4 v[200:201], off
	s_waitcnt vmcnt(8)
	s_waitcnt lgkmcnt(0)
	s_barrier
	s_setprio 1
	s_waitcnt lgkmcnt(0)
	v_mfma_f32_16x16x32_bf16 v[126:129], v[130:133], v[172:175], 0
	v_mfma_f32_16x16x32_bf16 v[122:125], v[138:141], v[172:175], 0
	v_mfma_f32_16x16x32_bf16 v[110:113], v[130:133], v[180:183], 0
	v_mfma_f32_16x16x32_bf16 v[106:109], v[138:141], v[180:183], 0
	v_mfma_f32_16x16x32_bf16 v[94:97], v[130:133], v[188:191], 0
	v_mfma_f32_16x16x32_bf16 v[90:93], v[138:141], v[188:191], 0
	v_mfma_f32_16x16x32_bf16 v[78:81], v[130:133], v[196:199], 0
	v_mfma_f32_16x16x32_bf16 v[74:77], v[138:141], v[196:199], 0
	v_mfma_f32_16x16x32_bf16 v[126:129], v[134:137], v[176:179], v[126:129]
	v_mfma_f32_16x16x32_bf16 v[122:125], v[142:145], v[176:179], v[122:125]
	v_mfma_f32_16x16x32_bf16 v[110:113], v[134:137], v[184:187], v[110:113]
	v_mfma_f32_16x16x32_bf16 v[106:109], v[142:145], v[184:187], v[106:109]
	v_mfma_f32_16x16x32_bf16 v[94:97], v[134:137], v[192:195], v[94:97]
	v_mfma_f32_16x16x32_bf16 v[90:93], v[142:145], v[192:195], v[90:93]
	v_mfma_f32_16x16x32_bf16 v[78:81], v[134:137], v[206:209], v[78:81]
	v_mfma_f32_16x16x32_bf16 v[74:77], v[142:145], v[206:209], v[74:77]
	s_setprio 0
	s_setprio 1
	v_mfma_f32_16x16x32_bf16 v[118:121], v[146:149], v[172:175], 0
	v_mfma_f32_16x16x32_bf16 v[114:117], v[164:167], v[172:175], 0
	v_mfma_f32_16x16x32_bf16 v[102:105], v[146:149], v[180:183], 0
	v_mfma_f32_16x16x32_bf16 v[98:101], v[164:167], v[180:183], 0
	v_mfma_f32_16x16x32_bf16 v[86:89], v[146:149], v[188:191], 0
	v_mfma_f32_16x16x32_bf16 v[82:85], v[164:167], v[188:191], 0
	v_mfma_f32_16x16x32_bf16 v[70:73], v[146:149], v[196:199], 0
	v_mfma_f32_16x16x32_bf16 v[66:69], v[164:167], v[196:199], 0
	v_mfma_f32_16x16x32_bf16 v[118:121], v[150:153], v[176:179], v[118:121]
	v_mfma_f32_16x16x32_bf16 v[114:117], v[168:171], v[176:179], v[114:117]
	v_mfma_f32_16x16x32_bf16 v[102:105], v[150:153], v[184:187], v[102:105]
	v_mfma_f32_16x16x32_bf16 v[98:101], v[168:171], v[184:187], v[98:101]
	v_mfma_f32_16x16x32_bf16 v[86:89], v[150:153], v[192:195], v[86:89]
	v_mfma_f32_16x16x32_bf16 v[82:85], v[168:171], v[192:195], v[82:85]
	v_mfma_f32_16x16x32_bf16 v[70:73], v[150:153], v[206:209], v[70:73]
	v_mfma_f32_16x16x32_bf16 v[66:69], v[168:171], v[206:209], v[66:69]
	s_setprio 0
	s_barrier
	v_lshl_add_u64 v[200:201], s[92:93], 0, v[156:157]
	s_add_i32 s92, s88, s33
	s_mov_b32 m0, s92
	ds_read_b128 v[172:175], v204 offset:16384
	ds_read_b128 v[176:179], v204 offset:17408
	ds_read_b128 v[180:183], v204 offset:18432
	ds_read_b128 v[184:187], v204 offset:19456
	ds_read_b128 v[188:191], v204 offset:20480
	ds_read_b128 v[192:195], v204 offset:21504
	ds_read_b128 v[196:199], v204 offset:22528
	ds_read_b128 v[206:209], v204 offset:23552
	global_load_lds_dwordx4 v[200:201], off
	v_lshl_add_u64 v[210:211], v[200:201], 0, s[12:13]
	s_add_i32 m0, s92, 0x2000
	s_add_i32 s92, s89, s33
	global_load_lds_dwordx4 v[210:211], off
	v_lshl_add_u64 v[210:211], v[200:201], 0, s[14:15]
	s_mov_b32 m0, s92
	s_nop 0
	global_load_lds_dwordx4 v[210:211], off
	v_lshl_add_u64 v[210:211], v[200:201], 0, s[44:45]
	s_add_i32 m0, s92, 0x2000
	s_nop 0
	global_load_lds_dwordx4 v[210:211], off
	v_lshl_add_u64 v[210:211], vcc, 0, v[154:155]
	s_mov_b32 m0, s58
	v_lshl_add_u64 v[212:213], v[210:211], 0, s[12:13]
	global_load_lds_dwordx4 v[210:211], off
	s_mov_b32 m0, s59
	s_nop 0
	global_load_lds_dwordx4 v[212:213], off
	s_waitcnt vmcnt(8)
	s_waitcnt lgkmcnt(0)
	s_barrier
	s_setprio 1
	s_waitcnt lgkmcnt(0)
	v_mfma_f32_16x16x32_bf16 v[62:65], v[130:133], v[172:175], 0
	v_mfma_f32_16x16x32_bf16 v[58:61], v[138:141], v[172:175], 0
	v_mfma_f32_16x16x32_bf16 v[46:49], v[130:133], v[180:183], 0
	v_mfma_f32_16x16x32_bf16 v[42:45], v[138:141], v[180:183], 0
	v_mfma_f32_16x16x32_bf16 v[30:33], v[130:133], v[188:191], 0
	v_mfma_f32_16x16x32_bf16 v[26:29], v[138:141], v[188:191], 0
	v_mfma_f32_16x16x32_bf16 v[14:17], v[130:133], v[196:199], 0
	v_mfma_f32_16x16x32_bf16 v[10:13], v[138:141], v[196:199], 0
	v_mfma_f32_16x16x32_bf16 v[62:65], v[134:137], v[176:179], v[62:65]
	v_mfma_f32_16x16x32_bf16 v[58:61], v[142:145], v[176:179], v[58:61]
	v_mfma_f32_16x16x32_bf16 v[46:49], v[134:137], v[184:187], v[46:49]
	v_mfma_f32_16x16x32_bf16 v[42:45], v[142:145], v[184:187], v[42:45]
	v_mfma_f32_16x16x32_bf16 v[30:33], v[134:137], v[192:195], v[30:33]
	v_mfma_f32_16x16x32_bf16 v[26:29], v[142:145], v[192:195], v[26:29]
	v_mfma_f32_16x16x32_bf16 v[14:17], v[134:137], v[206:209], v[14:17]
	v_mfma_f32_16x16x32_bf16 v[10:13], v[142:145], v[206:209], v[10:13]
	s_setprio 0
	s_setprio 1
	v_mfma_f32_16x16x32_bf16 v[54:57], v[146:149], v[172:175], 0
	v_mfma_f32_16x16x32_bf16 v[50:53], v[164:167], v[172:175], 0
	v_mfma_f32_16x16x32_bf16 v[38:41], v[146:149], v[180:183], 0
	v_mfma_f32_16x16x32_bf16 v[34:37], v[164:167], v[180:183], 0
	v_mfma_f32_16x16x32_bf16 v[22:25], v[146:149], v[188:191], 0
	v_mfma_f32_16x16x32_bf16 v[18:21], v[164:167], v[188:191], 0
	v_mfma_f32_16x16x32_bf16 v[6:9], v[146:149], v[196:199], 0
	v_mfma_f32_16x16x32_bf16 v[2:5], v[164:167], v[196:199], 0
	v_mfma_f32_16x16x32_bf16 v[54:57], v[150:153], v[176:179], v[54:57]
	v_mfma_f32_16x16x32_bf16 v[50:53], v[168:171], v[176:179], v[50:53]
	v_mfma_f32_16x16x32_bf16 v[38:41], v[150:153], v[184:187], v[38:41]
	v_mfma_f32_16x16x32_bf16 v[34:37], v[168:171], v[184:187], v[34:37]
	v_mfma_f32_16x16x32_bf16 v[22:25], v[150:153], v[192:195], v[22:25]
	v_mfma_f32_16x16x32_bf16 v[18:21], v[168:171], v[192:195], v[18:21]
	v_mfma_f32_16x16x32_bf16 v[6:9], v[150:153], v[206:209], v[6:9]
	v_mfma_f32_16x16x32_bf16 v[2:5], v[168:171], v[206:209], v[2:5]
	s_setprio 0
	s_barrier
	s_add_i32 s92, 0, 0x18000
	s_add_i32 s93, 0, 0x1c000
	v_add_u32_e32 v142, s92, v1
	v_add_u32_e32 v168, s93, v1
	ds_read_b128 v[130:133], v142
	ds_read_b128 v[134:137], v142 offset:1024
	ds_read_b128 v[138:141], v142 offset:2048
	ds_read_b128 v[142:145], v142 offset:3072
	ds_read_b128 v[146:149], v168
	ds_read_b128 v[150:153], v168 offset:1024
	ds_read_b128 v[164:167], v168 offset:2048
	ds_read_b128 v[168:171], v168 offset:3072
	s_mov_b32 m0, s60
	v_lshl_add_u64 v[212:213], v[210:211], 0, s[14:15]
	ds_read_b128 v[172:175], v204 offset:32768
	ds_read_b128 v[176:179], v204 offset:33792
	ds_read_b128 v[180:183], v204 offset:34816
	ds_read_b128 v[184:187], v204 offset:35840
	ds_read_b128 v[188:191], v204 offset:36864
	ds_read_b128 v[192:195], v204 offset:37888
	ds_read_b128 v[196:199], v204 offset:38912
	ds_read_b128 v[206:209], v204 offset:39936
	global_load_lds_dwordx4 v[212:213], off
	v_lshl_add_u64 v[212:213], v[210:211], 0, s[44:45]
	s_mov_b32 m0, s61
	s_nop 0
	global_load_lds_dwordx4 v[212:213], off
	s_waitcnt vmcnt(8)
	s_waitcnt lgkmcnt(0)
	s_barrier
	s_setprio 1
	s_waitcnt lgkmcnt(0)
	v_mfma_f32_16x16x32_bf16 v[126:129], v[130:133], v[172:175], v[126:129]
	v_mfma_f32_16x16x32_bf16 v[122:125], v[138:141], v[172:175], v[122:125]
	v_mfma_f32_16x16x32_bf16 v[110:113], v[130:133], v[180:183], v[110:113]
	v_mfma_f32_16x16x32_bf16 v[106:109], v[138:141], v[180:183], v[106:109]
	v_mfma_f32_16x16x32_bf16 v[94:97], v[130:133], v[188:191], v[94:97]
	v_mfma_f32_16x16x32_bf16 v[90:93], v[138:141], v[188:191], v[90:93]
	v_mfma_f32_16x16x32_bf16 v[78:81], v[130:133], v[196:199], v[78:81]
	v_mfma_f32_16x16x32_bf16 v[74:77], v[138:141], v[196:199], v[74:77]
	v_mfma_f32_16x16x32_bf16 v[126:129], v[134:137], v[176:179], v[126:129]
	v_mfma_f32_16x16x32_bf16 v[122:125], v[142:145], v[176:179], v[122:125]
	v_mfma_f32_16x16x32_bf16 v[110:113], v[134:137], v[184:187], v[110:113]
	v_mfma_f32_16x16x32_bf16 v[106:109], v[142:145], v[184:187], v[106:109]
	v_mfma_f32_16x16x32_bf16 v[94:97], v[134:137], v[192:195], v[94:97]
	v_mfma_f32_16x16x32_bf16 v[90:93], v[142:145], v[192:195], v[90:93]
	v_mfma_f32_16x16x32_bf16 v[78:81], v[134:137], v[206:209], v[78:81]
	v_mfma_f32_16x16x32_bf16 v[74:77], v[142:145], v[206:209], v[74:77]
	s_setprio 0
	s_setprio 1
	v_mfma_f32_16x16x32_bf16 v[118:121], v[146:149], v[172:175], v[118:121]
	v_mfma_f32_16x16x32_bf16 v[114:117], v[164:167], v[172:175], v[114:117]
	v_mfma_f32_16x16x32_bf16 v[102:105], v[146:149], v[180:183], v[102:105]
	v_mfma_f32_16x16x32_bf16 v[98:101], v[164:167], v[180:183], v[98:101]
	v_mfma_f32_16x16x32_bf16 v[86:89], v[146:149], v[188:191], v[86:89]
	v_mfma_f32_16x16x32_bf16 v[82:85], v[164:167], v[188:191], v[82:85]
	v_mfma_f32_16x16x32_bf16 v[70:73], v[146:149], v[196:199], v[70:73]
	v_mfma_f32_16x16x32_bf16 v[66:69], v[164:167], v[196:199], v[66:69]
	v_mfma_f32_16x16x32_bf16 v[118:121], v[150:153], v[176:179], v[118:121]
	v_mfma_f32_16x16x32_bf16 v[114:117], v[168:171], v[176:179], v[114:117]
	v_mfma_f32_16x16x32_bf16 v[102:105], v[150:153], v[184:187], v[102:105]
	v_mfma_f32_16x16x32_bf16 v[98:101], v[168:171], v[184:187], v[98:101]
	v_mfma_f32_16x16x32_bf16 v[86:89], v[150:153], v[192:195], v[86:89]
	v_mfma_f32_16x16x32_bf16 v[82:85], v[168:171], v[192:195], v[82:85]
	v_mfma_f32_16x16x32_bf16 v[70:73], v[150:153], v[206:209], v[70:73]
	v_mfma_f32_16x16x32_bf16 v[66:69], v[168:171], v[206:209], v[66:69]
	s_setprio 0
	s_barrier
	s_add_i32 s92, s92, s33
	v_lshl_add_u64 v[212:213], v[200:201], 0, s[50:51]
	s_mov_b32 m0, s92
	ds_read_b128 v[172:175], v204 offset:49152
	ds_read_b128 v[176:179], v204 offset:50176
	ds_read_b128 v[180:183], v204 offset:51200
	ds_read_b128 v[184:187], v204 offset:52224
	ds_read_b128 v[188:191], v204 offset:53248
	ds_read_b128 v[192:195], v204 offset:54272
	ds_read_b128 v[196:199], v204 offset:55296
	ds_read_b128 v[206:209], v204 offset:56320
	global_load_lds_dwordx4 v[212:213], off
	v_lshl_add_u64 v[212:213], v[200:201], 0, s[52:53]
	s_add_i32 m0, s92, 0x2000
	s_add_i32 s92, s93, s33
	global_load_lds_dwordx4 v[212:213], off
	v_lshl_add_u64 v[212:213], v[200:201], 0, s[66:67]
	s_mov_b32 m0, s92
	v_lshl_add_u64 v[200:201], v[200:201], 0, s[68:69]
	global_load_lds_dwordx4 v[212:213], off
	s_add_i32 m0, s92, 0x2000
	s_nop 0
	global_load_lds_dwordx4 v[200:201], off
	v_lshl_add_u64 v[200:201], v[210:211], 0, s[50:51]
	s_mov_b32 m0, s79
	s_nop 0
	global_load_lds_dwordx4 v[200:201], off
	v_lshl_add_u64 v[200:201], v[210:211], 0, s[52:53]
	s_mov_b32 m0, s81
	s_nop 0
	global_load_lds_dwordx4 v[200:201], off
	s_waitcnt vmcnt(8)
	s_waitcnt lgkmcnt(0)
	s_barrier
	s_setprio 1
	s_waitcnt lgkmcnt(0)
	v_mfma_f32_16x16x32_bf16 v[62:65], v[130:133], v[172:175], v[62:65]
	v_mfma_f32_16x16x32_bf16 v[58:61], v[138:141], v[172:175], v[58:61]
	v_mfma_f32_16x16x32_bf16 v[46:49], v[130:133], v[180:183], v[46:49]
	v_mfma_f32_16x16x32_bf16 v[42:45], v[138:141], v[180:183], v[42:45]
	v_mfma_f32_16x16x32_bf16 v[30:33], v[130:133], v[188:191], v[30:33]
	v_mfma_f32_16x16x32_bf16 v[26:29], v[138:141], v[188:191], v[26:29]
	v_mfma_f32_16x16x32_bf16 v[14:17], v[130:133], v[196:199], v[14:17]
	v_mfma_f32_16x16x32_bf16 v[10:13], v[138:141], v[196:199], v[10:13]
	v_mfma_f32_16x16x32_bf16 v[62:65], v[134:137], v[176:179], v[62:65]
	v_mfma_f32_16x16x32_bf16 v[58:61], v[142:145], v[176:179], v[58:61]
	v_mfma_f32_16x16x32_bf16 v[46:49], v[134:137], v[184:187], v[46:49]
	v_mfma_f32_16x16x32_bf16 v[42:45], v[142:145], v[184:187], v[42:45]
	v_mfma_f32_16x16x32_bf16 v[30:33], v[134:137], v[192:195], v[30:33]
	v_mfma_f32_16x16x32_bf16 v[26:29], v[142:145], v[192:195], v[26:29]
	v_mfma_f32_16x16x32_bf16 v[14:17], v[134:137], v[206:209], v[14:17]
	v_mfma_f32_16x16x32_bf16 v[10:13], v[142:145], v[206:209], v[10:13]
	s_setprio 0
	s_setprio 1
	v_mfma_f32_16x16x32_bf16 v[54:57], v[146:149], v[172:175], v[54:57]
	v_mfma_f32_16x16x32_bf16 v[50:53], v[164:167], v[172:175], v[50:53]
	v_mfma_f32_16x16x32_bf16 v[38:41], v[146:149], v[180:183], v[38:41]
	v_mfma_f32_16x16x32_bf16 v[34:37], v[164:167], v[180:183], v[34:37]
	v_mfma_f32_16x16x32_bf16 v[22:25], v[146:149], v[188:191], v[22:25]
	v_mfma_f32_16x16x32_bf16 v[18:21], v[164:167], v[188:191], v[18:21]
	v_mfma_f32_16x16x32_bf16 v[6:9], v[146:149], v[196:199], v[6:9]
	v_mfma_f32_16x16x32_bf16 v[2:5], v[164:167], v[196:199], v[2:5]
	v_mfma_f32_16x16x32_bf16 v[54:57], v[150:153], v[176:179], v[54:57]
	v_mfma_f32_16x16x32_bf16 v[50:53], v[168:171], v[176:179], v[50:53]
	v_mfma_f32_16x16x32_bf16 v[38:41], v[150:153], v[184:187], v[38:41]
	v_mfma_f32_16x16x32_bf16 v[34:37], v[168:171], v[184:187], v[34:37]
	v_mfma_f32_16x16x32_bf16 v[22:25], v[150:153], v[192:195], v[22:25]
	v_mfma_f32_16x16x32_bf16 v[18:21], v[168:171], v[192:195], v[18:21]
	v_mfma_f32_16x16x32_bf16 v[6:9], v[150:153], v[206:209], v[6:9]
	v_mfma_f32_16x16x32_bf16 v[2:5], v[168:171], v[206:209], v[2:5]
	s_setprio 0
	s_add_i32 s87, s87, 2
	s_add_u32 s6, s6, 0x100
	s_addc_u32 s7, s7, 0
	s_add_u32 s84, s84, 0x100
	s_addc_u32 s85, s85, 0
	s_cmp_gt_u32 s87, 13
	s_barrier
	s_cbranch_scc1 .Lpeel_exit_348
.LBB0_348:
	s_waitcnt vmcnt(0)
	ds_read_b128 v[130:133], v202
	ds_read_b128 v[134:137], v202 offset:1024
	ds_read_b128 v[138:141], v202 offset:2048
	ds_read_b128 v[142:145], v202 offset:3072
	ds_read_b128 v[146:149], v203
	ds_read_b128 v[150:153], v203 offset:1024
	ds_read_b128 v[164:167], v203 offset:2048
	ds_read_b128 v[168:171], v203 offset:3072
	s_add_u32 s92, s6, 0xfffc0080
	s_addc_u32 s93, s7, -1
	s_cmp_eq_u32 s87, 12
	s_cselect_b32 vcc_hi, s1, s93
	s_cselect_b32 vcc_lo, s34, s92
	s_cselect_b32 s93, s35, s85
	s_cselect_b32 s92, s83, s84
	v_lshl_add_u64 v[200:201], s[6:7], 0, v[158:159]
	s_add_i32 m0, s58, 0xc000
	ds_read_b128 v[172:175], v204
	ds_read_b128 v[176:179], v204 offset:1024
	ds_read_b128 v[180:183], v204 offset:2048
	ds_read_b128 v[184:187], v204 offset:3072
	ds_read_b128 v[188:191], v204 offset:4096
	ds_read_b128 v[192:195], v204 offset:5120
	ds_read_b128 v[196:199], v204 offset:6144
	ds_read_b128 v[206:209], v204 offset:7168
	global_load_lds_dwordx4 v[200:201], off
	v_lshl_add_u64 v[200:201], v[200:201], 0, s[12:13]
	s_add_i32 m0, s58, 0xe000
	s_nop 0
	global_load_lds_dwordx4 v[200:201], off
	s_waitcnt vmcnt(8)
	s_waitcnt lgkmcnt(0)
	s_barrier
	s_setprio 1
	s_waitcnt lgkmcnt(0)
	v_mfma_f32_16x16x32_bf16 v[126:129], v[130:133], v[172:175], v[126:129]
	v_mfma_f32_16x16x32_bf16 v[122:125], v[138:141], v[172:175], v[122:125]
	v_mfma_f32_16x16x32_bf16 v[110:113], v[130:133], v[180:183], v[110:113]
	v_mfma_f32_16x16x32_bf16 v[106:109], v[138:141], v[180:183], v[106:109]
	v_mfma_f32_16x16x32_bf16 v[94:97], v[130:133], v[188:191], v[94:97]
	v_mfma_f32_16x16x32_bf16 v[90:93], v[138:141], v[188:191], v[90:93]
	v_mfma_f32_16x16x32_bf16 v[78:81], v[130:133], v[196:199], v[78:81]
	v_mfma_f32_16x16x32_bf16 v[74:77], v[138:141], v[196:199], v[74:77]
	v_mfma_f32_16x16x32_bf16 v[126:129], v[134:137], v[176:179], v[126:129]
	v_mfma_f32_16x16x32_bf16 v[122:125], v[142:145], v[176:179], v[122:125]
	v_mfma_f32_16x16x32_bf16 v[110:113], v[134:137], v[184:187], v[110:113]
	v_mfma_f32_16x16x32_bf16 v[106:109], v[142:145], v[184:187], v[106:109]
	v_mfma_f32_16x16x32_bf16 v[94:97], v[134:137], v[192:195], v[94:97]
	v_mfma_f32_16x16x32_bf16 v[90:93], v[142:145], v[192:195], v[90:93]
	v_mfma_f32_16x16x32_bf16 v[78:81], v[134:137], v[206:209], v[78:81]
	v_mfma_f32_16x16x32_bf16 v[74:77], v[142:145], v[206:209], v[74:77]
	s_setprio 0
	s_setprio 1
	v_mfma_f32_16x16x32_bf16 v[118:121], v[146:149], v[172:175], v[118:121]
	v_mfma_f32_16x16x32_bf16 v[114:117], v[164:167], v[172:175], v[114:117]
	v_mfma_f32_16x16x32_bf16 v[102:105], v[146:149], v[180:183], v[102:105]
	v_mfma_f32_16x16x32_bf16 v[98:101], v[164:167], v[180:183], v[98:101]
	v_mfma_f32_16x16x32_bf16 v[86:89], v[146:149], v[188:191], v[86:89]
	v_mfma_f32_16x16x32_bf16 v[82:85], v[164:167], v[188:191], v[82:85]
	v_mfma_f32_16x16x32_bf16 v[70:73], v[146:149], v[196:199], v[70:73]
	v_mfma_f32_16x16x32_bf16 v[66:69], v[164:167], v[196:199], v[66:69]
	v_mfma_f32_16x16x32_bf16 v[118:121], v[150:153], v[176:179], v[118:121]
	v_mfma_f32_16x16x32_bf16 v[114:117], v[168:171], v[176:179], v[114:117]
	v_mfma_f32_16x16x32_bf16 v[102:105], v[150:153], v[184:187], v[102:105]
	v_mfma_f32_16x16x32_bf16 v[98:101], v[168:171], v[184:187], v[98:101]
	v_mfma_f32_16x16x32_bf16 v[86:89], v[150:153], v[192:195], v[86:89]
	v_mfma_f32_16x16x32_bf16 v[82:85], v[168:171], v[192:195], v[82:85]
	v_mfma_f32_16x16x32_bf16 v[70:73], v[150:153], v[206:209], v[70:73]
	v_mfma_f32_16x16x32_bf16 v[66:69], v[168:171], v[206:209], v[66:69]
	s_setprio 0
	s_barrier
	v_lshl_add_u64 v[200:201], s[92:93], 0, v[156:157]
	s_add_i32 s92, s88, s33
	s_mov_b32 m0, s92
	ds_read_b128 v[172:175], v204 offset:16384
	ds_read_b128 v[176:179], v204 offset:17408
	ds_read_b128 v[180:183], v204 offset:18432
	ds_read_b128 v[184:187], v204 offset:19456
	ds_read_b128 v[188:191], v204 offset:20480
	ds_read_b128 v[192:195], v204 offset:21504
	ds_read_b128 v[196:199], v204 offset:22528
	ds_read_b128 v[206:209], v204 offset:23552
	global_load_lds_dwordx4 v[200:201], off
	v_lshl_add_u64 v[210:211], v[200:201], 0, s[12:13]
	s_add_i32 m0, s92, 0x2000
	s_add_i32 s92, s89, s33
	global_load_lds_dwordx4 v[210:211], off
	v_lshl_add_u64 v[210:211], v[200:201], 0, s[14:15]
	s_mov_b32 m0, s92
	s_nop 0
	global_load_lds_dwordx4 v[210:211], off
	v_lshl_add_u64 v[210:211], v[200:201], 0, s[44:45]
	s_add_i32 m0, s92, 0x2000
	s_nop 0
	global_load_lds_dwordx4 v[210:211], off
	v_lshl_add_u64 v[210:211], vcc, 0, v[154:155]
	s_mov_b32 m0, s58
	v_lshl_add_u64 v[212:213], v[210:211], 0, s[12:13]
	global_load_lds_dwordx4 v[210:211], off
	s_mov_b32 m0, s59
	s_nop 0
	global_load_lds_dwordx4 v[212:213], off
	s_waitcnt vmcnt(8)
	s_waitcnt lgkmcnt(0)
	s_barrier
	s_setprio 1
	s_waitcnt lgkmcnt(0)
	v_mfma_f32_16x16x32_bf16 v[62:65], v[130:133], v[172:175], v[62:65]
	v_mfma_f32_16x16x32_bf16 v[58:61], v[138:141], v[172:175], v[58:61]
	v_mfma_f32_16x16x32_bf16 v[46:49], v[130:133], v[180:183], v[46:49]
	v_mfma_f32_16x16x32_bf16 v[42:45], v[138:141], v[180:183], v[42:45]
	v_mfma_f32_16x16x32_bf16 v[30:33], v[130:133], v[188:191], v[30:33]
	v_mfma_f32_16x16x32_bf16 v[26:29], v[138:141], v[188:191], v[26:29]
	v_mfma_f32_16x16x32_bf16 v[14:17], v[130:133], v[196:199], v[14:17]
	v_mfma_f32_16x16x32_bf16 v[10:13], v[138:141], v[196:199], v[10:13]
	v_mfma_f32_16x16x32_bf16 v[62:65], v[134:137], v[176:179], v[62:65]
	v_mfma_f32_16x16x32_bf16 v[58:61], v[142:145], v[176:179], v[58:61]
	v_mfma_f32_16x16x32_bf16 v[46:49], v[134:137], v[184:187], v[46:49]
	v_mfma_f32_16x16x32_bf16 v[42:45], v[142:145], v[184:187], v[42:45]
	v_mfma_f32_16x16x32_bf16 v[30:33], v[134:137], v[192:195], v[30:33]
	v_mfma_f32_16x16x32_bf16 v[26:29], v[142:145], v[192:195], v[26:29]
	v_mfma_f32_16x16x32_bf16 v[14:17], v[134:137], v[206:209], v[14:17]
	v_mfma_f32_16x16x32_bf16 v[10:13], v[142:145], v[206:209], v[10:13]
	s_setprio 0
	s_setprio 1
	v_mfma_f32_16x16x32_bf16 v[54:57], v[146:149], v[172:175], v[54:57]
	v_mfma_f32_16x16x32_bf16 v[50:53], v[164:167], v[172:175], v[50:53]
	v_mfma_f32_16x16x32_bf16 v[38:41], v[146:149], v[180:183], v[38:41]
	v_mfma_f32_16x16x32_bf16 v[34:37], v[164:167], v[180:183], v[34:37]
	v_mfma_f32_16x16x32_bf16 v[22:25], v[146:149], v[188:191], v[22:25]
	v_mfma_f32_16x16x32_bf16 v[18:21], v[164:167], v[188:191], v[18:21]
	v_mfma_f32_16x16x32_bf16 v[6:9], v[146:149], v[196:199], v[6:9]
	v_mfma_f32_16x16x32_bf16 v[2:5], v[164:167], v[196:199], v[2:5]
	v_mfma_f32_16x16x32_bf16 v[54:57], v[150:153], v[176:179], v[54:57]
	v_mfma_f32_16x16x32_bf16 v[50:53], v[168:171], v[176:179], v[50:53]
	v_mfma_f32_16x16x32_bf16 v[38:41], v[150:153], v[184:187], v[38:41]
	v_mfma_f32_16x16x32_bf16 v[34:37], v[168:171], v[184:187], v[34:37]
	v_mfma_f32_16x16x32_bf16 v[22:25], v[150:153], v[192:195], v[22:25]
	v_mfma_f32_16x16x32_bf16 v[18:21], v[168:171], v[192:195], v[18:21]
	v_mfma_f32_16x16x32_bf16 v[6:9], v[150:153], v[206:209], v[6:9]
	v_mfma_f32_16x16x32_bf16 v[2:5], v[168:171], v[206:209], v[2:5]
	s_setprio 0
	s_barrier
	s_add_i32 s92, 0, 0x18000
	s_add_i32 s93, 0, 0x1c000
	v_add_u32_e32 v142, s92, v1
	v_add_u32_e32 v168, s93, v1
	ds_read_b128 v[130:133], v142
	ds_read_b128 v[134:137], v142 offset:1024
	ds_read_b128 v[138:141], v142 offset:2048
	ds_read_b128 v[142:145], v142 offset:3072
	ds_read_b128 v[146:149], v168
	ds_read_b128 v[150:153], v168 offset:1024
	ds_read_b128 v[164:167], v168 offset:2048
	ds_read_b128 v[168:171], v168 offset:3072
	s_mov_b32 m0, s60
	v_lshl_add_u64 v[212:213], v[210:211], 0, s[14:15]
	ds_read_b128 v[172:175], v204 offset:32768
	ds_read_b128 v[176:179], v204 offset:33792
	ds_read_b128 v[180:183], v204 offset:34816
	ds_read_b128 v[184:187], v204 offset:35840
	ds_read_b128 v[188:191], v204 offset:36864
	ds_read_b128 v[192:195], v204 offset:37888
	ds_read_b128 v[196:199], v204 offset:38912
	ds_read_b128 v[206:209], v204 offset:39936
	global_load_lds_dwordx4 v[212:213], off
	v_lshl_add_u64 v[212:213], v[210:211], 0, s[44:45]
	s_mov_b32 m0, s61
	s_nop 0
	global_load_lds_dwordx4 v[212:213], off
	s_waitcnt vmcnt(8)
	s_waitcnt lgkmcnt(0)
	s_barrier
	s_setprio 1
	s_waitcnt lgkmcnt(0)
	v_mfma_f32_16x16x32_bf16 v[126:129], v[130:133], v[172:175], v[126:129]
	v_mfma_f32_16x16x32_bf16 v[122:125], v[138:141], v[172:175], v[122:125]
	v_mfma_f32_16x16x32_bf16 v[110:113], v[130:133], v[180:183], v[110:113]
	v_mfma_f32_16x16x32_bf16 v[106:109], v[138:141], v[180:183], v[106:109]
	v_mfma_f32_16x16x32_bf16 v[94:97], v[130:133], v[188:191], v[94:97]
	v_mfma_f32_16x16x32_bf16 v[90:93], v[138:141], v[188:191], v[90:93]
	v_mfma_f32_16x16x32_bf16 v[78:81], v[130:133], v[196:199], v[78:81]
	v_mfma_f32_16x16x32_bf16 v[74:77], v[138:141], v[196:199], v[74:77]
	v_mfma_f32_16x16x32_bf16 v[126:129], v[134:137], v[176:179], v[126:129]
	v_mfma_f32_16x16x32_bf16 v[122:125], v[142:145], v[176:179], v[122:125]
	v_mfma_f32_16x16x32_bf16 v[110:113], v[134:137], v[184:187], v[110:113]
	v_mfma_f32_16x16x32_bf16 v[106:109], v[142:145], v[184:187], v[106:109]
	v_mfma_f32_16x16x32_bf16 v[94:97], v[134:137], v[192:195], v[94:97]
	v_mfma_f32_16x16x32_bf16 v[90:93], v[142:145], v[192:195], v[90:93]
	v_mfma_f32_16x16x32_bf16 v[78:81], v[134:137], v[206:209], v[78:81]
	v_mfma_f32_16x16x32_bf16 v[74:77], v[142:145], v[206:209], v[74:77]
	s_setprio 0
	s_setprio 1
	v_mfma_f32_16x16x32_bf16 v[118:121], v[146:149], v[172:175], v[118:121]
	v_mfma_f32_16x16x32_bf16 v[114:117], v[164:167], v[172:175], v[114:117]
	v_mfma_f32_16x16x32_bf16 v[102:105], v[146:149], v[180:183], v[102:105]
	v_mfma_f32_16x16x32_bf16 v[98:101], v[164:167], v[180:183], v[98:101]
	v_mfma_f32_16x16x32_bf16 v[86:89], v[146:149], v[188:191], v[86:89]
	v_mfma_f32_16x16x32_bf16 v[82:85], v[164:167], v[188:191], v[82:85]
	v_mfma_f32_16x16x32_bf16 v[70:73], v[146:149], v[196:199], v[70:73]
	v_mfma_f32_16x16x32_bf16 v[66:69], v[164:167], v[196:199], v[66:69]
	v_mfma_f32_16x16x32_bf16 v[118:121], v[150:153], v[176:179], v[118:121]
	v_mfma_f32_16x16x32_bf16 v[114:117], v[168:171], v[176:179], v[114:117]
	v_mfma_f32_16x16x32_bf16 v[102:105], v[150:153], v[184:187], v[102:105]
	v_mfma_f32_16x16x32_bf16 v[98:101], v[168:171], v[184:187], v[98:101]
	v_mfma_f32_16x16x32_bf16 v[86:89], v[150:153], v[192:195], v[86:89]
	v_mfma_f32_16x16x32_bf16 v[82:85], v[168:171], v[192:195], v[82:85]
	v_mfma_f32_16x16x32_bf16 v[70:73], v[150:153], v[206:209], v[70:73]
	v_mfma_f32_16x16x32_bf16 v[66:69], v[168:171], v[206:209], v[66:69]
	s_setprio 0
	s_barrier
	s_add_i32 s92, s92, s33
	v_lshl_add_u64 v[212:213], v[200:201], 0, s[50:51]
	s_mov_b32 m0, s92
	ds_read_b128 v[172:175], v204 offset:49152
	ds_read_b128 v[176:179], v204 offset:50176
	ds_read_b128 v[180:183], v204 offset:51200
	ds_read_b128 v[184:187], v204 offset:52224
	ds_read_b128 v[188:191], v204 offset:53248
	ds_read_b128 v[192:195], v204 offset:54272
	ds_read_b128 v[196:199], v204 offset:55296
	ds_read_b128 v[206:209], v204 offset:56320
	global_load_lds_dwordx4 v[212:213], off
	v_lshl_add_u64 v[212:213], v[200:201], 0, s[52:53]
	s_add_i32 m0, s92, 0x2000
	s_add_i32 s92, s93, s33
	global_load_lds_dwordx4 v[212:213], off
	v_lshl_add_u64 v[212:213], v[200:201], 0, s[66:67]
	s_mov_b32 m0, s92
	v_lshl_add_u64 v[200:201], v[200:201], 0, s[68:69]
	global_load_lds_dwordx4 v[212:213], off
	s_add_i32 m0, s92, 0x2000
	s_nop 0
	global_load_lds_dwordx4 v[200:201], off
	v_lshl_add_u64 v[200:201], v[210:211], 0, s[50:51]
	s_mov_b32 m0, s79
	s_nop 0
	global_load_lds_dwordx4 v[200:201], off
	v_lshl_add_u64 v[200:201], v[210:211], 0, s[52:53]
	s_mov_b32 m0, s81
	s_nop 0
	global_load_lds_dwordx4 v[200:201], off
	s_waitcnt vmcnt(8)
	s_waitcnt lgkmcnt(0)
	s_barrier
	s_setprio 1
	s_waitcnt lgkmcnt(0)
	v_mfma_f32_16x16x32_bf16 v[62:65], v[130:133], v[172:175], v[62:65]
	v_mfma_f32_16x16x32_bf16 v[58:61], v[138:141], v[172:175], v[58:61]
	v_mfma_f32_16x16x32_bf16 v[46:49], v[130:133], v[180:183], v[46:49]
	v_mfma_f32_16x16x32_bf16 v[42:45], v[138:141], v[180:183], v[42:45]
	v_mfma_f32_16x16x32_bf16 v[30:33], v[130:133], v[188:191], v[30:33]
	v_mfma_f32_16x16x32_bf16 v[26:29], v[138:141], v[188:191], v[26:29]
	v_mfma_f32_16x16x32_bf16 v[14:17], v[130:133], v[196:199], v[14:17]
	v_mfma_f32_16x16x32_bf16 v[10:13], v[138:141], v[196:199], v[10:13]
	v_mfma_f32_16x16x32_bf16 v[62:65], v[134:137], v[176:179], v[62:65]
	v_mfma_f32_16x16x32_bf16 v[58:61], v[142:145], v[176:179], v[58:61]
	v_mfma_f32_16x16x32_bf16 v[46:49], v[134:137], v[184:187], v[46:49]
	v_mfma_f32_16x16x32_bf16 v[42:45], v[142:145], v[184:187], v[42:45]
	v_mfma_f32_16x16x32_bf16 v[30:33], v[134:137], v[192:195], v[30:33]
	v_mfma_f32_16x16x32_bf16 v[26:29], v[142:145], v[192:195], v[26:29]
	v_mfma_f32_16x16x32_bf16 v[14:17], v[134:137], v[206:209], v[14:17]
	v_mfma_f32_16x16x32_bf16 v[10:13], v[142:145], v[206:209], v[10:13]
	s_setprio 0
	s_setprio 1
	v_mfma_f32_16x16x32_bf16 v[54:57], v[146:149], v[172:175], v[54:57]
	v_mfma_f32_16x16x32_bf16 v[50:53], v[164:167], v[172:175], v[50:53]
	v_mfma_f32_16x16x32_bf16 v[38:41], v[146:149], v[180:183], v[38:41]
	v_mfma_f32_16x16x32_bf16 v[34:37], v[164:167], v[180:183], v[34:37]
	v_mfma_f32_16x16x32_bf16 v[22:25], v[146:149], v[188:191], v[22:25]
	v_mfma_f32_16x16x32_bf16 v[18:21], v[164:167], v[188:191], v[18:21]
	v_mfma_f32_16x16x32_bf16 v[6:9], v[146:149], v[196:199], v[6:9]
	v_mfma_f32_16x16x32_bf16 v[2:5], v[164:167], v[196:199], v[2:5]
	v_mfma_f32_16x16x32_bf16 v[54:57], v[150:153], v[176:179], v[54:57]
	v_mfma_f32_16x16x32_bf16 v[50:53], v[168:171], v[176:179], v[50:53]
	v_mfma_f32_16x16x32_bf16 v[38:41], v[150:153], v[184:187], v[38:41]
	v_mfma_f32_16x16x32_bf16 v[34:37], v[168:171], v[184:187], v[34:37]
	v_mfma_f32_16x16x32_bf16 v[22:25], v[150:153], v[192:195], v[22:25]
	v_mfma_f32_16x16x32_bf16 v[18:21], v[168:171], v[192:195], v[18:21]
	v_mfma_f32_16x16x32_bf16 v[6:9], v[150:153], v[206:209], v[6:9]
	v_mfma_f32_16x16x32_bf16 v[2:5], v[168:171], v[206:209], v[2:5]
	s_setprio 0
	s_add_i32 s87, s87, 2
	s_add_u32 s6, s6, 0x100
	s_addc_u32 s7, s7, 0
	s_add_u32 s84, s84, 0x100
	s_addc_u32 s85, s85, 0
	s_cmp_gt_u32 s87, 13
	s_barrier
	s_cbranch_scc0 .LBB0_348

.Lpeel_568:
	ds_read_b128 v[130:133], v236
	ds_read_b128 v[134:137], v236 offset:1024
	ds_read_b128 v[138:141], v236 offset:2048
	ds_read_b128 v[142:145], v236 offset:3072
	ds_read_b128 v[146:149], v237
	ds_read_b128 v[150:153], v237 offset:1024
	ds_read_b128 v[154:157], v237 offset:2048
	ds_read_b128 v[158:161], v237 offset:3072
	s_add_u32 s69, s0, 0xfffc0080
	s_addc_u32 s70, s1, -1
	s_cmp_eq_u32 s68, 12
	s_cselect_b32 s71, s34, s70
	s_cselect_b32 s70, s35, s69
	s_cselect_b32 s73, s40, s67
	s_cselect_b32 s72, s57, s59
	v_lshl_add_u64 v[172:173], s[0:1], 0, v[170:171]
	s_add_i32 m0, s17, 0xc000
	ds_read_b128 v[162:165], v238
	ds_read_b128 v[176:179], v238 offset:1024
	ds_read_b128 v[180:183], v238 offset:2048
	ds_read_b128 v[184:187], v238 offset:3072
	ds_read_b128 v[188:191], v238 offset:4096
	ds_read_b128 v[192:195], v238 offset:5120
	ds_read_b128 v[196:199], v238 offset:6144
	ds_read_b128 v[200:203], v238 offset:7168
	global_load_lds_dwordx4 v[172:173], off
	v_lshl_add_u64 v[172:173], v[172:173], 0, s[10:11]
	s_add_i32 m0, s17, 0xe000
	s_nop 0
	global_load_lds_dwordx4 v[172:173], off
	s_waitcnt vmcnt(8)
	s_waitcnt lgkmcnt(0)
	s_barrier
	s_setprio 1
	s_waitcnt lgkmcnt(0)
	v_mfma_f32_16x16x32_bf16 v[126:129], v[130:133], v[162:165], 0
	v_mfma_f32_16x16x32_bf16 v[122:125], v[138:141], v[162:165], 0
	v_mfma_f32_16x16x32_bf16 v[118:121], v[130:133], v[180:183], 0
	v_mfma_f32_16x16x32_bf16 v[114:117], v[138:141], v[180:183], 0
	v_mfma_f32_16x16x32_bf16 v[110:113], v[130:133], v[188:191], 0
	v_mfma_f32_16x16x32_bf16 v[106:109], v[138:141], v[188:191], 0
	v_mfma_f32_16x16x32_bf16 v[102:105], v[130:133], v[196:199], 0
	v_mfma_f32_16x16x32_bf16 v[98:101], v[138:141], v[196:199], 0
	v_mfma_f32_16x16x32_bf16 v[126:129], v[134:137], v[176:179], v[126:129]
	v_mfma_f32_16x16x32_bf16 v[122:125], v[142:145], v[176:179], v[122:125]
	v_mfma_f32_16x16x32_bf16 v[118:121], v[134:137], v[184:187], v[118:121]
	v_mfma_f32_16x16x32_bf16 v[114:117], v[142:145], v[184:187], v[114:117]
	v_mfma_f32_16x16x32_bf16 v[110:113], v[134:137], v[192:195], v[110:113]
	v_mfma_f32_16x16x32_bf16 v[106:109], v[142:145], v[192:195], v[106:109]
	v_mfma_f32_16x16x32_bf16 v[102:105], v[134:137], v[200:203], v[102:105]
	v_mfma_f32_16x16x32_bf16 v[98:101], v[142:145], v[200:203], v[98:101]
	s_setprio 0
	s_setprio 1
	v_mfma_f32_16x16x32_bf16 v[70:73], v[146:149], v[162:165], 0
	v_mfma_f32_16x16x32_bf16 v[62:65], v[154:157], v[162:165], 0
	v_mfma_f32_16x16x32_bf16 v[54:57], v[146:149], v[180:183], 0
	v_mfma_f32_16x16x32_bf16 v[50:53], v[154:157], v[180:183], 0
	v_mfma_f32_16x16x32_bf16 v[46:49], v[146:149], v[188:191], 0
	v_mfma_f32_16x16x32_bf16 v[42:45], v[154:157], v[188:191], 0
	v_mfma_f32_16x16x32_bf16 v[38:41], v[146:149], v[196:199], 0
	v_mfma_f32_16x16x32_bf16 v[34:37], v[154:157], v[196:199], 0
	v_mfma_f32_16x16x32_bf16 v[70:73], v[150:153], v[176:179], v[70:73]
	v_mfma_f32_16x16x32_bf16 v[62:65], v[158:161], v[176:179], v[62:65]
	v_mfma_f32_16x16x32_bf16 v[54:57], v[150:153], v[184:187], v[54:57]
	v_mfma_f32_16x16x32_bf16 v[50:53], v[158:161], v[184:187], v[50:53]
	v_mfma_f32_16x16x32_bf16 v[46:49], v[150:153], v[192:195], v[46:49]
	v_mfma_f32_16x16x32_bf16 v[42:45], v[158:161], v[192:195], v[42:45]
	v_mfma_f32_16x16x32_bf16 v[38:41], v[150:153], v[200:203], v[38:41]
	v_mfma_f32_16x16x32_bf16 v[34:37], v[158:161], v[200:203], v[34:37]
	s_setprio 0
	s_barrier
	s_add_i32 s69, s94, s16
	v_lshl_add_u64 v[172:173], s[72:73], 0, v[168:169]
	s_mov_b32 m0, s69
	ds_read_b128 v[162:165], v238 offset:16384
	ds_read_b128 v[176:179], v238 offset:17408
	ds_read_b128 v[180:183], v238 offset:18432
	ds_read_b128 v[184:187], v238 offset:19456
	ds_read_b128 v[188:191], v238 offset:20480
	ds_read_b128 v[192:195], v238 offset:21504
	ds_read_b128 v[196:199], v238 offset:22528
	ds_read_b128 v[200:203], v238 offset:23552
	global_load_lds_dwordx4 v[172:173], off
	v_lshl_add_u64 v[174:175], v[172:173], 0, s[10:11]
	s_add_i32 m0, s69, 0x2000
	s_add_i32 s69, s95, s16
	global_load_lds_dwordx4 v[174:175], off
	v_lshl_add_u64 v[174:175], v[172:173], 0, s[12:13]
	s_mov_b32 m0, s69
	s_nop 0
	global_load_lds_dwordx4 v[174:175], off
	v_lshl_add_u64 v[174:175], v[172:173], 0, s[14:15]
	s_add_i32 m0, s69, 0x2000
	s_nop 0
	global_load_lds_dwordx4 v[174:175], off
	v_lshl_add_u64 v[174:175], s[70:71], 0, v[166:167]
	s_mov_b32 m0, s17
	v_lshl_add_u64 v[204:205], v[174:175], 0, s[10:11]
	global_load_lds_dwordx4 v[174:175], off
	s_mov_b32 m0, s33
	s_nop 0
	global_load_lds_dwordx4 v[204:205], off
	s_waitcnt vmcnt(8)
	s_waitcnt lgkmcnt(0)
	s_barrier
	s_setprio 1
	s_waitcnt lgkmcnt(0)
	v_mfma_f32_16x16x32_bf16 v[94:97], v[130:133], v[162:165], 0
	v_mfma_f32_16x16x32_bf16 v[90:93], v[138:141], v[162:165], 0
	v_mfma_f32_16x16x32_bf16 v[86:89], v[130:133], v[180:183], 0
	v_mfma_f32_16x16x32_bf16 v[82:85], v[138:141], v[180:183], 0
	v_mfma_f32_16x16x32_bf16 v[78:81], v[130:133], v[188:191], 0
	v_mfma_f32_16x16x32_bf16 v[74:77], v[138:141], v[188:191], 0
	v_mfma_f32_16x16x32_bf16 v[66:69], v[130:133], v[196:199], 0
	v_mfma_f32_16x16x32_bf16 v[58:61], v[138:141], v[196:199], 0
	v_mfma_f32_16x16x32_bf16 v[94:97], v[134:137], v[176:179], v[94:97]
	v_mfma_f32_16x16x32_bf16 v[90:93], v[142:145], v[176:179], v[90:93]
	v_mfma_f32_16x16x32_bf16 v[86:89], v[134:137], v[184:187], v[86:89]
	v_mfma_f32_16x16x32_bf16 v[82:85], v[142:145], v[184:187], v[82:85]
	v_mfma_f32_16x16x32_bf16 v[78:81], v[134:137], v[192:195], v[78:81]
	v_mfma_f32_16x16x32_bf16 v[74:77], v[142:145], v[192:195], v[74:77]
	v_mfma_f32_16x16x32_bf16 v[66:69], v[134:137], v[200:203], v[66:69]
	v_mfma_f32_16x16x32_bf16 v[58:61], v[142:145], v[200:203], v[58:61]
	s_setprio 0
	s_setprio 1
	v_mfma_f32_16x16x32_bf16 v[30:33], v[146:149], v[162:165], 0
	v_mfma_f32_16x16x32_bf16 v[26:29], v[154:157], v[162:165], 0
	v_mfma_f32_16x16x32_bf16 v[22:25], v[146:149], v[180:183], 0
	v_mfma_f32_16x16x32_bf16 v[18:21], v[154:157], v[180:183], 0
	v_mfma_f32_16x16x32_bf16 v[14:17], v[146:149], v[188:191], 0
	v_mfma_f32_16x16x32_bf16 v[10:13], v[154:157], v[188:191], 0
	v_mfma_f32_16x16x32_bf16 v[6:9], v[146:149], v[196:199], 0
	v_mfma_f32_16x16x32_bf16 v[2:5], v[154:157], v[196:199], 0
	v_mfma_f32_16x16x32_bf16 v[30:33], v[150:153], v[176:179], v[30:33]
	v_mfma_f32_16x16x32_bf16 v[26:29], v[158:161], v[176:179], v[26:29]
	v_mfma_f32_16x16x32_bf16 v[22:25], v[150:153], v[184:187], v[22:25]
	v_mfma_f32_16x16x32_bf16 v[18:21], v[158:161], v[184:187], v[18:21]
	v_mfma_f32_16x16x32_bf16 v[14:17], v[150:153], v[192:195], v[14:17]
	v_mfma_f32_16x16x32_bf16 v[10:13], v[158:161], v[192:195], v[10:13]
	v_mfma_f32_16x16x32_bf16 v[6:9], v[150:153], v[200:203], v[6:9]
	v_mfma_f32_16x16x32_bf16 v[2:5], v[158:161], v[200:203], v[2:5]
	s_setprio 0
	s_barrier
	s_add_i32 s69, 0, 0x18000
	s_add_i32 s70, 0, 0x1c000
	v_add_u32_e32 v142, s69, v1
	v_add_u32_e32 v158, s70, v1
	ds_read_b128 v[130:133], v142
	ds_read_b128 v[134:137], v142 offset:1024
	ds_read_b128 v[138:141], v142 offset:2048
	ds_read_b128 v[142:145], v142 offset:3072
	ds_read_b128 v[146:149], v158
	ds_read_b128 v[150:153], v158 offset:1024
	ds_read_b128 v[154:157], v158 offset:2048
	ds_read_b128 v[158:161], v158 offset:3072
	s_mov_b32 m0, s19
	v_lshl_add_u64 v[204:205], v[174:175], 0, s[12:13]
	ds_read_b128 v[162:165], v238 offset:32768
	ds_read_b128 v[176:179], v238 offset:33792
	ds_read_b128 v[180:183], v238 offset:34816
	ds_read_b128 v[184:187], v238 offset:35840
	ds_read_b128 v[188:191], v238 offset:36864
	ds_read_b128 v[192:195], v238 offset:37888
	ds_read_b128 v[196:199], v238 offset:38912
	ds_read_b128 v[200:203], v238 offset:39936
	global_load_lds_dwordx4 v[204:205], off
	v_lshl_add_u64 v[204:205], v[174:175], 0, s[14:15]
	s_mov_b32 m0, s76
	s_nop 0
	global_load_lds_dwordx4 v[204:205], off
	s_waitcnt vmcnt(8)
	s_waitcnt lgkmcnt(0)
	s_barrier
	s_setprio 1
	s_waitcnt lgkmcnt(0)
	v_mfma_f32_16x16x32_bf16 v[126:129], v[130:133], v[162:165], v[126:129]
	v_mfma_f32_16x16x32_bf16 v[122:125], v[138:141], v[162:165], v[122:125]
	v_mfma_f32_16x16x32_bf16 v[118:121], v[130:133], v[180:183], v[118:121]
	v_mfma_f32_16x16x32_bf16 v[114:117], v[138:141], v[180:183], v[114:117]
	v_mfma_f32_16x16x32_bf16 v[110:113], v[130:133], v[188:191], v[110:113]
	v_mfma_f32_16x16x32_bf16 v[106:109], v[138:141], v[188:191], v[106:109]
	v_mfma_f32_16x16x32_bf16 v[102:105], v[130:133], v[196:199], v[102:105]
	v_mfma_f32_16x16x32_bf16 v[98:101], v[138:141], v[196:199], v[98:101]
	v_mfma_f32_16x16x32_bf16 v[126:129], v[134:137], v[176:179], v[126:129]
	v_mfma_f32_16x16x32_bf16 v[122:125], v[142:145], v[176:179], v[122:125]
	v_mfma_f32_16x16x32_bf16 v[118:121], v[134:137], v[184:187], v[118:121]
	v_mfma_f32_16x16x32_bf16 v[114:117], v[142:145], v[184:187], v[114:117]
	v_mfma_f32_16x16x32_bf16 v[110:113], v[134:137], v[192:195], v[110:113]
	v_mfma_f32_16x16x32_bf16 v[106:109], v[142:145], v[192:195], v[106:109]
	v_mfma_f32_16x16x32_bf16 v[102:105], v[134:137], v[200:203], v[102:105]
	v_mfma_f32_16x16x32_bf16 v[98:101], v[142:145], v[200:203], v[98:101]
	s_setprio 0
	s_setprio 1
	v_mfma_f32_16x16x32_bf16 v[70:73], v[146:149], v[162:165], v[70:73]
	v_mfma_f32_16x16x32_bf16 v[62:65], v[154:157], v[162:165], v[62:65]
	v_mfma_f32_16x16x32_bf16 v[54:57], v[146:149], v[180:183], v[54:57]
	v_mfma_f32_16x16x32_bf16 v[50:53], v[154:157], v[180:183], v[50:53]
	v_mfma_f32_16x16x32_bf16 v[46:49], v[146:149], v[188:191], v[46:49]
	v_mfma_f32_16x16x32_bf16 v[42:45], v[154:157], v[188:191], v[42:45]
	v_mfma_f32_16x16x32_bf16 v[38:41], v[146:149], v[196:199], v[38:41]
	v_mfma_f32_16x16x32_bf16 v[34:37], v[154:157], v[196:199], v[34:37]
	v_mfma_f32_16x16x32_bf16 v[70:73], v[150:153], v[176:179], v[70:73]
	v_mfma_f32_16x16x32_bf16 v[62:65], v[158:161], v[176:179], v[62:65]
	v_mfma_f32_16x16x32_bf16 v[54:57], v[150:153], v[184:187], v[54:57]
	v_mfma_f32_16x16x32_bf16 v[50:53], v[158:161], v[184:187], v[50:53]
	v_mfma_f32_16x16x32_bf16 v[46:49], v[150:153], v[192:195], v[46:49]
	v_mfma_f32_16x16x32_bf16 v[42:45], v[158:161], v[192:195], v[42:45]
	v_mfma_f32_16x16x32_bf16 v[38:41], v[150:153], v[200:203], v[38:41]
	v_mfma_f32_16x16x32_bf16 v[34:37], v[158:161], v[200:203], v[34:37]
	s_setprio 0
	s_barrier
	s_add_i32 s69, s69, s16
	v_lshl_add_u64 v[204:205], v[172:173], 0, s[44:45]
	s_mov_b32 m0, s69
	ds_read_b128 v[162:165], v238 offset:49152
	ds_read_b128 v[176:179], v238 offset:50176
	ds_read_b128 v[180:183], v238 offset:51200
	ds_read_b128 v[184:187], v238 offset:52224
	ds_read_b128 v[188:191], v238 offset:53248
	ds_read_b128 v[192:195], v238 offset:54272
	ds_read_b128 v[196:199], v238 offset:55296
	ds_read_b128 v[200:203], v238 offset:56320
	global_load_lds_dwordx4 v[204:205], off
	v_lshl_add_u64 v[204:205], v[172:173], 0, s[48:49]
	s_add_i32 m0, s69, 0x2000
	s_add_i32 s69, s70, s16
	global_load_lds_dwordx4 v[204:205], off
	v_lshl_add_u64 v[204:205], v[172:173], 0, s[50:51]
	s_mov_b32 m0, s69
	v_lshl_add_u64 v[172:173], v[172:173], 0, s[52:53]
	global_load_lds_dwordx4 v[204:205], off
	s_add_i32 m0, s69, 0x2000
	s_nop 0
	global_load_lds_dwordx4 v[172:173], off
	v_lshl_add_u64 v[172:173], v[174:175], 0, s[44:45]
	s_mov_b32 m0, s87
	s_nop 0
	global_load_lds_dwordx4 v[172:173], off
	v_lshl_add_u64 v[172:173], v[174:175], 0, s[48:49]
	s_mov_b32 m0, s88
	s_nop 0
	global_load_lds_dwordx4 v[172:173], off
	s_waitcnt vmcnt(8)
	s_waitcnt lgkmcnt(0)
	s_barrier
	s_setprio 1
	s_waitcnt lgkmcnt(0)
	v_mfma_f32_16x16x32_bf16 v[94:97], v[130:133], v[162:165], v[94:97]
	v_mfma_f32_16x16x32_bf16 v[90:93], v[138:141], v[162:165], v[90:93]
	v_mfma_f32_16x16x32_bf16 v[86:89], v[130:133], v[180:183], v[86:89]
	v_mfma_f32_16x16x32_bf16 v[82:85], v[138:141], v[180:183], v[82:85]
	v_mfma_f32_16x16x32_bf16 v[78:81], v[130:133], v[188:191], v[78:81]
	v_mfma_f32_16x16x32_bf16 v[74:77], v[138:141], v[188:191], v[74:77]
	v_mfma_f32_16x16x32_bf16 v[66:69], v[130:133], v[196:199], v[66:69]
	v_mfma_f32_16x16x32_bf16 v[58:61], v[138:141], v[196:199], v[58:61]
	v_mfma_f32_16x16x32_bf16 v[94:97], v[134:137], v[176:179], v[94:97]
	v_mfma_f32_16x16x32_bf16 v[90:93], v[142:145], v[176:179], v[90:93]
	v_mfma_f32_16x16x32_bf16 v[86:89], v[134:137], v[184:187], v[86:89]
	v_mfma_f32_16x16x32_bf16 v[82:85], v[142:145], v[184:187], v[82:85]
	v_mfma_f32_16x16x32_bf16 v[78:81], v[134:137], v[192:195], v[78:81]
	v_mfma_f32_16x16x32_bf16 v[74:77], v[142:145], v[192:195], v[74:77]
	v_mfma_f32_16x16x32_bf16 v[66:69], v[134:137], v[200:203], v[66:69]
	v_mfma_f32_16x16x32_bf16 v[58:61], v[142:145], v[200:203], v[58:61]
	s_setprio 0
	s_setprio 1
	v_mfma_f32_16x16x32_bf16 v[30:33], v[146:149], v[162:165], v[30:33]
	v_mfma_f32_16x16x32_bf16 v[26:29], v[154:157], v[162:165], v[26:29]
	v_mfma_f32_16x16x32_bf16 v[22:25], v[146:149], v[180:183], v[22:25]
	v_mfma_f32_16x16x32_bf16 v[18:21], v[154:157], v[180:183], v[18:21]
	v_mfma_f32_16x16x32_bf16 v[14:17], v[146:149], v[188:191], v[14:17]
	v_mfma_f32_16x16x32_bf16 v[10:13], v[154:157], v[188:191], v[10:13]
	v_mfma_f32_16x16x32_bf16 v[6:9], v[146:149], v[196:199], v[6:9]
	v_mfma_f32_16x16x32_bf16 v[2:5], v[154:157], v[196:199], v[2:5]
	v_mfma_f32_16x16x32_bf16 v[30:33], v[150:153], v[176:179], v[30:33]
	v_mfma_f32_16x16x32_bf16 v[26:29], v[158:161], v[176:179], v[26:29]
	v_mfma_f32_16x16x32_bf16 v[22:25], v[150:153], v[184:187], v[22:25]
	v_mfma_f32_16x16x32_bf16 v[18:21], v[158:161], v[184:187], v[18:21]
	v_mfma_f32_16x16x32_bf16 v[14:17], v[150:153], v[192:195], v[14:17]
	v_mfma_f32_16x16x32_bf16 v[10:13], v[158:161], v[192:195], v[10:13]
	v_mfma_f32_16x16x32_bf16 v[6:9], v[150:153], v[200:203], v[6:9]
	v_mfma_f32_16x16x32_bf16 v[2:5], v[158:161], v[200:203], v[2:5]
	s_setprio 0
	s_add_i32 s68, s68, 2
	s_add_u32 s59, s59, 0x100
	s_addc_u32 s67, s67, 0
	s_add_u32 s0, s0, 0x100
	s_addc_u32 s1, s1, 0
	s_cmp_gt_u32 s68, 13
	s_barrier
	s_cbranch_scc1 .Lpeel_exit_568
.LBB0_568:
	ds_read_b128 v[130:133], v236
	ds_read_b128 v[134:137], v236 offset:1024
	ds_read_b128 v[138:141], v236 offset:2048
	ds_read_b128 v[142:145], v236 offset:3072
	ds_read_b128 v[146:149], v237
	ds_read_b128 v[150:153], v237 offset:1024
	ds_read_b128 v[154:157], v237 offset:2048
	ds_read_b128 v[158:161], v237 offset:3072
	s_add_u32 s69, s0, 0xfffc0080
	s_addc_u32 s70, s1, -1
	s_cmp_eq_u32 s68, 12
	s_cselect_b32 s71, s34, s70
	s_cselect_b32 s70, s35, s69
	s_cselect_b32 s73, s40, s67
	s_cselect_b32 s72, s57, s59
	v_lshl_add_u64 v[172:173], s[0:1], 0, v[170:171]
	s_add_i32 m0, s17, 0xc000
	ds_read_b128 v[162:165], v238
	ds_read_b128 v[176:179], v238 offset:1024
	ds_read_b128 v[180:183], v238 offset:2048
	ds_read_b128 v[184:187], v238 offset:3072
	ds_read_b128 v[188:191], v238 offset:4096
	ds_read_b128 v[192:195], v238 offset:5120
	ds_read_b128 v[196:199], v238 offset:6144
	ds_read_b128 v[200:203], v238 offset:7168
	global_load_lds_dwordx4 v[172:173], off
	v_lshl_add_u64 v[172:173], v[172:173], 0, s[10:11]
	s_add_i32 m0, s17, 0xe000
	s_nop 0
	global_load_lds_dwordx4 v[172:173], off
	s_waitcnt vmcnt(8)
	s_waitcnt lgkmcnt(0)
	s_barrier
	s_setprio 1
	s_waitcnt lgkmcnt(0)
	v_mfma_f32_16x16x32_bf16 v[126:129], v[130:133], v[162:165], v[126:129]
	v_mfma_f32_16x16x32_bf16 v[122:125], v[138:141], v[162:165], v[122:125]
	v_mfma_f32_16x16x32_bf16 v[118:121], v[130:133], v[180:183], v[118:121]
	v_mfma_f32_16x16x32_bf16 v[114:117], v[138:141], v[180:183], v[114:117]
	v_mfma_f32_16x16x32_bf16 v[110:113], v[130:133], v[188:191], v[110:113]
	v_mfma_f32_16x16x32_bf16 v[106:109], v[138:141], v[188:191], v[106:109]
	v_mfma_f32_16x16x32_bf16 v[102:105], v[130:133], v[196:199], v[102:105]
	v_mfma_f32_16x16x32_bf16 v[98:101], v[138:141], v[196:199], v[98:101]
	v_mfma_f32_16x16x32_bf16 v[126:129], v[134:137], v[176:179], v[126:129]
	v_mfma_f32_16x16x32_bf16 v[122:125], v[142:145], v[176:179], v[122:125]
	v_mfma_f32_16x16x32_bf16 v[118:121], v[134:137], v[184:187], v[118:121]
	v_mfma_f32_16x16x32_bf16 v[114:117], v[142:145], v[184:187], v[114:117]
	v_mfma_f32_16x16x32_bf16 v[110:113], v[134:137], v[192:195], v[110:113]
	v_mfma_f32_16x16x32_bf16 v[106:109], v[142:145], v[192:195], v[106:109]
	v_mfma_f32_16x16x32_bf16 v[102:105], v[134:137], v[200:203], v[102:105]
	v_mfma_f32_16x16x32_bf16 v[98:101], v[142:145], v[200:203], v[98:101]
	s_setprio 0
	s_setprio 1
	v_mfma_f32_16x16x32_bf16 v[70:73], v[146:149], v[162:165], v[70:73]
	v_mfma_f32_16x16x32_bf16 v[62:65], v[154:157], v[162:165], v[62:65]
	v_mfma_f32_16x16x32_bf16 v[54:57], v[146:149], v[180:183], v[54:57]
	v_mfma_f32_16x16x32_bf16 v[50:53], v[154:157], v[180:183], v[50:53]
	v_mfma_f32_16x16x32_bf16 v[46:49], v[146:149], v[188:191], v[46:49]
	v_mfma_f32_16x16x32_bf16 v[42:45], v[154:157], v[188:191], v[42:45]
	v_mfma_f32_16x16x32_bf16 v[38:41], v[146:149], v[196:199], v[38:41]
	v_mfma_f32_16x16x32_bf16 v[34:37], v[154:157], v[196:199], v[34:37]
	v_mfma_f32_16x16x32_bf16 v[70:73], v[150:153], v[176:179], v[70:73]
	v_mfma_f32_16x16x32_bf16 v[62:65], v[158:161], v[176:179], v[62:65]
	v_mfma_f32_16x16x32_bf16 v[54:57], v[150:153], v[184:187], v[54:57]
	v_mfma_f32_16x16x32_bf16 v[50:53], v[158:161], v[184:187], v[50:53]
	v_mfma_f32_16x16x32_bf16 v[46:49], v[150:153], v[192:195], v[46:49]
	v_mfma_f32_16x16x32_bf16 v[42:45], v[158:161], v[192:195], v[42:45]
	v_mfma_f32_16x16x32_bf16 v[38:41], v[150:153], v[200:203], v[38:41]
	v_mfma_f32_16x16x32_bf16 v[34:37], v[158:161], v[200:203], v[34:37]
	s_setprio 0
	s_barrier
	s_add_i32 s69, s94, s16
	v_lshl_add_u64 v[172:173], s[72:73], 0, v[168:169]
	s_mov_b32 m0, s69
	ds_read_b128 v[162:165], v238 offset:16384
	ds_read_b128 v[176:179], v238 offset:17408
	ds_read_b128 v[180:183], v238 offset:18432
	ds_read_b128 v[184:187], v238 offset:19456
	ds_read_b128 v[188:191], v238 offset:20480
	ds_read_b128 v[192:195], v238 offset:21504
	ds_read_b128 v[196:199], v238 offset:22528
	ds_read_b128 v[200:203], v238 offset:23552
	global_load_lds_dwordx4 v[172:173], off
	v_lshl_add_u64 v[174:175], v[172:173], 0, s[10:11]
	s_add_i32 m0, s69, 0x2000
	s_add_i32 s69, s95, s16
	global_load_lds_dwordx4 v[174:175], off
	v_lshl_add_u64 v[174:175], v[172:173], 0, s[12:13]
	s_mov_b32 m0, s69
	s_nop 0
	global_load_lds_dwordx4 v[174:175], off
	v_lshl_add_u64 v[174:175], v[172:173], 0, s[14:15]
	s_add_i32 m0, s69, 0x2000
	s_nop 0
	global_load_lds_dwordx4 v[174:175], off
	v_lshl_add_u64 v[174:175], s[70:71], 0, v[166:167]
	s_mov_b32 m0, s17
	v_lshl_add_u64 v[204:205], v[174:175], 0, s[10:11]
	global_load_lds_dwordx4 v[174:175], off
	s_mov_b32 m0, s33
	s_nop 0
	global_load_lds_dwordx4 v[204:205], off
	s_waitcnt vmcnt(8)
	s_waitcnt lgkmcnt(0)
	s_barrier
	s_setprio 1
	s_waitcnt lgkmcnt(0)
	v_mfma_f32_16x16x32_bf16 v[94:97], v[130:133], v[162:165], v[94:97]
	v_mfma_f32_16x16x32_bf16 v[90:93], v[138:141], v[162:165], v[90:93]
	v_mfma_f32_16x16x32_bf16 v[86:89], v[130:133], v[180:183], v[86:89]
	v_mfma_f32_16x16x32_bf16 v[82:85], v[138:141], v[180:183], v[82:85]
	v_mfma_f32_16x16x32_bf16 v[78:81], v[130:133], v[188:191], v[78:81]
	v_mfma_f32_16x16x32_bf16 v[74:77], v[138:141], v[188:191], v[74:77]
	v_mfma_f32_16x16x32_bf16 v[66:69], v[130:133], v[196:199], v[66:69]
	v_mfma_f32_16x16x32_bf16 v[58:61], v[138:141], v[196:199], v[58:61]
	v_mfma_f32_16x16x32_bf16 v[94:97], v[134:137], v[176:179], v[94:97]
	v_mfma_f32_16x16x32_bf16 v[90:93], v[142:145], v[176:179], v[90:93]
	v_mfma_f32_16x16x32_bf16 v[86:89], v[134:137], v[184:187], v[86:89]
	v_mfma_f32_16x16x32_bf16 v[82:85], v[142:145], v[184:187], v[82:85]
	v_mfma_f32_16x16x32_bf16 v[78:81], v[134:137], v[192:195], v[78:81]
	v_mfma_f32_16x16x32_bf16 v[74:77], v[142:145], v[192:195], v[74:77]
	v_mfma_f32_16x16x32_bf16 v[66:69], v[134:137], v[200:203], v[66:69]
	v_mfma_f32_16x16x32_bf16 v[58:61], v[142:145], v[200:203], v[58:61]
	s_setprio 0
	s_setprio 1
	v_mfma_f32_16x16x32_bf16 v[30:33], v[146:149], v[162:165], v[30:33]
	v_mfma_f32_16x16x32_bf16 v[26:29], v[154:157], v[162:165], v[26:29]
	v_mfma_f32_16x16x32_bf16 v[22:25], v[146:149], v[180:183], v[22:25]
	v_mfma_f32_16x16x32_bf16 v[18:21], v[154:157], v[180:183], v[18:21]
	v_mfma_f32_16x16x32_bf16 v[14:17], v[146:149], v[188:191], v[14:17]
	v_mfma_f32_16x16x32_bf16 v[10:13], v[154:157], v[188:191], v[10:13]
	v_mfma_f32_16x16x32_bf16 v[6:9], v[146:149], v[196:199], v[6:9]
	v_mfma_f32_16x16x32_bf16 v[2:5], v[154:157], v[196:199], v[2:5]
	v_mfma_f32_16x16x32_bf16 v[30:33], v[150:153], v[176:179], v[30:33]
	v_mfma_f32_16x16x32_bf16 v[26:29], v[158:161], v[176:179], v[26:29]
	v_mfma_f32_16x16x32_bf16 v[22:25], v[150:153], v[184:187], v[22:25]
	v_mfma_f32_16x16x32_bf16 v[18:21], v[158:161], v[184:187], v[18:21]
	v_mfma_f32_16x16x32_bf16 v[14:17], v[150:153], v[192:195], v[14:17]
	v_mfma_f32_16x16x32_bf16 v[10:13], v[158:161], v[192:195], v[10:13]
	v_mfma_f32_16x16x32_bf16 v[6:9], v[150:153], v[200:203], v[6:9]
	v_mfma_f32_16x16x32_bf16 v[2:5], v[158:161], v[200:203], v[2:5]
	s_setprio 0
	s_barrier
	s_add_i32 s69, 0, 0x18000
	s_add_i32 s70, 0, 0x1c000
	v_add_u32_e32 v142, s69, v1
	v_add_u32_e32 v158, s70, v1
	ds_read_b128 v[130:133], v142
	ds_read_b128 v[134:137], v142 offset:1024
	ds_read_b128 v[138:141], v142 offset:2048
	ds_read_b128 v[142:145], v142 offset:3072
	ds_read_b128 v[146:149], v158
	ds_read_b128 v[150:153], v158 offset:1024
	ds_read_b128 v[154:157], v158 offset:2048
	ds_read_b128 v[158:161], v158 offset:3072
	s_mov_b32 m0, s19
	v_lshl_add_u64 v[204:205], v[174:175], 0, s[12:13]
	ds_read_b128 v[162:165], v238 offset:32768
	ds_read_b128 v[176:179], v238 offset:33792
	ds_read_b128 v[180:183], v238 offset:34816
	ds_read_b128 v[184:187], v238 offset:35840
	ds_read_b128 v[188:191], v238 offset:36864
	ds_read_b128 v[192:195], v238 offset:37888
	ds_read_b128 v[196:199], v238 offset:38912
	ds_read_b128 v[200:203], v238 offset:39936
	global_load_lds_dwordx4 v[204:205], off
	v_lshl_add_u64 v[204:205], v[174:175], 0, s[14:15]
	s_mov_b32 m0, s76
	s_nop 0
	global_load_lds_dwordx4 v[204:205], off
	s_waitcnt vmcnt(8)
	s_waitcnt lgkmcnt(0)
	s_barrier
	s_setprio 1
	s_waitcnt lgkmcnt(0)
	v_mfma_f32_16x16x32_bf16 v[126:129], v[130:133], v[162:165], v[126:129]
	v_mfma_f32_16x16x32_bf16 v[122:125], v[138:141], v[162:165], v[122:125]
	v_mfma_f32_16x16x32_bf16 v[118:121], v[130:133], v[180:183], v[118:121]
	v_mfma_f32_16x16x32_bf16 v[114:117], v[138:141], v[180:183], v[114:117]
	v_mfma_f32_16x16x32_bf16 v[110:113], v[130:133], v[188:191], v[110:113]
	v_mfma_f32_16x16x32_bf16 v[106:109], v[138:141], v[188:191], v[106:109]
	v_mfma_f32_16x16x32_bf16 v[102:105], v[130:133], v[196:199], v[102:105]
	v_mfma_f32_16x16x32_bf16 v[98:101], v[138:141], v[196:199], v[98:101]
	v_mfma_f32_16x16x32_bf16 v[126:129], v[134:137], v[176:179], v[126:129]
	v_mfma_f32_16x16x32_bf16 v[122:125], v[142:145], v[176:179], v[122:125]
	v_mfma_f32_16x16x32_bf16 v[118:121], v[134:137], v[184:187], v[118:121]
	v_mfma_f32_16x16x32_bf16 v[114:117], v[142:145], v[184:187], v[114:117]
	v_mfma_f32_16x16x32_bf16 v[110:113], v[134:137], v[192:195], v[110:113]
	v_mfma_f32_16x16x32_bf16 v[106:109], v[142:145], v[192:195], v[106:109]
	v_mfma_f32_16x16x32_bf16 v[102:105], v[134:137], v[200:203], v[102:105]
	v_mfma_f32_16x16x32_bf16 v[98:101], v[142:145], v[200:203], v[98:101]
	s_setprio 0
	s_setprio 1
	v_mfma_f32_16x16x32_bf16 v[70:73], v[146:149], v[162:165], v[70:73]
	v_mfma_f32_16x16x32_bf16 v[62:65], v[154:157], v[162:165], v[62:65]
	v_mfma_f32_16x16x32_bf16 v[54:57], v[146:149], v[180:183], v[54:57]
	v_mfma_f32_16x16x32_bf16 v[50:53], v[154:157], v[180:183], v[50:53]
	v_mfma_f32_16x16x32_bf16 v[46:49], v[146:149], v[188:191], v[46:49]
	v_mfma_f32_16x16x32_bf16 v[42:45], v[154:157], v[188:191], v[42:45]
	v_mfma_f32_16x16x32_bf16 v[38:41], v[146:149], v[196:199], v[38:41]
	v_mfma_f32_16x16x32_bf16 v[34:37], v[154:157], v[196:199], v[34:37]
	v_mfma_f32_16x16x32_bf16 v[70:73], v[150:153], v[176:179], v[70:73]
	v_mfma_f32_16x16x32_bf16 v[62:65], v[158:161], v[176:179], v[62:65]
	v_mfma_f32_16x16x32_bf16 v[54:57], v[150:153], v[184:187], v[54:57]
	v_mfma_f32_16x16x32_bf16 v[50:53], v[158:161], v[184:187], v[50:53]
	v_mfma_f32_16x16x32_bf16 v[46:49], v[150:153], v[192:195], v[46:49]
	v_mfma_f32_16x16x32_bf16 v[42:45], v[158:161], v[192:195], v[42:45]
	v_mfma_f32_16x16x32_bf16 v[38:41], v[150:153], v[200:203], v[38:41]
	v_mfma_f32_16x16x32_bf16 v[34:37], v[158:161], v[200:203], v[34:37]
	s_setprio 0
	s_barrier
	s_add_i32 s69, s69, s16
	v_lshl_add_u64 v[204:205], v[172:173], 0, s[44:45]
	s_mov_b32 m0, s69
	ds_read_b128 v[162:165], v238 offset:49152
	ds_read_b128 v[176:179], v238 offset:50176
	ds_read_b128 v[180:183], v238 offset:51200
	ds_read_b128 v[184:187], v238 offset:52224
	ds_read_b128 v[188:191], v238 offset:53248
	ds_read_b128 v[192:195], v238 offset:54272
	ds_read_b128 v[196:199], v238 offset:55296
	ds_read_b128 v[200:203], v238 offset:56320
	global_load_lds_dwordx4 v[204:205], off
	v_lshl_add_u64 v[204:205], v[172:173], 0, s[48:49]
	s_add_i32 m0, s69, 0x2000
	s_add_i32 s69, s70, s16
	global_load_lds_dwordx4 v[204:205], off
	v_lshl_add_u64 v[204:205], v[172:173], 0, s[50:51]
	s_mov_b32 m0, s69
	v_lshl_add_u64 v[172:173], v[172:173], 0, s[52:53]
	global_load_lds_dwordx4 v[204:205], off
	s_add_i32 m0, s69, 0x2000
	s_nop 0
	global_load_lds_dwordx4 v[172:173], off
	v_lshl_add_u64 v[172:173], v[174:175], 0, s[44:45]
	s_mov_b32 m0, s87
	s_nop 0
	global_load_lds_dwordx4 v[172:173], off
	v_lshl_add_u64 v[172:173], v[174:175], 0, s[48:49]
	s_mov_b32 m0, s88
	s_nop 0
	global_load_lds_dwordx4 v[172:173], off
	s_waitcnt vmcnt(8)
	s_waitcnt lgkmcnt(0)
	s_barrier
	s_setprio 1
	s_waitcnt lgkmcnt(0)
	v_mfma_f32_16x16x32_bf16 v[94:97], v[130:133], v[162:165], v[94:97]
	v_mfma_f32_16x16x32_bf16 v[90:93], v[138:141], v[162:165], v[90:93]
	v_mfma_f32_16x16x32_bf16 v[86:89], v[130:133], v[180:183], v[86:89]
	v_mfma_f32_16x16x32_bf16 v[82:85], v[138:141], v[180:183], v[82:85]
	v_mfma_f32_16x16x32_bf16 v[78:81], v[130:133], v[188:191], v[78:81]
	v_mfma_f32_16x16x32_bf16 v[74:77], v[138:141], v[188:191], v[74:77]
	v_mfma_f32_16x16x32_bf16 v[66:69], v[130:133], v[196:199], v[66:69]
	v_mfma_f32_16x16x32_bf16 v[58:61], v[138:141], v[196:199], v[58:61]
	v_mfma_f32_16x16x32_bf16 v[94:97], v[134:137], v[176:179], v[94:97]
	v_mfma_f32_16x16x32_bf16 v[90:93], v[142:145], v[176:179], v[90:93]
	v_mfma_f32_16x16x32_bf16 v[86:89], v[134:137], v[184:187], v[86:89]
	v_mfma_f32_16x16x32_bf16 v[82:85], v[142:145], v[184:187], v[82:85]
	v_mfma_f32_16x16x32_bf16 v[78:81], v[134:137], v[192:195], v[78:81]
	v_mfma_f32_16x16x32_bf16 v[74:77], v[142:145], v[192:195], v[74:77]
	v_mfma_f32_16x16x32_bf16 v[66:69], v[134:137], v[200:203], v[66:69]
	v_mfma_f32_16x16x32_bf16 v[58:61], v[142:145], v[200:203], v[58:61]
	s_setprio 0
	s_setprio 1
	v_mfma_f32_16x16x32_bf16 v[30:33], v[146:149], v[162:165], v[30:33]
	v_mfma_f32_16x16x32_bf16 v[26:29], v[154:157], v[162:165], v[26:29]
	v_mfma_f32_16x16x32_bf16 v[22:25], v[146:149], v[180:183], v[22:25]
	v_mfma_f32_16x16x32_bf16 v[18:21], v[154:157], v[180:183], v[18:21]
	v_mfma_f32_16x16x32_bf16 v[14:17], v[146:149], v[188:191], v[14:17]
	v_mfma_f32_16x16x32_bf16 v[10:13], v[154:157], v[188:191], v[10:13]
	v_mfma_f32_16x16x32_bf16 v[6:9], v[146:149], v[196:199], v[6:9]
	v_mfma_f32_16x16x32_bf16 v[2:5], v[154:157], v[196:199], v[2:5]
	v_mfma_f32_16x16x32_bf16 v[30:33], v[150:153], v[176:179], v[30:33]
	v_mfma_f32_16x16x32_bf16 v[26:29], v[158:161], v[176:179], v[26:29]
	v_mfma_f32_16x16x32_bf16 v[22:25], v[150:153], v[184:187], v[22:25]
	v_mfma_f32_16x16x32_bf16 v[18:21], v[158:161], v[184:187], v[18:21]
	v_mfma_f32_16x16x32_bf16 v[14:17], v[150:153], v[192:195], v[14:17]
	v_mfma_f32_16x16x32_bf16 v[10:13], v[158:161], v[192:195], v[10:13]
	v_mfma_f32_16x16x32_bf16 v[6:9], v[150:153], v[200:203], v[6:9]
	v_mfma_f32_16x16x32_bf16 v[2:5], v[158:161], v[200:203], v[2:5]
	s_setprio 0
	s_add_i32 s68, s68, 2
	s_add_u32 s59, s59, 0x100
	s_addc_u32 s67, s67, 0
	s_add_u32 s0, s0, 0x100
	s_addc_u32 s1, s1, 0
	s_cmp_gt_u32 s68, 13
	s_barrier
	s_cbranch_scc0 .LBB0_568

.Lpeel_660:
	ds_read_b128 v[98:101], v158
	ds_read_b128 v[102:105], v158 offset:1024
	ds_read_b128 v[106:109], v158 offset:2048
	ds_read_b128 v[110:113], v158 offset:3072
	ds_read_b128 v[162:165], v159
	ds_read_b128 v[166:169], v159 offset:1024
	ds_read_b128 v[170:173], v159 offset:2048
	ds_read_b128 v[174:177], v159 offset:3072
	s_add_u32 s63, s60, 0xfffe0080
	s_addc_u32 s80, s61, -1
	s_cmp_eq_u32 s62, 4
	s_cselect_b32 s81, s34, s80
	s_cselect_b32 s80, s35, s63
	s_cselect_b32 s83, s51, s79
	s_cselect_b32 s82, s53, s78
	v_lshl_add_u64 v[210:211], s[60:61], 0, v[152:153]
	s_add_i32 m0, s49, 0xc000
	ds_read_b128 v[178:181], v160
	ds_read_b128 v[182:185], v160 offset:1024
	ds_read_b128 v[186:189], v160 offset:2048
	ds_read_b128 v[190:193], v160 offset:3072
	ds_read_b128 v[194:197], v160 offset:4096
	ds_read_b128 v[198:201], v160 offset:5120
	ds_read_b128 v[202:205], v160 offset:6144
	ds_read_b128 v[206:209], v160 offset:7168
	global_load_lds_dwordx4 v[210:211], off
	v_lshl_add_u64 v[210:211], v[210:211], 0, s[4:5]
	s_add_i32 m0, s49, 0xe000
	s_nop 0
	global_load_lds_dwordx4 v[210:211], off
	s_waitcnt vmcnt(8)
	s_waitcnt lgkmcnt(0)
	s_barrier
	s_setprio 1
	s_waitcnt lgkmcnt(0)
	v_mfma_i32_16x16x64_i8 v[142:145], v[98:101], v[178:181], 0
	v_mfma_i32_16x16x64_i8 v[138:141], v[106:109], v[178:181], 0
	v_mfma_i32_16x16x64_i8 v[126:129], v[98:101], v[186:189], 0
	v_mfma_i32_16x16x64_i8 v[122:125], v[106:109], v[186:189], 0
	v_mfma_i32_16x16x64_i8 v[94:97], v[98:101], v[194:197], 0
	v_mfma_i32_16x16x64_i8 v[90:93], v[106:109], v[194:197], 0
	v_mfma_i32_16x16x64_i8 v[78:81], v[98:101], v[202:205], 0
	v_mfma_i32_16x16x64_i8 v[74:77], v[106:109], v[202:205], 0
	v_mfma_i32_16x16x64_i8 v[142:145], v[102:105], v[182:185], v[142:145]
	v_mfma_i32_16x16x64_i8 v[138:141], v[110:113], v[182:185], v[138:141]
	v_mfma_i32_16x16x64_i8 v[126:129], v[102:105], v[190:193], v[126:129]
	v_mfma_i32_16x16x64_i8 v[122:125], v[110:113], v[190:193], v[122:125]
	v_mfma_i32_16x16x64_i8 v[94:97], v[102:105], v[198:201], v[94:97]
	v_mfma_i32_16x16x64_i8 v[90:93], v[110:113], v[198:201], v[90:93]
	v_mfma_i32_16x16x64_i8 v[78:81], v[102:105], v[206:209], v[78:81]
	v_mfma_i32_16x16x64_i8 v[74:77], v[110:113], v[206:209], v[74:77]
	s_setprio 0
	s_setprio 1
	v_mfma_i32_16x16x64_i8 v[134:137], v[162:165], v[178:181], 0
	v_mfma_i32_16x16x64_i8 v[130:133], v[170:173], v[178:181], 0
	v_mfma_i32_16x16x64_i8 v[118:121], v[162:165], v[186:189], 0
	v_mfma_i32_16x16x64_i8 v[114:117], v[170:173], v[186:189], 0
	v_mfma_i32_16x16x64_i8 v[86:89], v[162:165], v[194:197], 0
	v_mfma_i32_16x16x64_i8 v[82:85], v[170:173], v[194:197], 0
	v_mfma_i32_16x16x64_i8 v[70:73], v[162:165], v[202:205], 0
	v_mfma_i32_16x16x64_i8 v[66:69], v[170:173], v[202:205], 0
	v_mfma_i32_16x16x64_i8 v[134:137], v[166:169], v[182:185], v[134:137]
	v_mfma_i32_16x16x64_i8 v[130:133], v[174:177], v[182:185], v[130:133]
	v_mfma_i32_16x16x64_i8 v[118:121], v[166:169], v[190:193], v[118:121]
	v_mfma_i32_16x16x64_i8 v[114:117], v[174:177], v[190:193], v[114:117]
	v_mfma_i32_16x16x64_i8 v[86:89], v[166:169], v[198:201], v[86:89]
	v_mfma_i32_16x16x64_i8 v[82:85], v[174:177], v[198:201], v[82:85]
	v_mfma_i32_16x16x64_i8 v[70:73], v[166:169], v[206:209], v[70:73]
	v_mfma_i32_16x16x64_i8 v[66:69], v[174:177], v[206:209], v[66:69]
	s_setprio 0
	s_barrier
	s_add_i32 s63, s72, s16
	v_lshl_add_u64 v[210:211], s[82:83], 0, v[148:149]
	s_mov_b32 m0, s63
	ds_read_b128 v[178:181], v160 offset:16384
	ds_read_b128 v[182:185], v160 offset:17408
	ds_read_b128 v[186:189], v160 offset:18432
	ds_read_b128 v[190:193], v160 offset:19456
	ds_read_b128 v[194:197], v160 offset:20480
	ds_read_b128 v[198:201], v160 offset:21504
	ds_read_b128 v[202:205], v160 offset:22528
	ds_read_b128 v[206:209], v160 offset:23552
	global_load_lds_dwordx4 v[210:211], off
	v_lshl_add_u64 v[212:213], v[210:211], 0, s[4:5]
	s_add_i32 m0, s63, 0x2000
	s_add_i32 s63, s73, s16
	global_load_lds_dwordx4 v[212:213], off
	v_lshl_add_u64 v[212:213], v[210:211], 0, s[8:9]
	s_mov_b32 m0, s63
	s_nop 0
	global_load_lds_dwordx4 v[212:213], off
	v_lshl_add_u64 v[212:213], v[210:211], 0, s[10:11]
	s_add_i32 m0, s63, 0x2000
	s_nop 0
	global_load_lds_dwordx4 v[212:213], off
	v_lshl_add_u64 v[212:213], s[80:81], 0, v[146:147]
	s_mov_b32 m0, s49
	v_lshl_add_u64 v[214:215], v[212:213], 0, s[4:5]
	global_load_lds_dwordx4 v[212:213], off
	s_mov_b32 m0, s64
	s_nop 0
	global_load_lds_dwordx4 v[214:215], off
	s_waitcnt vmcnt(8)
	s_waitcnt lgkmcnt(0)
	s_barrier
	s_setprio 1
	s_waitcnt lgkmcnt(0)
	v_mfma_i32_16x16x64_i8 v[62:65], v[98:101], v[178:181], 0
	v_mfma_i32_16x16x64_i8 v[58:61], v[106:109], v[178:181], 0
	v_mfma_i32_16x16x64_i8 v[46:49], v[98:101], v[186:189], 0
	v_mfma_i32_16x16x64_i8 v[42:45], v[106:109], v[186:189], 0
	v_mfma_i32_16x16x64_i8 v[30:33], v[98:101], v[194:197], 0
	v_mfma_i32_16x16x64_i8 v[26:29], v[106:109], v[194:197], 0
	v_mfma_i32_16x16x64_i8 v[14:17], v[98:101], v[202:205], 0
	v_mfma_i32_16x16x64_i8 v[10:13], v[106:109], v[202:205], 0
	v_mfma_i32_16x16x64_i8 v[62:65], v[102:105], v[182:185], v[62:65]
	v_mfma_i32_16x16x64_i8 v[58:61], v[110:113], v[182:185], v[58:61]
	v_mfma_i32_16x16x64_i8 v[46:49], v[102:105], v[190:193], v[46:49]
	v_mfma_i32_16x16x64_i8 v[42:45], v[110:113], v[190:193], v[42:45]
	v_mfma_i32_16x16x64_i8 v[30:33], v[102:105], v[198:201], v[30:33]
	v_mfma_i32_16x16x64_i8 v[26:29], v[110:113], v[198:201], v[26:29]
	v_mfma_i32_16x16x64_i8 v[14:17], v[102:105], v[206:209], v[14:17]
	v_mfma_i32_16x16x64_i8 v[10:13], v[110:113], v[206:209], v[10:13]
	s_setprio 0
	s_setprio 1
	v_mfma_i32_16x16x64_i8 v[54:57], v[162:165], v[178:181], 0
	v_mfma_i32_16x16x64_i8 v[50:53], v[170:173], v[178:181], 0
	v_mfma_i32_16x16x64_i8 v[38:41], v[162:165], v[186:189], 0
	v_mfma_i32_16x16x64_i8 v[34:37], v[170:173], v[186:189], 0
	v_mfma_i32_16x16x64_i8 v[22:25], v[162:165], v[194:197], 0
	v_mfma_i32_16x16x64_i8 v[18:21], v[170:173], v[194:197], 0
	v_mfma_i32_16x16x64_i8 v[6:9], v[162:165], v[202:205], 0
	v_mfma_i32_16x16x64_i8 v[2:5], v[170:173], v[202:205], 0
	v_mfma_i32_16x16x64_i8 v[54:57], v[166:169], v[182:185], v[54:57]
	v_mfma_i32_16x16x64_i8 v[50:53], v[174:177], v[182:185], v[50:53]
	v_mfma_i32_16x16x64_i8 v[38:41], v[166:169], v[190:193], v[38:41]
	v_mfma_i32_16x16x64_i8 v[34:37], v[174:177], v[190:193], v[34:37]
	v_mfma_i32_16x16x64_i8 v[22:25], v[166:169], v[198:201], v[22:25]
	v_mfma_i32_16x16x64_i8 v[18:21], v[174:177], v[198:201], v[18:21]
	v_mfma_i32_16x16x64_i8 v[6:9], v[166:169], v[206:209], v[6:9]
	v_mfma_i32_16x16x64_i8 v[2:5], v[174:177], v[206:209], v[2:5]
	s_setprio 0
	s_barrier
	s_add_i32 s63, 0, 0x18000
	s_add_i32 s80, 0, 0x1c000
	v_add_u32_e32 v110, s63, v1
	v_add_u32_e32 v150, s80, v1
	ds_read_b128 v[98:101], v110
	ds_read_b128 v[102:105], v110 offset:1024
	ds_read_b128 v[106:109], v110 offset:2048
	ds_read_b128 v[110:113], v110 offset:3072
	ds_read_b128 v[162:165], v150
	ds_read_b128 v[166:169], v150 offset:1024
	ds_read_b128 v[170:173], v150 offset:2048
	ds_read_b128 v[174:177], v150 offset:3072
	s_mov_b32 m0, s65
	v_lshl_add_u64 v[214:215], v[212:213], 0, s[8:9]
	ds_read_b128 v[178:181], v160 offset:32768
	ds_read_b128 v[182:185], v160 offset:33792
	ds_read_b128 v[186:189], v160 offset:34816
	ds_read_b128 v[190:193], v160 offset:35840
	ds_read_b128 v[194:197], v160 offset:36864
	ds_read_b128 v[198:201], v160 offset:37888
	ds_read_b128 v[202:205], v160 offset:38912
	ds_read_b128 v[206:209], v160 offset:39936
	global_load_lds_dwordx4 v[214:215], off
	v_lshl_add_u64 v[214:215], v[212:213], 0, s[10:11]
	s_mov_b32 m0, s66
	s_nop 0
	global_load_lds_dwordx4 v[214:215], off
	s_waitcnt vmcnt(8)
	s_waitcnt lgkmcnt(0)
	s_barrier
	s_setprio 1
	s_waitcnt lgkmcnt(0)
	v_mfma_i32_16x16x64_i8 v[142:145], v[98:101], v[178:181], v[142:145]
	v_mfma_i32_16x16x64_i8 v[138:141], v[106:109], v[178:181], v[138:141]
	v_mfma_i32_16x16x64_i8 v[126:129], v[98:101], v[186:189], v[126:129]
	v_mfma_i32_16x16x64_i8 v[122:125], v[106:109], v[186:189], v[122:125]
	v_mfma_i32_16x16x64_i8 v[94:97], v[98:101], v[194:197], v[94:97]
	v_mfma_i32_16x16x64_i8 v[90:93], v[106:109], v[194:197], v[90:93]
	v_mfma_i32_16x16x64_i8 v[78:81], v[98:101], v[202:205], v[78:81]
	v_mfma_i32_16x16x64_i8 v[74:77], v[106:109], v[202:205], v[74:77]
	v_mfma_i32_16x16x64_i8 v[142:145], v[102:105], v[182:185], v[142:145]
	v_mfma_i32_16x16x64_i8 v[138:141], v[110:113], v[182:185], v[138:141]
	v_mfma_i32_16x16x64_i8 v[126:129], v[102:105], v[190:193], v[126:129]
	v_mfma_i32_16x16x64_i8 v[122:125], v[110:113], v[190:193], v[122:125]
	v_mfma_i32_16x16x64_i8 v[94:97], v[102:105], v[198:201], v[94:97]
	v_mfma_i32_16x16x64_i8 v[90:93], v[110:113], v[198:201], v[90:93]
	v_mfma_i32_16x16x64_i8 v[78:81], v[102:105], v[206:209], v[78:81]
	v_mfma_i32_16x16x64_i8 v[74:77], v[110:113], v[206:209], v[74:77]
	s_setprio 0
	s_setprio 1
	v_mfma_i32_16x16x64_i8 v[134:137], v[162:165], v[178:181], v[134:137]
	v_mfma_i32_16x16x64_i8 v[130:133], v[170:173], v[178:181], v[130:133]
	v_mfma_i32_16x16x64_i8 v[118:121], v[162:165], v[186:189], v[118:121]
	v_mfma_i32_16x16x64_i8 v[114:117], v[170:173], v[186:189], v[114:117]
	v_mfma_i32_16x16x64_i8 v[86:89], v[162:165], v[194:197], v[86:89]
	v_mfma_i32_16x16x64_i8 v[82:85], v[170:173], v[194:197], v[82:85]
	v_mfma_i32_16x16x64_i8 v[70:73], v[162:165], v[202:205], v[70:73]
	v_mfma_i32_16x16x64_i8 v[66:69], v[170:173], v[202:205], v[66:69]
	v_mfma_i32_16x16x64_i8 v[134:137], v[166:169], v[182:185], v[134:137]
	v_mfma_i32_16x16x64_i8 v[130:133], v[174:177], v[182:185], v[130:133]
	v_mfma_i32_16x16x64_i8 v[118:121], v[166:169], v[190:193], v[118:121]
	v_mfma_i32_16x16x64_i8 v[114:117], v[174:177], v[190:193], v[114:117]
	v_mfma_i32_16x16x64_i8 v[86:89], v[166:169], v[198:201], v[86:89]
	v_mfma_i32_16x16x64_i8 v[82:85], v[174:177], v[198:201], v[82:85]
	v_mfma_i32_16x16x64_i8 v[70:73], v[166:169], v[206:209], v[70:73]
	v_mfma_i32_16x16x64_i8 v[66:69], v[174:177], v[206:209], v[66:69]
	s_setprio 0
	s_barrier
	s_add_i32 s63, s63, s16
	v_lshl_add_u64 v[214:215], v[210:211], 0, s[36:37]
	s_mov_b32 m0, s63
	ds_read_b128 v[178:181], v160 offset:49152
	ds_read_b128 v[182:185], v160 offset:50176
	ds_read_b128 v[186:189], v160 offset:51200
	ds_read_b128 v[190:193], v160 offset:52224
	ds_read_b128 v[194:197], v160 offset:53248
	ds_read_b128 v[198:201], v160 offset:54272
	ds_read_b128 v[202:205], v160 offset:55296
	ds_read_b128 v[206:209], v160 offset:56320
	global_load_lds_dwordx4 v[214:215], off
	v_lshl_add_u64 v[214:215], v[210:211], 0, s[40:41]
	s_add_i32 m0, s63, 0x2000
	s_add_i32 s63, s80, s16
	global_load_lds_dwordx4 v[214:215], off
	v_lshl_add_u64 v[214:215], v[210:211], 0, s[42:43]
	s_mov_b32 m0, s63
	v_lshl_add_u64 v[210:211], v[210:211], 0, s[44:45]
	global_load_lds_dwordx4 v[214:215], off
	s_add_i32 m0, s63, 0x2000
	s_nop 0
	global_load_lds_dwordx4 v[210:211], off
	v_lshl_add_u64 v[210:211], v[212:213], 0, s[36:37]
	s_mov_b32 m0, s68
	s_nop 0
	global_load_lds_dwordx4 v[210:211], off
	v_lshl_add_u64 v[210:211], v[212:213], 0, s[40:41]
	s_mov_b32 m0, s69
	s_nop 0
	global_load_lds_dwordx4 v[210:211], off
	s_waitcnt vmcnt(8)
	s_waitcnt lgkmcnt(0)
	s_barrier
	s_setprio 1
	s_waitcnt lgkmcnt(0)
	v_mfma_i32_16x16x64_i8 v[62:65], v[98:101], v[178:181], v[62:65]
	v_mfma_i32_16x16x64_i8 v[58:61], v[106:109], v[178:181], v[58:61]
	v_mfma_i32_16x16x64_i8 v[46:49], v[98:101], v[186:189], v[46:49]
	v_mfma_i32_16x16x64_i8 v[42:45], v[106:109], v[186:189], v[42:45]
	v_mfma_i32_16x16x64_i8 v[30:33], v[98:101], v[194:197], v[30:33]
	v_mfma_i32_16x16x64_i8 v[26:29], v[106:109], v[194:197], v[26:29]
	v_mfma_i32_16x16x64_i8 v[14:17], v[98:101], v[202:205], v[14:17]
	v_mfma_i32_16x16x64_i8 v[10:13], v[106:109], v[202:205], v[10:13]
	v_mfma_i32_16x16x64_i8 v[62:65], v[102:105], v[182:185], v[62:65]
	v_mfma_i32_16x16x64_i8 v[58:61], v[110:113], v[182:185], v[58:61]
	v_mfma_i32_16x16x64_i8 v[46:49], v[102:105], v[190:193], v[46:49]
	v_mfma_i32_16x16x64_i8 v[42:45], v[110:113], v[190:193], v[42:45]
	v_mfma_i32_16x16x64_i8 v[30:33], v[102:105], v[198:201], v[30:33]
	v_mfma_i32_16x16x64_i8 v[26:29], v[110:113], v[198:201], v[26:29]
	v_mfma_i32_16x16x64_i8 v[14:17], v[102:105], v[206:209], v[14:17]
	v_mfma_i32_16x16x64_i8 v[10:13], v[110:113], v[206:209], v[10:13]
	s_setprio 0
	s_setprio 1
	v_mfma_i32_16x16x64_i8 v[54:57], v[162:165], v[178:181], v[54:57]
	v_mfma_i32_16x16x64_i8 v[50:53], v[170:173], v[178:181], v[50:53]
	v_mfma_i32_16x16x64_i8 v[38:41], v[162:165], v[186:189], v[38:41]
	v_mfma_i32_16x16x64_i8 v[34:37], v[170:173], v[186:189], v[34:37]
	v_mfma_i32_16x16x64_i8 v[22:25], v[162:165], v[194:197], v[22:25]
	v_mfma_i32_16x16x64_i8 v[18:21], v[170:173], v[194:197], v[18:21]
	v_mfma_i32_16x16x64_i8 v[6:9], v[162:165], v[202:205], v[6:9]
	v_mfma_i32_16x16x64_i8 v[2:5], v[170:173], v[202:205], v[2:5]
	v_mfma_i32_16x16x64_i8 v[54:57], v[166:169], v[182:185], v[54:57]
	v_mfma_i32_16x16x64_i8 v[50:53], v[174:177], v[182:185], v[50:53]
	v_mfma_i32_16x16x64_i8 v[38:41], v[166:169], v[190:193], v[38:41]
	v_mfma_i32_16x16x64_i8 v[34:37], v[174:177], v[190:193], v[34:37]
	v_mfma_i32_16x16x64_i8 v[22:25], v[166:169], v[198:201], v[22:25]
	v_mfma_i32_16x16x64_i8 v[18:21], v[174:177], v[198:201], v[18:21]
	v_mfma_i32_16x16x64_i8 v[6:9], v[166:169], v[206:209], v[6:9]
	v_mfma_i32_16x16x64_i8 v[2:5], v[174:177], v[206:209], v[2:5]
	s_setprio 0
	s_add_i32 s62, s62, 2
	s_add_u32 s78, s78, 0x100
	s_addc_u32 s79, s79, 0
	s_add_u32 s60, s60, 0x100
	s_addc_u32 s61, s61, 0
	s_cmp_gt_u32 s62, 5
	s_barrier
	s_cbranch_scc1 .Lpeel_exit_660
.LBB0_660:
	ds_read_b128 v[98:101], v158
	ds_read_b128 v[102:105], v158 offset:1024
	ds_read_b128 v[106:109], v158 offset:2048
	ds_read_b128 v[110:113], v158 offset:3072
	ds_read_b128 v[162:165], v159
	ds_read_b128 v[166:169], v159 offset:1024
	ds_read_b128 v[170:173], v159 offset:2048
	ds_read_b128 v[174:177], v159 offset:3072
	s_add_u32 s63, s60, 0xfffe0080
	s_addc_u32 s80, s61, -1
	s_cmp_eq_u32 s62, 4
	s_cselect_b32 s81, s34, s80
	s_cselect_b32 s80, s35, s63
	s_cselect_b32 s83, s51, s79
	s_cselect_b32 s82, s53, s78
	v_lshl_add_u64 v[210:211], s[60:61], 0, v[152:153]
	s_add_i32 m0, s49, 0xc000
	ds_read_b128 v[178:181], v160
	ds_read_b128 v[182:185], v160 offset:1024
	ds_read_b128 v[186:189], v160 offset:2048
	ds_read_b128 v[190:193], v160 offset:3072
	ds_read_b128 v[194:197], v160 offset:4096
	ds_read_b128 v[198:201], v160 offset:5120
	ds_read_b128 v[202:205], v160 offset:6144
	ds_read_b128 v[206:209], v160 offset:7168
	global_load_lds_dwordx4 v[210:211], off
	v_lshl_add_u64 v[210:211], v[210:211], 0, s[4:5]
	s_add_i32 m0, s49, 0xe000
	s_nop 0
	global_load_lds_dwordx4 v[210:211], off
	s_waitcnt vmcnt(8)
	s_waitcnt lgkmcnt(0)
	s_barrier
	s_setprio 1
	s_waitcnt lgkmcnt(0)
	v_mfma_i32_16x16x64_i8 v[142:145], v[98:101], v[178:181], v[142:145]
	v_mfma_i32_16x16x64_i8 v[138:141], v[106:109], v[178:181], v[138:141]
	v_mfma_i32_16x16x64_i8 v[126:129], v[98:101], v[186:189], v[126:129]
	v_mfma_i32_16x16x64_i8 v[122:125], v[106:109], v[186:189], v[122:125]
	v_mfma_i32_16x16x64_i8 v[94:97], v[98:101], v[194:197], v[94:97]
	v_mfma_i32_16x16x64_i8 v[90:93], v[106:109], v[194:197], v[90:93]
	v_mfma_i32_16x16x64_i8 v[78:81], v[98:101], v[202:205], v[78:81]
	v_mfma_i32_16x16x64_i8 v[74:77], v[106:109], v[202:205], v[74:77]
	v_mfma_i32_16x16x64_i8 v[142:145], v[102:105], v[182:185], v[142:145]
	v_mfma_i32_16x16x64_i8 v[138:141], v[110:113], v[182:185], v[138:141]
	v_mfma_i32_16x16x64_i8 v[126:129], v[102:105], v[190:193], v[126:129]
	v_mfma_i32_16x16x64_i8 v[122:125], v[110:113], v[190:193], v[122:125]
	v_mfma_i32_16x16x64_i8 v[94:97], v[102:105], v[198:201], v[94:97]
	v_mfma_i32_16x16x64_i8 v[90:93], v[110:113], v[198:201], v[90:93]
	v_mfma_i32_16x16x64_i8 v[78:81], v[102:105], v[206:209], v[78:81]
	v_mfma_i32_16x16x64_i8 v[74:77], v[110:113], v[206:209], v[74:77]
	s_setprio 0
	s_setprio 1
	v_mfma_i32_16x16x64_i8 v[134:137], v[162:165], v[178:181], v[134:137]
	v_mfma_i32_16x16x64_i8 v[130:133], v[170:173], v[178:181], v[130:133]
	v_mfma_i32_16x16x64_i8 v[118:121], v[162:165], v[186:189], v[118:121]
	v_mfma_i32_16x16x64_i8 v[114:117], v[170:173], v[186:189], v[114:117]
	v_mfma_i32_16x16x64_i8 v[86:89], v[162:165], v[194:197], v[86:89]
	v_mfma_i32_16x16x64_i8 v[82:85], v[170:173], v[194:197], v[82:85]
	v_mfma_i32_16x16x64_i8 v[70:73], v[162:165], v[202:205], v[70:73]
	v_mfma_i32_16x16x64_i8 v[66:69], v[170:173], v[202:205], v[66:69]
	v_mfma_i32_16x16x64_i8 v[134:137], v[166:169], v[182:185], v[134:137]
	v_mfma_i32_16x16x64_i8 v[130:133], v[174:177], v[182:185], v[130:133]
	v_mfma_i32_16x16x64_i8 v[118:121], v[166:169], v[190:193], v[118:121]
	v_mfma_i32_16x16x64_i8 v[114:117], v[174:177], v[190:193], v[114:117]
	v_mfma_i32_16x16x64_i8 v[86:89], v[166:169], v[198:201], v[86:89]
	v_mfma_i32_16x16x64_i8 v[82:85], v[174:177], v[198:201], v[82:85]
	v_mfma_i32_16x16x64_i8 v[70:73], v[166:169], v[206:209], v[70:73]
	v_mfma_i32_16x16x64_i8 v[66:69], v[174:177], v[206:209], v[66:69]
	s_setprio 0
	s_barrier
	s_add_i32 s63, s72, s16
	v_lshl_add_u64 v[210:211], s[82:83], 0, v[148:149]
	s_mov_b32 m0, s63
	ds_read_b128 v[178:181], v160 offset:16384
	ds_read_b128 v[182:185], v160 offset:17408
	ds_read_b128 v[186:189], v160 offset:18432
	ds_read_b128 v[190:193], v160 offset:19456
	ds_read_b128 v[194:197], v160 offset:20480
	ds_read_b128 v[198:201], v160 offset:21504
	ds_read_b128 v[202:205], v160 offset:22528
	ds_read_b128 v[206:209], v160 offset:23552
	global_load_lds_dwordx4 v[210:211], off
	v_lshl_add_u64 v[212:213], v[210:211], 0, s[4:5]
	s_add_i32 m0, s63, 0x2000
	s_add_i32 s63, s73, s16
	global_load_lds_dwordx4 v[212:213], off
	v_lshl_add_u64 v[212:213], v[210:211], 0, s[8:9]
	s_mov_b32 m0, s63
	s_nop 0
	global_load_lds_dwordx4 v[212:213], off
	v_lshl_add_u64 v[212:213], v[210:211], 0, s[10:11]
	s_add_i32 m0, s63, 0x2000
	s_nop 0
	global_load_lds_dwordx4 v[212:213], off
	v_lshl_add_u64 v[212:213], s[80:81], 0, v[146:147]
	s_mov_b32 m0, s49
	v_lshl_add_u64 v[214:215], v[212:213], 0, s[4:5]
	global_load_lds_dwordx4 v[212:213], off
	s_mov_b32 m0, s64
	s_nop 0
	global_load_lds_dwordx4 v[214:215], off
	s_waitcnt vmcnt(8)
	s_waitcnt lgkmcnt(0)
	s_barrier
	s_setprio 1
	s_waitcnt lgkmcnt(0)
	v_mfma_i32_16x16x64_i8 v[62:65], v[98:101], v[178:181], v[62:65]
	v_mfma_i32_16x16x64_i8 v[58:61], v[106:109], v[178:181], v[58:61]
	v_mfma_i32_16x16x64_i8 v[46:49], v[98:101], v[186:189], v[46:49]
	v_mfma_i32_16x16x64_i8 v[42:45], v[106:109], v[186:189], v[42:45]
	v_mfma_i32_16x16x64_i8 v[30:33], v[98:101], v[194:197], v[30:33]
	v_mfma_i32_16x16x64_i8 v[26:29], v[106:109], v[194:197], v[26:29]
	v_mfma_i32_16x16x64_i8 v[14:17], v[98:101], v[202:205], v[14:17]
	v_mfma_i32_16x16x64_i8 v[10:13], v[106:109], v[202:205], v[10:13]
	v_mfma_i32_16x16x64_i8 v[62:65], v[102:105], v[182:185], v[62:65]
	v_mfma_i32_16x16x64_i8 v[58:61], v[110:113], v[182:185], v[58:61]
	v_mfma_i32_16x16x64_i8 v[46:49], v[102:105], v[190:193], v[46:49]
	v_mfma_i32_16x16x64_i8 v[42:45], v[110:113], v[190:193], v[42:45]
	v_mfma_i32_16x16x64_i8 v[30:33], v[102:105], v[198:201], v[30:33]
	v_mfma_i32_16x16x64_i8 v[26:29], v[110:113], v[198:201], v[26:29]
	v_mfma_i32_16x16x64_i8 v[14:17], v[102:105], v[206:209], v[14:17]
	v_mfma_i32_16x16x64_i8 v[10:13], v[110:113], v[206:209], v[10:13]
	s_setprio 0
	s_setprio 1
	v_mfma_i32_16x16x64_i8 v[54:57], v[162:165], v[178:181], v[54:57]
	v_mfma_i32_16x16x64_i8 v[50:53], v[170:173], v[178:181], v[50:53]
	v_mfma_i32_16x16x64_i8 v[38:41], v[162:165], v[186:189], v[38:41]
	v_mfma_i32_16x16x64_i8 v[34:37], v[170:173], v[186:189], v[34:37]
	v_mfma_i32_16x16x64_i8 v[22:25], v[162:165], v[194:197], v[22:25]
	v_mfma_i32_16x16x64_i8 v[18:21], v[170:173], v[194:197], v[18:21]
	v_mfma_i32_16x16x64_i8 v[6:9], v[162:165], v[202:205], v[6:9]
	v_mfma_i32_16x16x64_i8 v[2:5], v[170:173], v[202:205], v[2:5]
	v_mfma_i32_16x16x64_i8 v[54:57], v[166:169], v[182:185], v[54:57]
	v_mfma_i32_16x16x64_i8 v[50:53], v[174:177], v[182:185], v[50:53]
	v_mfma_i32_16x16x64_i8 v[38:41], v[166:169], v[190:193], v[38:41]
	v_mfma_i32_16x16x64_i8 v[34:37], v[174:177], v[190:193], v[34:37]
	v_mfma_i32_16x16x64_i8 v[22:25], v[166:169], v[198:201], v[22:25]
	v_mfma_i32_16x16x64_i8 v[18:21], v[174:177], v[198:201], v[18:21]
	v_mfma_i32_16x16x64_i8 v[6:9], v[166:169], v[206:209], v[6:9]
	v_mfma_i32_16x16x64_i8 v[2:5], v[174:177], v[206:209], v[2:5]
	s_setprio 0
	s_barrier
	s_add_i32 s63, 0, 0x18000
	s_add_i32 s80, 0, 0x1c000
	v_add_u32_e32 v110, s63, v1
	v_add_u32_e32 v150, s80, v1
	ds_read_b128 v[98:101], v110
	ds_read_b128 v[102:105], v110 offset:1024
	ds_read_b128 v[106:109], v110 offset:2048
	ds_read_b128 v[110:113], v110 offset:3072
	ds_read_b128 v[162:165], v150
	ds_read_b128 v[166:169], v150 offset:1024
	ds_read_b128 v[170:173], v150 offset:2048
	ds_read_b128 v[174:177], v150 offset:3072
	s_mov_b32 m0, s65
	v_lshl_add_u64 v[214:215], v[212:213], 0, s[8:9]
	ds_read_b128 v[178:181], v160 offset:32768
	ds_read_b128 v[182:185], v160 offset:33792
	ds_read_b128 v[186:189], v160 offset:34816
	ds_read_b128 v[190:193], v160 offset:35840
	ds_read_b128 v[194:197], v160 offset:36864
	ds_read_b128 v[198:201], v160 offset:37888
	ds_read_b128 v[202:205], v160 offset:38912
	ds_read_b128 v[206:209], v160 offset:39936
	global_load_lds_dwordx4 v[214:215], off
	v_lshl_add_u64 v[214:215], v[212:213], 0, s[10:11]
	s_mov_b32 m0, s66
	s_nop 0
	global_load_lds_dwordx4 v[214:215], off
	s_waitcnt vmcnt(8)
	s_waitcnt lgkmcnt(0)
	s_barrier
	s_setprio 1
	s_waitcnt lgkmcnt(0)
	v_mfma_i32_16x16x64_i8 v[142:145], v[98:101], v[178:181], v[142:145]
	v_mfma_i32_16x16x64_i8 v[138:141], v[106:109], v[178:181], v[138:141]
	v_mfma_i32_16x16x64_i8 v[126:129], v[98:101], v[186:189], v[126:129]
	v_mfma_i32_16x16x64_i8 v[122:125], v[106:109], v[186:189], v[122:125]
	v_mfma_i32_16x16x64_i8 v[94:97], v[98:101], v[194:197], v[94:97]
	v_mfma_i32_16x16x64_i8 v[90:93], v[106:109], v[194:197], v[90:93]
	v_mfma_i32_16x16x64_i8 v[78:81], v[98:101], v[202:205], v[78:81]
	v_mfma_i32_16x16x64_i8 v[74:77], v[106:109], v[202:205], v[74:77]
	v_mfma_i32_16x16x64_i8 v[142:145], v[102:105], v[182:185], v[142:145]
	v_mfma_i32_16x16x64_i8 v[138:141], v[110:113], v[182:185], v[138:141]
	v_mfma_i32_16x16x64_i8 v[126:129], v[102:105], v[190:193], v[126:129]
	v_mfma_i32_16x16x64_i8 v[122:125], v[110:113], v[190:193], v[122:125]
	v_mfma_i32_16x16x64_i8 v[94:97], v[102:105], v[198:201], v[94:97]
	v_mfma_i32_16x16x64_i8 v[90:93], v[110:113], v[198:201], v[90:93]
	v_mfma_i32_16x16x64_i8 v[78:81], v[102:105], v[206:209], v[78:81]
	v_mfma_i32_16x16x64_i8 v[74:77], v[110:113], v[206:209], v[74:77]
	s_setprio 0
	s_setprio 1
	v_mfma_i32_16x16x64_i8 v[134:137], v[162:165], v[178:181], v[134:137]
	v_mfma_i32_16x16x64_i8 v[130:133], v[170:173], v[178:181], v[130:133]
	v_mfma_i32_16x16x64_i8 v[118:121], v[162:165], v[186:189], v[118:121]
	v_mfma_i32_16x16x64_i8 v[114:117], v[170:173], v[186:189], v[114:117]
	v_mfma_i32_16x16x64_i8 v[86:89], v[162:165], v[194:197], v[86:89]
	v_mfma_i32_16x16x64_i8 v[82:85], v[170:173], v[194:197], v[82:85]
	v_mfma_i32_16x16x64_i8 v[70:73], v[162:165], v[202:205], v[70:73]
	v_mfma_i32_16x16x64_i8 v[66:69], v[170:173], v[202:205], v[66:69]
	v_mfma_i32_16x16x64_i8 v[134:137], v[166:169], v[182:185], v[134:137]
	v_mfma_i32_16x16x64_i8 v[130:133], v[174:177], v[182:185], v[130:133]
	v_mfma_i32_16x16x64_i8 v[118:121], v[166:169], v[190:193], v[118:121]
	v_mfma_i32_16x16x64_i8 v[114:117], v[174:177], v[190:193], v[114:117]
	v_mfma_i32_16x16x64_i8 v[86:89], v[166:169], v[198:201], v[86:89]
	v_mfma_i32_16x16x64_i8 v[82:85], v[174:177], v[198:201], v[82:85]
	v_mfma_i32_16x16x64_i8 v[70:73], v[166:169], v[206:209], v[70:73]
	v_mfma_i32_16x16x64_i8 v[66:69], v[174:177], v[206:209], v[66:69]
	s_setprio 0
	s_barrier
	s_add_i32 s63, s63, s16
	v_lshl_add_u64 v[214:215], v[210:211], 0, s[36:37]
	s_mov_b32 m0, s63
	ds_read_b128 v[178:181], v160 offset:49152
	ds_read_b128 v[182:185], v160 offset:50176
	ds_read_b128 v[186:189], v160 offset:51200
	ds_read_b128 v[190:193], v160 offset:52224
	ds_read_b128 v[194:197], v160 offset:53248
	ds_read_b128 v[198:201], v160 offset:54272
	ds_read_b128 v[202:205], v160 offset:55296
	ds_read_b128 v[206:209], v160 offset:56320
	global_load_lds_dwordx4 v[214:215], off
	v_lshl_add_u64 v[214:215], v[210:211], 0, s[40:41]
	s_add_i32 m0, s63, 0x2000
	s_add_i32 s63, s80, s16
	global_load_lds_dwordx4 v[214:215], off
	v_lshl_add_u64 v[214:215], v[210:211], 0, s[42:43]
	s_mov_b32 m0, s63
	v_lshl_add_u64 v[210:211], v[210:211], 0, s[44:45]
	global_load_lds_dwordx4 v[214:215], off
	s_add_i32 m0, s63, 0x2000
	s_nop 0
	global_load_lds_dwordx4 v[210:211], off
	v_lshl_add_u64 v[210:211], v[212:213], 0, s[36:37]
	s_mov_b32 m0, s68
	s_nop 0
	global_load_lds_dwordx4 v[210:211], off
	v_lshl_add_u64 v[210:211], v[212:213], 0, s[40:41]
	s_mov_b32 m0, s69
	s_nop 0
	global_load_lds_dwordx4 v[210:211], off
	s_waitcnt vmcnt(8)
	s_waitcnt lgkmcnt(0)
	s_barrier
	s_setprio 1
	s_waitcnt lgkmcnt(0)
	v_mfma_i32_16x16x64_i8 v[62:65], v[98:101], v[178:181], v[62:65]
	v_mfma_i32_16x16x64_i8 v[58:61], v[106:109], v[178:181], v[58:61]
	v_mfma_i32_16x16x64_i8 v[46:49], v[98:101], v[186:189], v[46:49]
	v_mfma_i32_16x16x64_i8 v[42:45], v[106:109], v[186:189], v[42:45]
	v_mfma_i32_16x16x64_i8 v[30:33], v[98:101], v[194:197], v[30:33]
	v_mfma_i32_16x16x64_i8 v[26:29], v[106:109], v[194:197], v[26:29]
	v_mfma_i32_16x16x64_i8 v[14:17], v[98:101], v[202:205], v[14:17]
	v_mfma_i32_16x16x64_i8 v[10:13], v[106:109], v[202:205], v[10:13]
	v_mfma_i32_16x16x64_i8 v[62:65], v[102:105], v[182:185], v[62:65]
	v_mfma_i32_16x16x64_i8 v[58:61], v[110:113], v[182:185], v[58:61]
	v_mfma_i32_16x16x64_i8 v[46:49], v[102:105], v[190:193], v[46:49]
	v_mfma_i32_16x16x64_i8 v[42:45], v[110:113], v[190:193], v[42:45]
	v_mfma_i32_16x16x64_i8 v[30:33], v[102:105], v[198:201], v[30:33]
	v_mfma_i32_16x16x64_i8 v[26:29], v[110:113], v[198:201], v[26:29]
	v_mfma_i32_16x16x64_i8 v[14:17], v[102:105], v[206:209], v[14:17]
	v_mfma_i32_16x16x64_i8 v[10:13], v[110:113], v[206:209], v[10:13]
	s_setprio 0
	s_setprio 1
	v_mfma_i32_16x16x64_i8 v[54:57], v[162:165], v[178:181], v[54:57]
	v_mfma_i32_16x16x64_i8 v[50:53], v[170:173], v[178:181], v[50:53]
	v_mfma_i32_16x16x64_i8 v[38:41], v[162:165], v[186:189], v[38:41]
	v_mfma_i32_16x16x64_i8 v[34:37], v[170:173], v[186:189], v[34:37]
	v_mfma_i32_16x16x64_i8 v[22:25], v[162:165], v[194:197], v[22:25]
	v_mfma_i32_16x16x64_i8 v[18:21], v[170:173], v[194:197], v[18:21]
	v_mfma_i32_16x16x64_i8 v[6:9], v[162:165], v[202:205], v[6:9]
	v_mfma_i32_16x16x64_i8 v[2:5], v[170:173], v[202:205], v[2:5]
	v_mfma_i32_16x16x64_i8 v[54:57], v[166:169], v[182:185], v[54:57]
	v_mfma_i32_16x16x64_i8 v[50:53], v[174:177], v[182:185], v[50:53]
	v_mfma_i32_16x16x64_i8 v[38:41], v[166:169], v[190:193], v[38:41]
	v_mfma_i32_16x16x64_i8 v[34:37], v[174:177], v[190:193], v[34:37]
	v_mfma_i32_16x16x64_i8 v[22:25], v[166:169], v[198:201], v[22:25]
	v_mfma_i32_16x16x64_i8 v[18:21], v[174:177], v[198:201], v[18:21]
	v_mfma_i32_16x16x64_i8 v[6:9], v[166:169], v[206:209], v[6:9]
	v_mfma_i32_16x16x64_i8 v[2:5], v[174:177], v[206:209], v[2:5]
	s_setprio 0
	s_add_i32 s62, s62, 2
	s_add_u32 s78, s78, 0x100
	s_addc_u32 s79, s79, 0
	s_add_u32 s60, s60, 0x100
	s_addc_u32 s61, s61, 0
	s_cmp_gt_u32 s62, 5
	s_barrier
	s_cbranch_scc0 .LBB0_660

.Lpeel_721:
	ds_read_b128 v[128:131], v217
	ds_read_b128 v[132:135], v217 offset:1024
	ds_read_b128 v[136:139], v217 offset:2048
	ds_read_b128 v[140:143], v217 offset:3072
	ds_read_b128 v[144:147], v218
	ds_read_b128 v[148:151], v218 offset:1024
	ds_read_b128 v[152:155], v218 offset:2048
	ds_read_b128 v[156:159], v218 offset:3072
	s_add_u32 s6, s0, 0xfffa8080
	s_addc_u32 s7, s1, -1
	s_cmp_eq_u32 s67, 18
	s_cselect_b32 s7, s61, s7
	s_cselect_b32 s6, s60, s6
	s_cselect_b32 s65, s63, s66
	s_cselect_b32 s64, s62, s35
	v_lshl_add_u64 v[192:193], s[0:1], 0, v[190:191]
	s_add_i32 m0, s17, 0xc000
	ds_read_b128 v[160:163], v219
	ds_read_b128 v[164:167], v219 offset:1024
	ds_read_b128 v[168:171], v219 offset:2048
	ds_read_b128 v[172:175], v219 offset:3072
	ds_read_b128 v[176:179], v219 offset:4096
	ds_read_b128 v[180:183], v219 offset:5120
	ds_read_b128 v[196:199], v219 offset:6144
	ds_read_b128 v[200:203], v219 offset:7168
	global_load_lds_dwordx4 v[192:193], off
	v_lshl_add_u64 v[192:193], v[192:193], 0, s[8:9]
	s_add_i32 m0, s17, 0xe000
	s_nop 0
	global_load_lds_dwordx4 v[192:193], off
	s_waitcnt vmcnt(8)
	s_waitcnt lgkmcnt(0)
	s_barrier
	s_setprio 1
	s_waitcnt lgkmcnt(0)
	v_mfma_scale_f32_16x16x128_f8f6f4 v[124:127], v[128:135], v[160:167], 0, v220, v220 op_sel_hi:[0, 0, 0]
	v_mfma_scale_f32_16x16x128_f8f6f4 v[120:123], v[136:143], v[160:167], 0, v220, v220 op_sel_hi:[0, 0, 0]
	v_mfma_scale_f32_16x16x128_f8f6f4 v[108:111], v[128:135], v[168:175], 0, v220, v220 op_sel_hi:[0, 0, 0]
	v_mfma_scale_f32_16x16x128_f8f6f4 v[104:107], v[136:143], v[168:175], 0, v220, v220 op_sel_hi:[0, 0, 0]
	v_mfma_scale_f32_16x16x128_f8f6f4 v[204:207], v[128:135], v[176:183], 0, v220, v220 op_sel_hi:[0, 0, 0]
	v_mfma_scale_f32_16x16x128_f8f6f4 v[208:211], v[136:143], v[176:183], 0, v220, v220 op_sel_hi:[0, 0, 0]
	v_mfma_scale_f32_16x16x128_f8f6f4 v[212:215], v[128:135], v[196:203], 0, v220, v220 op_sel_hi:[0, 0, 0]
	v_mfma_scale_f32_16x16x128_f8f6f4 v[222:225], v[136:143], v[196:203], 0, v220, v220 op_sel_hi:[0, 0, 0]
	s_setprio 0
	s_setprio 1
	v_mfma_scale_f32_16x16x128_f8f6f4 v[116:119], v[144:151], v[160:167], 0, v220, v220 op_sel_hi:[0, 0, 0]
	v_mfma_scale_f32_16x16x128_f8f6f4 v[112:115], v[152:159], v[160:167], 0, v220, v220 op_sel_hi:[0, 0, 0]
	v_mfma_scale_f32_16x16x128_f8f6f4 v[100:103], v[144:151], v[168:175], 0, v220, v220 op_sel_hi:[0, 0, 0]
	v_mfma_scale_f32_16x16x128_f8f6f4 v[96:99], v[152:159], v[168:175], 0, v220, v220 op_sel_hi:[0, 0, 0]
	v_mfma_scale_f32_16x16x128_f8f6f4 v[160:163], v[144:151], v[176:183], 0, v220, v220 op_sel_hi:[0, 0, 0]
	v_mfma_scale_f32_16x16x128_f8f6f4 v[164:167], v[152:159], v[176:183], 0, v220, v220 op_sel_hi:[0, 0, 0]
	v_mfma_scale_f32_16x16x128_f8f6f4 v[168:171], v[144:151], v[196:203], 0, v220, v220 op_sel_hi:[0, 0, 0]
	v_mfma_scale_f32_16x16x128_f8f6f4 v[172:175], v[152:159], v[196:203], 0, v220, v220 op_sel_hi:[0, 0, 0]
	s_setprio 0
	s_barrier
	v_lshl_add_u64 v[184:185], s[64:65], 0, v[188:189]
	s_add_i32 s64, s84, s16
	s_mov_b32 m0, s64
	ds_read_b128 v[64:67], v219 offset:16384
	ds_read_b128 v[68:71], v219 offset:17408
	ds_read_b128 v[72:75], v219 offset:18432
	ds_read_b128 v[76:79], v219 offset:19456
	ds_read_b128 v[80:83], v219 offset:20480
	ds_read_b128 v[84:87], v219 offset:21504
	ds_read_b128 v[88:91], v219 offset:22528
	ds_read_b128 v[92:95], v219 offset:23552
	global_load_lds_dwordx4 v[184:185], off
	v_lshl_add_u64 v[176:177], v[184:185], 0, s[8:9]
	s_add_i32 m0, s64, 0x2000
	s_add_i32 s64, s85, s16
	global_load_lds_dwordx4 v[176:177], off
	v_lshl_add_u64 v[176:177], v[184:185], 0, s[10:11]
	s_mov_b32 m0, s64
	v_lshl_add_u64 v[186:187], s[6:7], 0, v[238:239]
	global_load_lds_dwordx4 v[176:177], off
	v_lshl_add_u64 v[176:177], v[184:185], 0, s[12:13]
	s_add_i32 m0, s64, 0x2000
	s_nop 0
	global_load_lds_dwordx4 v[176:177], off
	s_mov_b32 m0, s17
	v_lshl_add_u64 v[176:177], v[186:187], 0, s[8:9]
	global_load_lds_dwordx4 v[186:187], off
	s_mov_b32 m0, s33
	s_nop 0
	global_load_lds_dwordx4 v[176:177], off
	s_waitcnt vmcnt(8)
	s_waitcnt lgkmcnt(0)
	s_barrier
	s_setprio 1
	s_waitcnt lgkmcnt(0)
	v_mfma_scale_f32_16x16x128_f8f6f4 v[60:63], v[128:135], v[64:71], 0, v220, v220 op_sel_hi:[0, 0, 0]
	v_mfma_scale_f32_16x16x128_f8f6f4 v[56:59], v[136:143], v[64:71], 0, v220, v220 op_sel_hi:[0, 0, 0]
	v_mfma_scale_f32_16x16x128_f8f6f4 v[226:229], v[128:135], v[88:95], 0, v220, v220 op_sel_hi:[0, 0, 0]
	v_mfma_scale_f32_16x16x128_f8f6f4 v[230:233], v[136:143], v[88:95], 0, v220, v220 op_sel_hi:[0, 0, 0]
	v_mfma_scale_f32_16x16x128_f8f6f4 v[176:179], v[128:135], v[72:79], 0, v220, v220 op_sel_hi:[0, 0, 0]
	v_mfma_scale_f32_16x16x128_f8f6f4 v[180:183], v[136:143], v[72:79], 0, v220, v220 op_sel_hi:[0, 0, 0]
	v_mfma_scale_f32_16x16x128_f8f6f4 v[196:199], v[128:135], v[80:87], 0, v220, v220 op_sel_hi:[0, 0, 0]
	v_mfma_scale_f32_16x16x128_f8f6f4 v[200:203], v[136:143], v[80:87], 0, v220, v220 op_sel_hi:[0, 0, 0]
	s_setprio 0
	s_setprio 1
	v_mfma_scale_f32_16x16x128_f8f6f4 v[52:55], v[144:151], v[64:71], 0, v220, v220 op_sel_hi:[0, 0, 0]
	v_mfma_scale_f32_16x16x128_f8f6f4 v[48:51], v[152:159], v[64:71], 0, v220, v220 op_sel_hi:[0, 0, 0]
	v_mfma_scale_f32_16x16x128_f8f6f4 v[242:245], v[144:151], v[80:87], 0, v220, v220 op_sel_hi:[0, 0, 0]
	v_mfma_scale_f32_16x16x128_f8f6f4 v[234:237], v[144:151], v[72:79], 0, v220, v220 op_sel_hi:[0, 0, 0]
	v_mfma_scale_f32_16x16x128_f8f6f4 v[66:69], v[152:159], v[72:79], 0, v220, v220 op_sel_hi:[0, 0, 0]
	v_mfma_scale_f32_16x16x128_f8f6f4 v[246:249], v[152:159], v[80:87], 0, v220, v220 op_sel_hi:[0, 0, 0]
	v_mfma_scale_f32_16x16x128_f8f6f4 v[250:253], v[144:151], v[88:95], 0, v220, v220 op_sel_hi:[0, 0, 0]
	v_mfma_scale_f32_16x16x128_f8f6f4 v[192:195], v[152:159], v[88:95], 0, v220, v220 op_sel_hi:[0, 0, 0]
	s_setprio 0
	s_barrier
	s_add_i32 s6, 0, 0x18000
	v_add_u32_e32 v8, s6, v216
	s_add_i32 s7, 0, 0x1c000
	s_nop 1
	ds_read_b128 v[0:3], v8
	ds_read_b128 v[4:7], v8 offset:1024
	ds_read_b128 v[16:19], v8 offset:2048
	ds_read_b128 v[20:23], v8 offset:3072
	v_add_u32_e32 v8, s7, v216
	ds_read_b128 v[128:131], v8
	ds_read_b128 v[132:135], v8 offset:1024
	ds_read_b128 v[136:139], v8 offset:2048
	ds_read_b128 v[140:143], v8 offset:3072
	s_mov_b32 m0, s47
	v_lshl_add_u64 v[64:65], v[186:187], 0, s[10:11]
	ds_read_b128 v[8:11], v219 offset:32768
	ds_read_b128 v[12:15], v219 offset:33792
	ds_read_b128 v[24:27], v219 offset:34816
	ds_read_b128 v[28:31], v219 offset:35840
	ds_read_b128 v[32:35], v219 offset:36864
	ds_read_b128 v[36:39], v219 offset:37888
	ds_read_b128 v[40:43], v219 offset:38912
	ds_read_b128 v[44:47], v219 offset:39936
	global_load_lds_dwordx4 v[64:65], off
	v_lshl_add_u64 v[64:65], v[186:187], 0, s[12:13]
	s_mov_b32 m0, s57
	s_nop 0
	global_load_lds_dwordx4 v[64:65], off
	s_waitcnt vmcnt(8)
	s_waitcnt lgkmcnt(0)
	s_barrier
	s_setprio 1
	s_waitcnt lgkmcnt(0)
	v_mfma_scale_f32_16x16x128_f8f6f4 v[124:127], v[0:7], v[8:15], v[124:127], v220, v220 op_sel_hi:[0,0,0]
	v_mfma_scale_f32_16x16x128_f8f6f4 v[120:123], v[16:23], v[8:15], v[120:123], v220, v220 op_sel_hi:[0,0,0]
	v_mfma_scale_f32_16x16x128_f8f6f4 v[108:111], v[0:7], v[24:31], v[108:111], v220, v220 op_sel_hi:[0,0,0]
	v_mfma_scale_f32_16x16x128_f8f6f4 v[104:107], v[16:23], v[24:31], v[104:107], v220, v220 op_sel_hi:[0,0,0]
	v_mfma_scale_f32_16x16x128_f8f6f4 v[92:95], v[0:7], v[32:39], v[204:207], v220, v220 op_sel_hi:[0,0,0]
	v_mfma_scale_f32_16x16x128_f8f6f4 v[88:91], v[16:23], v[32:39], v[208:211], v220, v220 op_sel_hi:[0,0,0]
	v_mfma_scale_f32_16x16x128_f8f6f4 v[76:79], v[0:7], v[40:47], v[212:215], v220, v220 op_sel_hi:[0,0,0]
	v_mfma_scale_f32_16x16x128_f8f6f4 v[72:75], v[16:23], v[40:47], v[222:225], v220, v220 op_sel_hi:[0,0,0]
	s_setprio 0
	s_setprio 1
	v_mfma_scale_f32_16x16x128_f8f6f4 v[116:119], v[128:135], v[8:15], v[116:119], v220, v220 op_sel_hi:[0,0,0]
	v_mfma_scale_f32_16x16x128_f8f6f4 v[112:115], v[136:143], v[8:15], v[112:115], v220, v220 op_sel_hi:[0,0,0]
	v_mfma_scale_f32_16x16x128_f8f6f4 v[100:103], v[128:135], v[24:31], v[100:103], v220, v220 op_sel_hi:[0,0,0]
	v_mfma_scale_f32_16x16x128_f8f6f4 v[96:99], v[136:143], v[24:31], v[96:99], v220, v220 op_sel_hi:[0,0,0]
	v_mfma_scale_f32_16x16x128_f8f6f4 v[84:87], v[128:135], v[32:39], v[160:163], v220, v220 op_sel_hi:[0,0,0]
	v_mfma_scale_f32_16x16x128_f8f6f4 v[80:83], v[136:143], v[32:39], v[164:167], v220, v220 op_sel_hi:[0,0,0]
	v_mfma_scale_f32_16x16x128_f8f6f4 v[24:27], v[128:135], v[40:47], v[168:171], v220, v220 op_sel_hi:[0,0,0]
	v_mfma_scale_f32_16x16x128_f8f6f4 v[10:13], v[136:143], v[40:47], v[172:175], v220, v220 op_sel_hi:[0,0,0]
	s_setprio 0
	s_barrier
	s_add_i32 s6, s6, s16
	v_lshl_add_u64 v[8:9], v[184:185], 0, s[28:29]
	s_mov_b32 m0, s6
	ds_read_b128 v[32:35], v219 offset:49152
	ds_read_b128 v[36:39], v219 offset:50176
	ds_read_b128 v[144:147], v219 offset:51200
	ds_read_b128 v[148:151], v219 offset:52224
	ds_read_b128 v[152:155], v219 offset:53248
	ds_read_b128 v[156:159], v219 offset:54272
	ds_read_b128 v[160:163], v219 offset:55296
	ds_read_b128 v[164:167], v219 offset:56320
	global_load_lds_dwordx4 v[8:9], off
	v_lshl_add_u64 v[8:9], v[184:185], 0, s[36:37]
	s_add_i32 m0, s6, 0x2000
	s_add_i32 s6, s7, s16
	global_load_lds_dwordx4 v[8:9], off
	v_lshl_add_u64 v[8:9], v[184:185], 0, s[40:41]
	s_mov_b32 m0, s6
	s_nop 0
	global_load_lds_dwordx4 v[8:9], off
	v_lshl_add_u64 v[8:9], v[184:185], 0, s[42:43]
	s_add_i32 m0, s6, 0x2000
	s_nop 0
	global_load_lds_dwordx4 v[8:9], off
	v_lshl_add_u64 v[8:9], v[186:187], 0, s[28:29]
	s_mov_b32 m0, s77
	s_nop 0
	global_load_lds_dwordx4 v[8:9], off
	v_lshl_add_u64 v[8:9], v[186:187], 0, s[36:37]
	s_mov_b32 m0, s78
	s_nop 0
	global_load_lds_dwordx4 v[8:9], off
	s_waitcnt vmcnt(8)
	s_waitcnt lgkmcnt(0)
	s_barrier
	s_setprio 1
	s_waitcnt lgkmcnt(0)
	v_mfma_scale_f32_16x16x128_f8f6f4 v[60:63], v[0:7], v[32:39], v[60:63], v220, v220 op_sel_hi:[0,0,0]
	v_mfma_scale_f32_16x16x128_f8f6f4 v[56:59], v[16:23], v[32:39], v[56:59], v220, v220 op_sel_hi:[0,0,0]
	v_mfma_scale_f32_16x16x128_f8f6f4 v[44:47], v[0:7], v[144:151], v[176:179], v220, v220 op_sel_hi:[0,0,0]
	v_mfma_scale_f32_16x16x128_f8f6f4 v[40:43], v[16:23], v[144:151], v[180:183], v220, v220 op_sel_hi:[0,0,0]
	v_mfma_scale_f32_16x16x128_f8f6f4 v[28:31], v[0:7], v[152:159], v[196:199], v220, v220 op_sel_hi:[0,0,0]
	v_mfma_scale_f32_16x16x128_f8f6f4 v[226:229], v[0:7], v[160:167], v[226:229], v220, v220 op_sel_hi:[0,0,0]
	v_mfma_scale_f32_16x16x128_f8f6f4 v[230:233], v[16:23], v[160:167], v[230:233], v220, v220 op_sel_hi:[0,0,0]
	v_mfma_scale_f32_16x16x128_f8f6f4 v[168:171], v[16:23], v[152:159], v[200:203], v220, v220 op_sel_hi:[0,0,0]
	s_setprio 0
	s_setprio 1
	v_mfma_scale_f32_16x16x128_f8f6f4 v[52:55], v[128:135], v[32:39], v[52:55], v220, v220 op_sel_hi:[0,0,0]
	v_mfma_scale_f32_16x16x128_f8f6f4 v[48:51], v[136:143], v[32:39], v[48:51], v220, v220 op_sel_hi:[0,0,0]
	v_mfma_scale_f32_16x16x128_f8f6f4 v[36:39], v[128:135], v[144:151], v[234:237], v220, v220 op_sel_hi:[0,0,0]
	v_mfma_scale_f32_16x16x128_f8f6f4 v[32:35], v[136:143], v[144:151], v[66:69], v220, v220 op_sel_hi:[0,0,0]
	v_mfma_scale_f32_16x16x128_f8f6f4 v[20:23], v[128:135], v[152:159], v[242:245], v220, v220 op_sel_hi:[0,0,0]
	v_mfma_scale_f32_16x16x128_f8f6f4 v[16:19], v[136:143], v[152:159], v[246:249], v220, v220 op_sel_hi:[0,0,0]
	s_nop 5
	v_mov_b64_e32 v[244:245], v[170:171]
	v_mov_b64_e32 v[242:243], v[168:169]
	v_mfma_scale_f32_16x16x128_f8f6f4 v[4:7], v[128:135], v[160:167], v[250:253], v220, v220 op_sel_hi:[0,0,0]
	v_mfma_scale_f32_16x16x128_f8f6f4 v[0:3], v[136:143], v[160:167], v[192:195], v220, v220 op_sel_hi:[0,0,0]
	s_setprio 0
	s_add_i32 s67, s67, 2
	s_add_u32 s35, s35, 0x100
	s_addc_u32 s66, s66, 0
	s_add_u32 s0, s0, 0x100
	s_addc_u32 s1, s1, 0
	s_cmp_gt_u32 s67, 19
	s_barrier
	s_cbranch_scc1 .Lpeel_exit_721
.LBB0_721:
	ds_read_b128 v[128:131], v217
	ds_read_b128 v[132:135], v217 offset:1024
	ds_read_b128 v[136:139], v217 offset:2048
	ds_read_b128 v[140:143], v217 offset:3072
	ds_read_b128 v[144:147], v218
	ds_read_b128 v[148:151], v218 offset:1024
	ds_read_b128 v[152:155], v218 offset:2048
	ds_read_b128 v[156:159], v218 offset:3072
	s_add_u32 s6, s0, 0xfffa8080
	s_addc_u32 s7, s1, -1
	s_cmp_eq_u32 s67, 18
	s_cselect_b32 s7, s61, s7
	s_cselect_b32 s6, s60, s6
	s_cselect_b32 s65, s63, s66
	s_cselect_b32 s64, s62, s35
	v_lshl_add_u64 v[192:193], s[0:1], 0, v[190:191]
	s_add_i32 m0, s17, 0xc000
	ds_read_b128 v[160:163], v219
	ds_read_b128 v[164:167], v219 offset:1024
	ds_read_b128 v[168:171], v219 offset:2048
	ds_read_b128 v[172:175], v219 offset:3072
	ds_read_b128 v[176:179], v219 offset:4096
	ds_read_b128 v[180:183], v219 offset:5120
	ds_read_b128 v[196:199], v219 offset:6144
	ds_read_b128 v[200:203], v219 offset:7168
	global_load_lds_dwordx4 v[192:193], off
	v_lshl_add_u64 v[192:193], v[192:193], 0, s[8:9]
	s_add_i32 m0, s17, 0xe000
	s_nop 0
	global_load_lds_dwordx4 v[192:193], off
	s_waitcnt vmcnt(8)
	s_waitcnt lgkmcnt(0)
	s_barrier
	s_setprio 1
	s_waitcnt lgkmcnt(0)
	v_mfma_scale_f32_16x16x128_f8f6f4 v[124:127], v[128:135], v[160:167], v[124:127], v220, v220 op_sel_hi:[0,0,0]
	v_mfma_scale_f32_16x16x128_f8f6f4 v[120:123], v[136:143], v[160:167], v[120:123], v220, v220 op_sel_hi:[0,0,0]
	v_mfma_scale_f32_16x16x128_f8f6f4 v[108:111], v[128:135], v[168:175], v[108:111], v220, v220 op_sel_hi:[0,0,0]
	v_mfma_scale_f32_16x16x128_f8f6f4 v[104:107], v[136:143], v[168:175], v[104:107], v220, v220 op_sel_hi:[0,0,0]
	v_mfma_scale_f32_16x16x128_f8f6f4 v[204:207], v[128:135], v[176:183], v[92:95], v220, v220 op_sel_hi:[0,0,0]
	v_mfma_scale_f32_16x16x128_f8f6f4 v[208:211], v[136:143], v[176:183], v[88:91], v220, v220 op_sel_hi:[0,0,0]
	v_mfma_scale_f32_16x16x128_f8f6f4 v[212:215], v[128:135], v[196:203], v[76:79], v220, v220 op_sel_hi:[0,0,0]
	v_mfma_scale_f32_16x16x128_f8f6f4 v[222:225], v[136:143], v[196:203], v[72:75], v220, v220 op_sel_hi:[0,0,0]
	s_setprio 0
	s_setprio 1
	v_mfma_scale_f32_16x16x128_f8f6f4 v[116:119], v[144:151], v[160:167], v[116:119], v220, v220 op_sel_hi:[0,0,0]
	v_mfma_scale_f32_16x16x128_f8f6f4 v[112:115], v[152:159], v[160:167], v[112:115], v220, v220 op_sel_hi:[0,0,0]
	v_mfma_scale_f32_16x16x128_f8f6f4 v[100:103], v[144:151], v[168:175], v[100:103], v220, v220 op_sel_hi:[0,0,0]
	v_mfma_scale_f32_16x16x128_f8f6f4 v[96:99], v[152:159], v[168:175], v[96:99], v220, v220 op_sel_hi:[0,0,0]
	v_mfma_scale_f32_16x16x128_f8f6f4 v[160:163], v[144:151], v[176:183], v[84:87], v220, v220 op_sel_hi:[0,0,0]
	v_mfma_scale_f32_16x16x128_f8f6f4 v[164:167], v[152:159], v[176:183], v[80:83], v220, v220 op_sel_hi:[0,0,0]
	v_mfma_scale_f32_16x16x128_f8f6f4 v[168:171], v[144:151], v[196:203], v[24:27], v220, v220 op_sel_hi:[0,0,0]
	v_mfma_scale_f32_16x16x128_f8f6f4 v[172:175], v[152:159], v[196:203], v[10:13], v220, v220 op_sel_hi:[0,0,0]
	s_setprio 0
	s_barrier
	v_lshl_add_u64 v[184:185], s[64:65], 0, v[188:189]
	s_add_i32 s64, s84, s16
	s_mov_b32 m0, s64
	ds_read_b128 v[64:67], v219 offset:16384
	ds_read_b128 v[68:71], v219 offset:17408
	ds_read_b128 v[72:75], v219 offset:18432
	ds_read_b128 v[76:79], v219 offset:19456
	ds_read_b128 v[80:83], v219 offset:20480
	ds_read_b128 v[84:87], v219 offset:21504
	ds_read_b128 v[88:91], v219 offset:22528
	ds_read_b128 v[92:95], v219 offset:23552
	global_load_lds_dwordx4 v[184:185], off
	v_lshl_add_u64 v[176:177], v[184:185], 0, s[8:9]
	s_add_i32 m0, s64, 0x2000
	s_add_i32 s64, s85, s16
	global_load_lds_dwordx4 v[176:177], off
	v_lshl_add_u64 v[176:177], v[184:185], 0, s[10:11]
	s_mov_b32 m0, s64
	v_lshl_add_u64 v[186:187], s[6:7], 0, v[238:239]
	global_load_lds_dwordx4 v[176:177], off
	v_lshl_add_u64 v[176:177], v[184:185], 0, s[12:13]
	s_add_i32 m0, s64, 0x2000
	s_nop 0
	global_load_lds_dwordx4 v[176:177], off
	s_mov_b32 m0, s17
	v_lshl_add_u64 v[176:177], v[186:187], 0, s[8:9]
	global_load_lds_dwordx4 v[186:187], off
	s_mov_b32 m0, s33
	s_nop 0
	global_load_lds_dwordx4 v[176:177], off
	s_waitcnt vmcnt(8)
	s_waitcnt lgkmcnt(0)
	s_barrier
	s_setprio 1
	s_waitcnt lgkmcnt(0)
	v_mfma_scale_f32_16x16x128_f8f6f4 v[60:63], v[128:135], v[64:71], v[60:63], v220, v220 op_sel_hi:[0,0,0]
	v_mfma_scale_f32_16x16x128_f8f6f4 v[56:59], v[136:143], v[64:71], v[56:59], v220, v220 op_sel_hi:[0,0,0]
	v_mfma_scale_f32_16x16x128_f8f6f4 v[226:229], v[128:135], v[88:95], v[226:229], v220, v220 op_sel_hi:[0,0,0]
	v_mfma_scale_f32_16x16x128_f8f6f4 v[230:233], v[136:143], v[88:95], v[230:233], v220, v220 op_sel_hi:[0,0,0]
	v_mfma_scale_f32_16x16x128_f8f6f4 v[176:179], v[128:135], v[72:79], v[44:47], v220, v220 op_sel_hi:[0,0,0]
	v_mfma_scale_f32_16x16x128_f8f6f4 v[180:183], v[136:143], v[72:79], v[40:43], v220, v220 op_sel_hi:[0,0,0]
	v_mfma_scale_f32_16x16x128_f8f6f4 v[196:199], v[128:135], v[80:87], v[28:31], v220, v220 op_sel_hi:[0,0,0]
	v_mfma_scale_f32_16x16x128_f8f6f4 v[200:203], v[136:143], v[80:87], v[242:245], v220, v220 op_sel_hi:[0,0,0]
	s_setprio 0
	s_setprio 1
	v_mfma_scale_f32_16x16x128_f8f6f4 v[52:55], v[144:151], v[64:71], v[52:55], v220, v220 op_sel_hi:[0,0,0]
	v_mfma_scale_f32_16x16x128_f8f6f4 v[48:51], v[152:159], v[64:71], v[48:51], v220, v220 op_sel_hi:[0,0,0]
	v_mfma_scale_f32_16x16x128_f8f6f4 v[242:245], v[144:151], v[80:87], v[20:23], v220, v220 op_sel_hi:[0,0,0]
	v_mfma_scale_f32_16x16x128_f8f6f4 v[234:237], v[144:151], v[72:79], v[36:39], v220, v220 op_sel_hi:[0,0,0]
	v_mfma_scale_f32_16x16x128_f8f6f4 v[66:69], v[152:159], v[72:79], v[32:35], v220, v220 op_sel_hi:[0,0,0]
	v_mfma_scale_f32_16x16x128_f8f6f4 v[246:249], v[152:159], v[80:87], v[16:19], v220, v220 op_sel_hi:[0,0,0]
	v_mfma_scale_f32_16x16x128_f8f6f4 v[250:253], v[144:151], v[88:95], v[4:7], v220, v220 op_sel_hi:[0,0,0]
	v_mfma_scale_f32_16x16x128_f8f6f4 v[192:195], v[152:159], v[88:95], v[0:3], v220, v220 op_sel_hi:[0,0,0]
	s_setprio 0
	s_barrier
	s_add_i32 s6, 0, 0x18000
	v_add_u32_e32 v8, s6, v216
	s_add_i32 s7, 0, 0x1c000
	s_nop 1
	ds_read_b128 v[0:3], v8
	ds_read_b128 v[4:7], v8 offset:1024
	ds_read_b128 v[16:19], v8 offset:2048
	ds_read_b128 v[20:23], v8 offset:3072
	v_add_u32_e32 v8, s7, v216
	ds_read_b128 v[128:131], v8
	ds_read_b128 v[132:135], v8 offset:1024
	ds_read_b128 v[136:139], v8 offset:2048
	ds_read_b128 v[140:143], v8 offset:3072
	s_mov_b32 m0, s47
	v_lshl_add_u64 v[64:65], v[186:187], 0, s[10:11]
	ds_read_b128 v[8:11], v219 offset:32768
	ds_read_b128 v[12:15], v219 offset:33792
	ds_read_b128 v[24:27], v219 offset:34816
	ds_read_b128 v[28:31], v219 offset:35840
	ds_read_b128 v[32:35], v219 offset:36864
	ds_read_b128 v[36:39], v219 offset:37888
	ds_read_b128 v[40:43], v219 offset:38912
	ds_read_b128 v[44:47], v219 offset:39936
	global_load_lds_dwordx4 v[64:65], off
	v_lshl_add_u64 v[64:65], v[186:187], 0, s[12:13]
	s_mov_b32 m0, s57
	s_nop 0
	global_load_lds_dwordx4 v[64:65], off
	s_waitcnt vmcnt(8)
	s_waitcnt lgkmcnt(0)
	s_barrier
	s_setprio 1
	s_waitcnt lgkmcnt(0)
	v_mfma_scale_f32_16x16x128_f8f6f4 v[124:127], v[0:7], v[8:15], v[124:127], v220, v220 op_sel_hi:[0,0,0]
	v_mfma_scale_f32_16x16x128_f8f6f4 v[120:123], v[16:23], v[8:15], v[120:123], v220, v220 op_sel_hi:[0,0,0]
	v_mfma_scale_f32_16x16x128_f8f6f4 v[108:111], v[0:7], v[24:31], v[108:111], v220, v220 op_sel_hi:[0,0,0]
	v_mfma_scale_f32_16x16x128_f8f6f4 v[104:107], v[16:23], v[24:31], v[104:107], v220, v220 op_sel_hi:[0,0,0]
	v_mfma_scale_f32_16x16x128_f8f6f4 v[92:95], v[0:7], v[32:39], v[204:207], v220, v220 op_sel_hi:[0,0,0]
	v_mfma_scale_f32_16x16x128_f8f6f4 v[88:91], v[16:23], v[32:39], v[208:211], v220, v220 op_sel_hi:[0,0,0]
	v_mfma_scale_f32_16x16x128_f8f6f4 v[76:79], v[0:7], v[40:47], v[212:215], v220, v220 op_sel_hi:[0,0,0]
	v_mfma_scale_f32_16x16x128_f8f6f4 v[72:75], v[16:23], v[40:47], v[222:225], v220, v220 op_sel_hi:[0,0,0]
	s_setprio 0
	s_setprio 1
	v_mfma_scale_f32_16x16x128_f8f6f4 v[116:119], v[128:135], v[8:15], v[116:119], v220, v220 op_sel_hi:[0,0,0]
	v_mfma_scale_f32_16x16x128_f8f6f4 v[112:115], v[136:143], v[8:15], v[112:115], v220, v220 op_sel_hi:[0,0,0]
	v_mfma_scale_f32_16x16x128_f8f6f4 v[100:103], v[128:135], v[24:31], v[100:103], v220, v220 op_sel_hi:[0,0,0]
	v_mfma_scale_f32_16x16x128_f8f6f4 v[96:99], v[136:143], v[24:31], v[96:99], v220, v220 op_sel_hi:[0,0,0]
	v_mfma_scale_f32_16x16x128_f8f6f4 v[84:87], v[128:135], v[32:39], v[160:163], v220, v220 op_sel_hi:[0,0,0]
	v_mfma_scale_f32_16x16x128_f8f6f4 v[80:83], v[136:143], v[32:39], v[164:167], v220, v220 op_sel_hi:[0,0,0]
	v_mfma_scale_f32_16x16x128_f8f6f4 v[24:27], v[128:135], v[40:47], v[168:171], v220, v220 op_sel_hi:[0,0,0]
	v_mfma_scale_f32_16x16x128_f8f6f4 v[10:13], v[136:143], v[40:47], v[172:175], v220, v220 op_sel_hi:[0,0,0]
	s_setprio 0
	s_barrier
	s_add_i32 s6, s6, s16
	v_lshl_add_u64 v[8:9], v[184:185], 0, s[28:29]
	s_mov_b32 m0, s6
	ds_read_b128 v[32:35], v219 offset:49152
	ds_read_b128 v[36:39], v219 offset:50176
	ds_read_b128 v[144:147], v219 offset:51200
	ds_read_b128 v[148:151], v219 offset:52224
	ds_read_b128 v[152:155], v219 offset:53248
	ds_read_b128 v[156:159], v219 offset:54272
	ds_read_b128 v[160:163], v219 offset:55296
	ds_read_b128 v[164:167], v219 offset:56320
	global_load_lds_dwordx4 v[8:9], off
	v_lshl_add_u64 v[8:9], v[184:185], 0, s[36:37]
	s_add_i32 m0, s6, 0x2000
	s_add_i32 s6, s7, s16
	global_load_lds_dwordx4 v[8:9], off
	v_lshl_add_u64 v[8:9], v[184:185], 0, s[40:41]
	s_mov_b32 m0, s6
	s_nop 0
	global_load_lds_dwordx4 v[8:9], off
	v_lshl_add_u64 v[8:9], v[184:185], 0, s[42:43]
	s_add_i32 m0, s6, 0x2000
	s_nop 0
	global_load_lds_dwordx4 v[8:9], off
	v_lshl_add_u64 v[8:9], v[186:187], 0, s[28:29]
	s_mov_b32 m0, s77
	s_nop 0
	global_load_lds_dwordx4 v[8:9], off
	v_lshl_add_u64 v[8:9], v[186:187], 0, s[36:37]
	s_mov_b32 m0, s78
	s_nop 0
	global_load_lds_dwordx4 v[8:9], off
	s_waitcnt vmcnt(8)
	s_waitcnt lgkmcnt(0)
	s_barrier
	s_setprio 1
	s_waitcnt lgkmcnt(0)
	v_mfma_scale_f32_16x16x128_f8f6f4 v[60:63], v[0:7], v[32:39], v[60:63], v220, v220 op_sel_hi:[0,0,0]
	v_mfma_scale_f32_16x16x128_f8f6f4 v[56:59], v[16:23], v[32:39], v[56:59], v220, v220 op_sel_hi:[0,0,0]
	v_mfma_scale_f32_16x16x128_f8f6f4 v[44:47], v[0:7], v[144:151], v[176:179], v220, v220 op_sel_hi:[0,0,0]
	v_mfma_scale_f32_16x16x128_f8f6f4 v[40:43], v[16:23], v[144:151], v[180:183], v220, v220 op_sel_hi:[0,0,0]
	v_mfma_scale_f32_16x16x128_f8f6f4 v[28:31], v[0:7], v[152:159], v[196:199], v220, v220 op_sel_hi:[0,0,0]
	v_mfma_scale_f32_16x16x128_f8f6f4 v[226:229], v[0:7], v[160:167], v[226:229], v220, v220 op_sel_hi:[0,0,0]
	v_mfma_scale_f32_16x16x128_f8f6f4 v[230:233], v[16:23], v[160:167], v[230:233], v220, v220 op_sel_hi:[0,0,0]
	v_mfma_scale_f32_16x16x128_f8f6f4 v[168:171], v[16:23], v[152:159], v[200:203], v220, v220 op_sel_hi:[0,0,0]
	s_setprio 0
	s_setprio 1
	v_mfma_scale_f32_16x16x128_f8f6f4 v[52:55], v[128:135], v[32:39], v[52:55], v220, v220 op_sel_hi:[0,0,0]
	v_mfma_scale_f32_16x16x128_f8f6f4 v[48:51], v[136:143], v[32:39], v[48:51], v220, v220 op_sel_hi:[0,0,0]
	v_mfma_scale_f32_16x16x128_f8f6f4 v[36:39], v[128:135], v[144:151], v[234:237], v220, v220 op_sel_hi:[0,0,0]
	v_mfma_scale_f32_16x16x128_f8f6f4 v[32:35], v[136:143], v[144:151], v[66:69], v220, v220 op_sel_hi:[0,0,0]
	v_mfma_scale_f32_16x16x128_f8f6f4 v[20:23], v[128:135], v[152:159], v[242:245], v220, v220 op_sel_hi:[0,0,0]
	v_mfma_scale_f32_16x16x128_f8f6f4 v[16:19], v[136:143], v[152:159], v[246:249], v220, v220 op_sel_hi:[0,0,0]
	s_nop 5
	v_mov_b64_e32 v[244:245], v[170:171]
	v_mov_b64_e32 v[242:243], v[168:169]
	v_mfma_scale_f32_16x16x128_f8f6f4 v[4:7], v[128:135], v[160:167], v[250:253], v220, v220 op_sel_hi:[0,0,0]
	v_mfma_scale_f32_16x16x128_f8f6f4 v[0:3], v[136:143], v[160:167], v[192:195], v220, v220 op_sel_hi:[0,0,0]
	s_setprio 0
	s_add_i32 s67, s67, 2
	s_add_u32 s35, s35, 0x100
	s_addc_u32 s66, s66, 0
	s_add_u32 s0, s0, 0x100
	s_addc_u32 s1, s1, 0
	s_cmp_gt_u32 s67, 19
	s_barrier
	s_cbranch_scc0 .LBB0_721
